# GEMM K-loops: all per-segment s_setprio flips deleted (no static raise)
# baseline (speedup 1.0000x reference)
;     __host__ __device__ bool next(int i, Unit& u) const { return i < cnt ? so.next(base + i, u) : false; }
;     __host__ __device__ bool next(int i, Unit& u) const { const int L = i * G + c; if (L >= 32) return false; u.g = L >> 3; u.pm = L & 7; u.pn = 0; return true; }
; #define PG8_STAGE(bufoff, gbase, voff) do { _Pragma("unroll") for (int _i = 0; _i < 2; ++_i) \
;         __builtin_amdgcn_global_load_lds((const unsigned*)((const char*)(gbase) + (voff)[_i]), (PG8_LAS unsigned*)(lds + (bufoff) + ldsw + _i * 8192), 16, 0, 0); } while (0)
; #define PG8_LDA(dst, b, h) do { _Pragma("unroll") for (int m = 0; m < 4; ++m) _Pragma("unroll") for (int k = 0; k < 2; ++k) dst[m][k] = *(const PG8_LAS bf16x8*)(lds + PG8_SA(b, h) + aoff + m * 2048 + k * 1024); } while (0)
; #define PG8_SCHED __builtin_amdgcn_sched_barrier(0)
; template <class Epi, class Sched, bool ALIGN_EPI = false, bool SP2 = false>
; __device__ __forceinline__ void gemm_phase(PG8_LAS unsigned char* lds, const Gemm g, const Sched& S, const Epi& E) {
;     ...
;         const bool has_next = S.next(ui + 1, nxt);
;         const char* nA = has_next ? (const char*)(g.A + (size_t)nxt.g * g.gsA) + (size_t)nxt.pm * tstepA : cA; const char* nB = has_next ? (const char*)(g.Bt + (size_t)nxt.g * g.gsB) + (size_t)nxt.pn * tstepB : cB;
;         for (int t = 0; t < nt; t += 2) {
;             if constexpr (Epi::MIDK) { if (t == (nt >> 1)) { asm volatile("s_waitcnt vmcnt(0)" ::: "memory"); E.mid(acc, cur, wr, wc, fr, fq); asm volatile("s_waitcnt vmcnt(0)" ::: "memory"); } }
;             const bool last = (t == nt - 2);
;             const char* a1 = cA + (size_t)(t + 1) * kstep;
;             const char* a2 = last ? nA : cA + (size_t)(t + 2) * kstep; const char* b2 = last ? nB : cB + (size_t)(t + 2) * kstep;
;             const char* a3 = a2 + kstep; const char* b3 = b2 + kstep;
;             if (last && has_next) S.a_ready(nxt);
;             if constexpr (SP2) {
;             PG8_LDB(B0, 0, 0); PG8_LDB(B1, 0, 1); PG8_SCHED; PG8_LDA(At, 0, 0); PG8_STAGE(PG8_SA(1, 1), a1 + hstepA, voffA);
;     ...
; #pragma unroll
;         for (int a = 0; a < 2; ++a)
; #pragma unroll
;             for (int b = 0; b < 2; ++b)
; #pragma unroll
;                 for (int m = 0; m < 4; ++m)
; #pragma unroll
;                     for (int n = 0; n < 2; ++n) acc[a][b][m][n] = (f32x4){0.f, 0.f, 0.f, 0.f};
;         cur = nxt; cA = nA; cB = nB; ++ui;
.LBB0_84:
	s_ashr_i32 s25, s24, 31
	s_lshl_b64 s[26:27], s[24:25], 20
	s_add_u32 s26, s37, s26
	s_addc_u32 s27, s38, s27
	s_ashr_i32 s23, s22, 31
	s_lshl_b64 s[28:29], s[22:23], 20
	s_add_u32 s28, s39, s28
	v_mov_b32_e32 v127, 0
	s_addc_u32 s29, s44, s29
	s_and_b64 vcc, exec, s[6:7]
	v_mov_b32_e32 v126, v127
	v_mov_b32_e32 v125, v127
	v_mov_b32_e32 v124, v127
	v_mov_b32_e32 v123, v127
	v_mov_b32_e32 v122, v127
	v_mov_b32_e32 v121, v127
	v_mov_b32_e32 v120, v127
	v_mov_b32_e32 v111, v127
	v_mov_b32_e32 v110, v127
	v_mov_b32_e32 v109, v127
	v_mov_b32_e32 v108, v127
	v_mov_b32_e32 v107, v127
	v_mov_b32_e32 v106, v127
	v_mov_b32_e32 v105, v127
	v_mov_b32_e32 v104, v127
	v_mov_b32_e32 v95, v127
	v_mov_b32_e32 v94, v127
	v_mov_b32_e32 v93, v127
	v_mov_b32_e32 v92, v127
	v_mov_b32_e32 v91, v127
	v_mov_b32_e32 v90, v127
	v_mov_b32_e32 v89, v127
	v_mov_b32_e32 v88, v127
	v_mov_b32_e32 v79, v127
	v_mov_b32_e32 v78, v127
	v_mov_b32_e32 v77, v127
	v_mov_b32_e32 v76, v127
	v_mov_b32_e32 v75, v127
	v_mov_b32_e32 v74, v127
	v_mov_b32_e32 v73, v127
	v_mov_b32_e32 v72, v127
	v_mov_b32_e32 v119, v127
	v_mov_b32_e32 v118, v127
	v_mov_b32_e32 v117, v127
	v_mov_b32_e32 v116, v127
	v_mov_b32_e32 v115, v127
	v_mov_b32_e32 v114, v127
	v_mov_b32_e32 v113, v127
	v_mov_b32_e32 v112, v127
	v_mov_b32_e32 v103, v127
	v_mov_b32_e32 v102, v127
	v_mov_b32_e32 v101, v127
	v_mov_b32_e32 v100, v127
	v_mov_b32_e32 v99, v127
	v_mov_b32_e32 v98, v127
	v_mov_b32_e32 v97, v127
	v_mov_b32_e32 v96, v127
	v_mov_b32_e32 v87, v127
	v_mov_b32_e32 v86, v127
	v_mov_b32_e32 v85, v127
	v_mov_b32_e32 v84, v127
	v_mov_b32_e32 v83, v127
	v_mov_b32_e32 v82, v127
	v_mov_b32_e32 v81, v127
	v_mov_b32_e32 v80, v127
	v_mov_b32_e32 v71, v127
	v_mov_b32_e32 v70, v127
	v_mov_b32_e32 v69, v127
	v_mov_b32_e32 v68, v127
	v_mov_b32_e32 v67, v127
	v_mov_b32_e32 v66, v127
	v_mov_b32_e32 v65, v127
	v_mov_b32_e32 v64, v127
	v_mov_b32_e32 v63, v127
	v_mov_b32_e32 v62, v127
	v_mov_b32_e32 v61, v127
	v_mov_b32_e32 v60, v127
	v_mov_b32_e32 v59, v127
	v_mov_b32_e32 v58, v127
	v_mov_b32_e32 v57, v127
	v_mov_b32_e32 v56, v127
	v_mov_b32_e32 v47, v127
	v_mov_b32_e32 v46, v127
	v_mov_b32_e32 v45, v127
	v_mov_b32_e32 v44, v127
	v_mov_b32_e32 v43, v127
	v_mov_b32_e32 v42, v127
	v_mov_b32_e32 v41, v127
	v_mov_b32_e32 v40, v127
	v_mov_b32_e32 v31, v127
	v_mov_b32_e32 v30, v127
	v_mov_b32_e32 v29, v127
	v_mov_b32_e32 v28, v127
	v_mov_b32_e32 v27, v127
	v_mov_b32_e32 v26, v127
	v_mov_b32_e32 v25, v127
	v_mov_b32_e32 v24, v127
	v_mov_b32_e32 v15, v127
	v_mov_b32_e32 v14, v127
	v_mov_b32_e32 v13, v127
	v_mov_b32_e32 v12, v127
	v_mov_b32_e32 v11, v127
	v_mov_b32_e32 v10, v127
	v_mov_b32_e32 v9, v127
	v_mov_b32_e32 v8, v127
	v_mov_b32_e32 v55, v127
	v_mov_b32_e32 v54, v127
	v_mov_b32_e32 v53, v127
	v_mov_b32_e32 v52, v127
	v_mov_b32_e32 v51, v127
	v_mov_b32_e32 v50, v127
	v_mov_b32_e32 v49, v127
	v_mov_b32_e32 v48, v127
	v_mov_b32_e32 v39, v127
	v_mov_b32_e32 v38, v127
	v_mov_b32_e32 v37, v127
	v_mov_b32_e32 v36, v127
	v_mov_b32_e32 v35, v127
	v_mov_b32_e32 v34, v127
	v_mov_b32_e32 v33, v127
	v_mov_b32_e32 v32, v127
	v_mov_b32_e32 v23, v127
	v_mov_b32_e32 v22, v127
	v_mov_b32_e32 v21, v127
	v_mov_b32_e32 v20, v127
	v_mov_b32_e32 v19, v127
	v_mov_b32_e32 v18, v127
	v_mov_b32_e32 v17, v127
	v_mov_b32_e32 v16, v127
	v_mov_b32_e32 v7, v127
	v_mov_b32_e32 v6, v127
	v_mov_b32_e32 v5, v127
	v_mov_b32_e32 v4, v127
	v_mov_b32_e32 v3, v127
	v_mov_b32_e32 v2, v127
	s_waitcnt lgkmcnt(0)
	v_mov_b32_e32 v1, v127
	v_mov_b32_e32 v0, v127
	s_cbranch_vccnz .LBB0_87
	s_and_b64 s[34:35], s[8:9], exec
	s_cselect_b32 s11, s27, s31
	s_cselect_b32 s23, s26, s30
	s_cselect_b32 s25, s29, s13
	s_cselect_b32 s40, s28, s12
	s_add_u32 s41, s12, 0x100
	s_addc_u32 s42, s13, 0
	s_add_u32 s12, s30, 0x80080
	s_addc_u32 s13, s31, 0
	s_mov_b32 s30, 0
.LBB0_86:
	ds_read_b128 v[146:149], v159
	ds_read_b128 v[150:153], v159 offset:1024
	ds_read_b128 v[164:167], v159 offset:2048
	ds_read_b128 v[168:171], v159 offset:3072
	ds_read_b128 v[172:175], v160
	ds_read_b128 v[176:179], v160 offset:1024
	ds_read_b128 v[180:183], v160 offset:2048
	ds_read_b128 v[184:187], v160 offset:3072
	s_add_i32 s43, s30, 2
	s_add_u32 s31, s12, 0xfff80080
	s_addc_u32 s34, s13, -1
	s_cmp_eq_u32 s60, s30
	s_cselect_b32 s30, s40, s41
	s_cselect_b32 s35, s11, s34
	s_cselect_b32 s34, s23, s31
	s_cselect_b32 s31, s25, s42
	v_lshl_add_u64 v[154:155], s[12:13], 0, v[140:141]
	s_add_i32 m0, s46, 0xc000
	ds_read_b128 v[188:191], v161
	ds_read_b128 v[192:195], v161 offset:1024
	ds_read_b128 v[196:199], v161 offset:2048
	ds_read_b128 v[200:203], v161 offset:3072
	ds_read_b128 v[204:207], v161 offset:4096
	ds_read_b128 v[208:211], v161 offset:5120
	ds_read_b128 v[212:215], v161 offset:6144
	ds_read_b128 v[216:219], v161 offset:7168
	global_load_lds_dwordx4 v[154:155], off
	v_lshl_add_u64 v[154:155], s[12:13], 0, v[138:139]
	s_add_i32 m0, s46, 0xe000
	s_nop 0
	global_load_lds_dwordx4 v[154:155], off
	s_waitcnt vmcnt(8)
	s_waitcnt lgkmcnt(0)
	s_barrier
; #define PG8_STAGE(bufoff, gbase, voff) do { _Pragma("unroll") for (int _i = 0; _i < 2; ++_i) \
;         __builtin_amdgcn_global_load_lds((const unsigned*)((const char*)(gbase) + (voff)[_i]), (PG8_LAS unsigned*)(lds + (bufoff) + ldsw + _i * 8192), 16, 0, 0); } while (0)
; #define PG8_LDA(dst, b, h) do { _Pragma("unroll") for (int m = 0; m < 4; ++m) _Pragma("unroll") for (int k = 0; k < 2; ++k) dst[m][k] = *(const PG8_LAS bf16x8*)(lds + PG8_SA(b, h) + aoff + m * 2048 + k * 1024); } while (0)
; #define PG8_LDB(dst, b, h) do { _Pragma("unroll") for (int n = 0; n < 2; ++n) _Pragma("unroll") for (int k = 0; k < 2; ++k) dst[n][k] = *(const PG8_LAS bf16x8*)(lds + PG8_SB(b, h) + boff + n * 2048 + k * 1024); } while (0)
; #define PG8_MMA(ai, bj, At, Bt) do { __builtin_amdgcn_s_setprio(1); _Pragma("unroll") for (int m = 0; m < 4; ++m) _Pragma("unroll") for (int n = 0; n < 2; ++n) _Pragma("unroll") for (int k = 0; k < 2; ++k) \
;         acc[ai][bj][m][n] = __builtin_amdgcn_mfma_f32_16x16x32_bf16(Bt[n][k], At[m][k], acc[ai][bj][m][n], 0, 0, 0); __builtin_amdgcn_s_setprio(0); } while (0)
; #define PG8_WAIT_V(n) asm volatile("s_waitcnt vmcnt(" #n ")" ::: "memory")
; #define PG8_WAIT_L(n) asm volatile("s_waitcnt lgkmcnt(" #n ")" ::: "memory")
; #define PG8_BAR __builtin_amdgcn_s_barrier()
; #define PG8_SCHED __builtin_amdgcn_sched_barrier(0)
; template <class Epi, class Sched, bool ALIGN_EPI = false, bool SP2 = false>
; __device__ __forceinline__ void gemm_phase(PG8_LAS unsigned char* lds, const Gemm g, const Sched& S, const Epi& E) {
;     ...
;             PG8_WAIT_V(8); PG8_WAIT_L(0); PG8_BAR; PG8_MMA(0, 0, At, B0); PG8_MMA(0, 1, At, B1); PG8_BAR; PG8_SCHED;
;             PG8_LDA(At, 0, 1); PG8_STAGE(PG8_SB(0, 0), b2, voffB); PG8_STAGE(PG8_SB(0, 1), b2 + hstepB, voffB); PG8_STAGE(PG8_SA(0, 0), a2, voffA);
;             PG8_WAIT_V(8); PG8_WAIT_L(0); PG8_BAR; PG8_MMA(1, 0, At, B0); PG8_MMA(1, 1, At, B1); PG8_BAR; PG8_SCHED;
;             PG8_LDB(B0, 1, 0); PG8_LDB(B1, 1, 1); PG8_SCHED; PG8_LDA(At, 1, 0); PG8_STAGE(PG8_SA(0, 1), a2 + hstepA, voffA);
;             PG8_WAIT_V(8); PG8_WAIT_L(0); PG8_BAR; PG8_MMA(0, 0, At, B0); PG8_MMA(0, 1, At, B1); PG8_BAR; PG8_SCHED;
	s_waitcnt lgkmcnt(0)
	v_mfma_f32_16x16x32_bf16 v[124:127], v[146:149], v[188:191], v[124:127]
	v_mfma_f32_16x16x32_bf16 v[120:123], v[164:167], v[188:191], v[120:123]
	v_mfma_f32_16x16x32_bf16 v[108:111], v[146:149], v[196:199], v[108:111]
	v_mfma_f32_16x16x32_bf16 v[104:107], v[164:167], v[196:199], v[104:107]
	v_mfma_f32_16x16x32_bf16 v[92:95], v[146:149], v[204:207], v[92:95]
	v_mfma_f32_16x16x32_bf16 v[88:91], v[164:167], v[204:207], v[88:91]
	v_mfma_f32_16x16x32_bf16 v[76:79], v[146:149], v[212:215], v[76:79]
	v_mfma_f32_16x16x32_bf16 v[72:75], v[164:167], v[212:215], v[72:75]
	v_mfma_f32_16x16x32_bf16 v[124:127], v[150:153], v[192:195], v[124:127]
	v_mfma_f32_16x16x32_bf16 v[120:123], v[168:171], v[192:195], v[120:123]
	v_mfma_f32_16x16x32_bf16 v[108:111], v[150:153], v[200:203], v[108:111]
	v_mfma_f32_16x16x32_bf16 v[104:107], v[168:171], v[200:203], v[104:107]
	v_mfma_f32_16x16x32_bf16 v[92:95], v[150:153], v[208:211], v[92:95]
	v_mfma_f32_16x16x32_bf16 v[88:91], v[168:171], v[208:211], v[88:91]
	v_mfma_f32_16x16x32_bf16 v[76:79], v[150:153], v[216:219], v[76:79]
	v_mfma_f32_16x16x32_bf16 v[72:75], v[168:171], v[216:219], v[72:75]
	v_mfma_f32_16x16x32_bf16 v[116:119], v[172:175], v[188:191], v[116:119]
	v_mfma_f32_16x16x32_bf16 v[112:115], v[180:183], v[188:191], v[112:115]
	v_mfma_f32_16x16x32_bf16 v[100:103], v[172:175], v[196:199], v[100:103]
	v_mfma_f32_16x16x32_bf16 v[96:99], v[180:183], v[196:199], v[96:99]
	v_mfma_f32_16x16x32_bf16 v[84:87], v[172:175], v[204:207], v[84:87]
	v_mfma_f32_16x16x32_bf16 v[80:83], v[180:183], v[204:207], v[80:83]
	v_mfma_f32_16x16x32_bf16 v[68:71], v[172:175], v[212:215], v[68:71]
	v_mfma_f32_16x16x32_bf16 v[64:67], v[180:183], v[212:215], v[64:67]
	v_mfma_f32_16x16x32_bf16 v[116:119], v[176:179], v[192:195], v[116:119]
	v_mfma_f32_16x16x32_bf16 v[112:115], v[184:187], v[192:195], v[112:115]
	v_mfma_f32_16x16x32_bf16 v[100:103], v[176:179], v[200:203], v[100:103]
	v_mfma_f32_16x16x32_bf16 v[96:99], v[184:187], v[200:203], v[96:99]
	v_mfma_f32_16x16x32_bf16 v[84:87], v[176:179], v[208:211], v[84:87]
	v_mfma_f32_16x16x32_bf16 v[80:83], v[184:187], v[208:211], v[80:83]
	v_mfma_f32_16x16x32_bf16 v[68:71], v[176:179], v[216:219], v[68:71]
	v_mfma_f32_16x16x32_bf16 v[64:67], v[184:187], v[216:219], v[64:67]
	s_barrier
	s_add_i32 s64, s61, s45
	v_lshl_add_u64 v[154:155], s[30:31], 0, v[130:131]
	s_mov_b32 m0, s64
	ds_read_b128 v[188:191], v161 offset:16384
	ds_read_b128 v[192:195], v161 offset:17408
	ds_read_b128 v[196:199], v161 offset:18432
	ds_read_b128 v[200:203], v161 offset:19456
	ds_read_b128 v[204:207], v161 offset:20480
	ds_read_b128 v[208:211], v161 offset:21504
	ds_read_b128 v[212:215], v161 offset:22528
	ds_read_b128 v[216:219], v161 offset:23552
	global_load_lds_dwordx4 v[154:155], off
	s_add_i32 m0, s64, 0x2000
	s_add_u32 s64, s30, 0x80000
	v_lshl_add_u64 v[220:221], s[30:31], 0, v[134:135]
	s_addc_u32 s65, s31, 0
	s_add_i32 s66, s62, s45
	global_load_lds_dwordx4 v[220:221], off
	v_lshl_add_u64 v[222:223], s[64:65], 0, v[130:131]
	s_mov_b32 m0, s66
	v_lshl_add_u64 v[224:225], s[34:35], 0, v[132:133]
	global_load_lds_dwordx4 v[222:223], off
	v_lshl_add_u64 v[222:223], s[64:65], 0, v[134:135]
	s_add_i32 m0, s66, 0x2000
	s_nop 0
	global_load_lds_dwordx4 v[222:223], off
	v_lshl_add_u64 v[222:223], s[34:35], 0, v[128:129]
	s_mov_b32 m0, s46
	s_nop 0
	global_load_lds_dwordx4 v[222:223], off
	s_mov_b32 m0, s47
	s_nop 0
	global_load_lds_dwordx4 v[224:225], off
	s_waitcnt vmcnt(8)
	s_waitcnt lgkmcnt(0)
	s_barrier
	s_waitcnt lgkmcnt(0)
	v_mfma_f32_16x16x32_bf16 v[60:63], v[146:149], v[188:191], v[60:63]
	v_mfma_f32_16x16x32_bf16 v[56:59], v[164:167], v[188:191], v[56:59]
	v_mfma_f32_16x16x32_bf16 v[44:47], v[146:149], v[196:199], v[44:47]
	v_mfma_f32_16x16x32_bf16 v[40:43], v[164:167], v[196:199], v[40:43]
	v_mfma_f32_16x16x32_bf16 v[28:31], v[146:149], v[204:207], v[28:31]
	v_mfma_f32_16x16x32_bf16 v[24:27], v[164:167], v[204:207], v[24:27]
	v_mfma_f32_16x16x32_bf16 v[12:15], v[146:149], v[212:215], v[12:15]
	v_mfma_f32_16x16x32_bf16 v[8:11], v[164:167], v[212:215], v[8:11]
	v_mfma_f32_16x16x32_bf16 v[60:63], v[150:153], v[192:195], v[60:63]
	v_mfma_f32_16x16x32_bf16 v[56:59], v[168:171], v[192:195], v[56:59]
	v_mfma_f32_16x16x32_bf16 v[44:47], v[150:153], v[200:203], v[44:47]
	v_mfma_f32_16x16x32_bf16 v[40:43], v[168:171], v[200:203], v[40:43]
	v_mfma_f32_16x16x32_bf16 v[28:31], v[150:153], v[208:211], v[28:31]
	v_mfma_f32_16x16x32_bf16 v[24:27], v[168:171], v[208:211], v[24:27]
	v_mfma_f32_16x16x32_bf16 v[12:15], v[150:153], v[216:219], v[12:15]
	v_mfma_f32_16x16x32_bf16 v[8:11], v[168:171], v[216:219], v[8:11]
	v_mfma_f32_16x16x32_bf16 v[52:55], v[172:175], v[188:191], v[52:55]
	v_mfma_f32_16x16x32_bf16 v[48:51], v[180:183], v[188:191], v[48:51]
	v_mfma_f32_16x16x32_bf16 v[36:39], v[172:175], v[196:199], v[36:39]
	v_mfma_f32_16x16x32_bf16 v[32:35], v[180:183], v[196:199], v[32:35]
	v_mfma_f32_16x16x32_bf16 v[20:23], v[172:175], v[204:207], v[20:23]
	v_mfma_f32_16x16x32_bf16 v[16:19], v[180:183], v[204:207], v[16:19]
	v_mfma_f32_16x16x32_bf16 v[4:7], v[172:175], v[212:215], v[4:7]
	v_mfma_f32_16x16x32_bf16 v[0:3], v[180:183], v[212:215], v[0:3]
	v_mfma_f32_16x16x32_bf16 v[52:55], v[176:179], v[192:195], v[52:55]
	v_mfma_f32_16x16x32_bf16 v[48:51], v[184:187], v[192:195], v[48:51]
	v_mfma_f32_16x16x32_bf16 v[36:39], v[176:179], v[200:203], v[36:39]
	v_mfma_f32_16x16x32_bf16 v[32:35], v[184:187], v[200:203], v[32:35]
	v_mfma_f32_16x16x32_bf16 v[20:23], v[176:179], v[208:211], v[20:23]
	v_mfma_f32_16x16x32_bf16 v[16:19], v[184:187], v[208:211], v[16:19]
	v_mfma_f32_16x16x32_bf16 v[4:7], v[176:179], v[216:219], v[4:7]
	v_mfma_f32_16x16x32_bf16 v[0:3], v[184:187], v[216:219], v[0:3]
	s_barrier
; #define PG8_STAGE(bufoff, gbase, voff) do { _Pragma("unroll") for (int _i = 0; _i < 2; ++_i) \
;         __builtin_amdgcn_global_load_lds((const unsigned*)((const char*)(gbase) + (voff)[_i]), (PG8_LAS unsigned*)(lds + (bufoff) + ldsw + _i * 8192), 16, 0, 0); } while (0)
; #define PG8_LDA(dst, b, h) do { _Pragma("unroll") for (int m = 0; m < 4; ++m) _Pragma("unroll") for (int k = 0; k < 2; ++k) dst[m][k] = *(const PG8_LAS bf16x8*)(lds + PG8_SA(b, h) + aoff + m * 2048 + k * 1024); } while (0)
; #define PG8_LDB(dst, b, h) do { _Pragma("unroll") for (int n = 0; n < 2; ++n) _Pragma("unroll") for (int k = 0; k < 2; ++k) dst[n][k] = *(const PG8_LAS bf16x8*)(lds + PG8_SB(b, h) + boff + n * 2048 + k * 1024); } while (0)
; #define PG8_MMA(ai, bj, At, Bt) do { __builtin_amdgcn_s_setprio(1); _Pragma("unroll") for (int m = 0; m < 4; ++m) _Pragma("unroll") for (int n = 0; n < 2; ++n) _Pragma("unroll") for (int k = 0; k < 2; ++k) \
;         acc[ai][bj][m][n] = __builtin_amdgcn_mfma_f32_16x16x32_bf16(Bt[n][k], At[m][k], acc[ai][bj][m][n], 0, 0, 0); __builtin_amdgcn_s_setprio(0); } while (0)
; #define PG8_WAIT_V(n) asm volatile("s_waitcnt vmcnt(" #n ")" ::: "memory")
; #define PG8_WAIT_L(n) asm volatile("s_waitcnt lgkmcnt(" #n ")" ::: "memory")
; #define PG8_BAR __builtin_amdgcn_s_barrier()
; #define PG8_SCHED __builtin_amdgcn_sched_barrier(0)
; template <class Epi, class Sched, bool ALIGN_EPI = false, bool SP2 = false>
; __device__ __forceinline__ void gemm_phase(PG8_LAS unsigned char* lds, const Gemm g, const Sched& S, const Epi& E) {
;     ...
;             PG8_LDB(B0, 1, 0); PG8_LDB(B1, 1, 1); PG8_SCHED; PG8_LDA(At, 1, 0); PG8_STAGE(PG8_SA(0, 1), a2 + hstepA, voffA);
;             PG8_WAIT_V(8); PG8_WAIT_L(0); PG8_BAR; PG8_MMA(0, 0, At, B0); PG8_MMA(0, 1, At, B1); PG8_BAR; PG8_SCHED;
;             PG8_LDA(At, 1, 1); PG8_STAGE(PG8_SB(1, 0), b3, voffB); PG8_STAGE(PG8_SB(1, 1), b3 + hstepB, voffB); PG8_STAGE(PG8_SA(1, 0), a3, voffA);
;             PG8_WAIT_V(8); PG8_WAIT_L(0); PG8_BAR; PG8_MMA(1, 0, At, B0); PG8_MMA(1, 1, At, B1); PG8_BAR; PG8_SCHED;
	s_add_i32 s64, 0, 0x18000
	v_add_u32_e32 v137, s64, v158
	s_add_i32 s65, 0, 0x1c000
	ds_read_b128 v[146:149], v137
	ds_read_b128 v[150:153], v137 offset:1024
	ds_read_b128 v[164:167], v137 offset:2048
	ds_read_b128 v[168:171], v137 offset:3072
	v_add_u32_e32 v137, s65, v158
	ds_read_b128 v[172:175], v137
	ds_read_b128 v[176:179], v137 offset:1024
	ds_read_b128 v[180:183], v137 offset:2048
	ds_read_b128 v[184:187], v137 offset:3072
	s_add_u32 s34, s34, 0x80000
	s_addc_u32 s35, s35, 0
	s_mov_b32 m0, s48
	v_lshl_add_u64 v[228:229], s[34:35], 0, v[128:129]
	ds_read_b128 v[188:191], v161 offset:32768
	ds_read_b128 v[192:195], v161 offset:33792
	ds_read_b128 v[196:199], v161 offset:34816
	ds_read_b128 v[200:203], v161 offset:35840
	ds_read_b128 v[204:207], v161 offset:36864
	ds_read_b128 v[208:211], v161 offset:37888
	ds_read_b128 v[212:215], v161 offset:38912
	ds_read_b128 v[216:219], v161 offset:39936
	global_load_lds_dwordx4 v[228:229], off
	v_lshl_add_u64 v[228:229], s[34:35], 0, v[132:133]
	s_mov_b32 m0, s49
	s_nop 0
	global_load_lds_dwordx4 v[228:229], off
	s_waitcnt vmcnt(8)
	s_waitcnt lgkmcnt(0)
	s_barrier
	s_waitcnt lgkmcnt(0)
	v_mfma_f32_16x16x32_bf16 v[124:127], v[146:149], v[188:191], v[124:127]
	v_mfma_f32_16x16x32_bf16 v[120:123], v[164:167], v[188:191], v[120:123]
	v_mfma_f32_16x16x32_bf16 v[108:111], v[146:149], v[196:199], v[108:111]
	v_mfma_f32_16x16x32_bf16 v[104:107], v[164:167], v[196:199], v[104:107]
	v_mfma_f32_16x16x32_bf16 v[92:95], v[146:149], v[204:207], v[92:95]
	v_mfma_f32_16x16x32_bf16 v[88:91], v[164:167], v[204:207], v[88:91]
	v_mfma_f32_16x16x32_bf16 v[76:79], v[146:149], v[212:215], v[76:79]
	v_mfma_f32_16x16x32_bf16 v[72:75], v[164:167], v[212:215], v[72:75]
	v_mfma_f32_16x16x32_bf16 v[124:127], v[150:153], v[192:195], v[124:127]
	v_mfma_f32_16x16x32_bf16 v[120:123], v[168:171], v[192:195], v[120:123]
	v_mfma_f32_16x16x32_bf16 v[108:111], v[150:153], v[200:203], v[108:111]
	v_mfma_f32_16x16x32_bf16 v[104:107], v[168:171], v[200:203], v[104:107]
	v_mfma_f32_16x16x32_bf16 v[92:95], v[150:153], v[208:211], v[92:95]
	v_mfma_f32_16x16x32_bf16 v[88:91], v[168:171], v[208:211], v[88:91]
	v_mfma_f32_16x16x32_bf16 v[76:79], v[150:153], v[216:219], v[76:79]
	v_mfma_f32_16x16x32_bf16 v[72:75], v[168:171], v[216:219], v[72:75]
	v_mfma_f32_16x16x32_bf16 v[116:119], v[172:175], v[188:191], v[116:119]
	v_mfma_f32_16x16x32_bf16 v[112:115], v[180:183], v[188:191], v[112:115]
	v_mfma_f32_16x16x32_bf16 v[100:103], v[172:175], v[196:199], v[100:103]
	v_mfma_f32_16x16x32_bf16 v[96:99], v[180:183], v[196:199], v[96:99]
	v_mfma_f32_16x16x32_bf16 v[84:87], v[172:175], v[204:207], v[84:87]
	v_mfma_f32_16x16x32_bf16 v[80:83], v[180:183], v[204:207], v[80:83]
	v_mfma_f32_16x16x32_bf16 v[68:71], v[172:175], v[212:215], v[68:71]
	v_mfma_f32_16x16x32_bf16 v[64:67], v[180:183], v[212:215], v[64:67]
	v_mfma_f32_16x16x32_bf16 v[116:119], v[176:179], v[192:195], v[116:119]
	v_mfma_f32_16x16x32_bf16 v[112:115], v[184:187], v[192:195], v[112:115]
	v_mfma_f32_16x16x32_bf16 v[100:103], v[176:179], v[200:203], v[100:103]
	v_mfma_f32_16x16x32_bf16 v[96:99], v[184:187], v[200:203], v[96:99]
	v_mfma_f32_16x16x32_bf16 v[84:87], v[176:179], v[208:211], v[84:87]
	v_mfma_f32_16x16x32_bf16 v[80:83], v[184:187], v[208:211], v[80:83]
	v_mfma_f32_16x16x32_bf16 v[68:71], v[176:179], v[216:219], v[68:71]
	v_mfma_f32_16x16x32_bf16 v[64:67], v[184:187], v[216:219], v[64:67]
	s_barrier
	s_add_i32 s34, s64, s45
	v_lshl_add_u64 v[154:155], v[154:155], 0, s[18:19]
	s_mov_b32 m0, s34
	ds_read_b128 v[188:191], v161 offset:49152
	ds_read_b128 v[192:195], v161 offset:50176
	ds_read_b128 v[196:199], v161 offset:51200
	ds_read_b128 v[200:203], v161 offset:52224
	ds_read_b128 v[204:207], v161 offset:53248
	ds_read_b128 v[208:211], v161 offset:54272
	ds_read_b128 v[212:215], v161 offset:55296
	ds_read_b128 v[216:219], v161 offset:56320
	global_load_lds_dwordx4 v[154:155], off
	s_add_i32 m0, s34, 0x2000
	s_add_u32 s30, s30, 0x80080
	v_lshl_add_u64 v[154:155], v[220:221], 0, s[18:19]
	s_addc_u32 s31, s31, 0
	s_add_i32 s34, s65, s45
	global_load_lds_dwordx4 v[154:155], off
	v_lshl_add_u64 v[154:155], s[30:31], 0, v[130:131]
	s_mov_b32 m0, s34
	s_nop 0
	global_load_lds_dwordx4 v[154:155], off
	v_lshl_add_u64 v[154:155], s[30:31], 0, v[134:135]
	s_add_i32 m0, s34, 0x2000
	s_nop 0
	global_load_lds_dwordx4 v[154:155], off
	v_lshl_add_u64 v[154:155], v[222:223], 0, s[18:19]
	s_mov_b32 m0, s58
	s_nop 0
	global_load_lds_dwordx4 v[154:155], off
	v_lshl_add_u64 v[154:155], v[224:225], 0, s[18:19]
	s_mov_b32 m0, s59
	s_nop 0
	global_load_lds_dwordx4 v[154:155], off
	s_waitcnt vmcnt(8)
	s_waitcnt lgkmcnt(0)
	s_barrier
	s_waitcnt lgkmcnt(0)
	v_mfma_f32_16x16x32_bf16 v[60:63], v[146:149], v[188:191], v[60:63]
	v_mfma_f32_16x16x32_bf16 v[56:59], v[164:167], v[188:191], v[56:59]
	v_mfma_f32_16x16x32_bf16 v[44:47], v[146:149], v[196:199], v[44:47]
	v_mfma_f32_16x16x32_bf16 v[40:43], v[164:167], v[196:199], v[40:43]
	v_mfma_f32_16x16x32_bf16 v[28:31], v[146:149], v[204:207], v[28:31]
	v_mfma_f32_16x16x32_bf16 v[24:27], v[164:167], v[204:207], v[24:27]
	v_mfma_f32_16x16x32_bf16 v[12:15], v[146:149], v[212:215], v[12:15]
	v_mfma_f32_16x16x32_bf16 v[8:11], v[164:167], v[212:215], v[8:11]
	v_mfma_f32_16x16x32_bf16 v[60:63], v[150:153], v[192:195], v[60:63]
	v_mfma_f32_16x16x32_bf16 v[56:59], v[168:171], v[192:195], v[56:59]
	v_mfma_f32_16x16x32_bf16 v[44:47], v[150:153], v[200:203], v[44:47]
	v_mfma_f32_16x16x32_bf16 v[40:43], v[168:171], v[200:203], v[40:43]
	v_mfma_f32_16x16x32_bf16 v[28:31], v[150:153], v[208:211], v[28:31]
	v_mfma_f32_16x16x32_bf16 v[24:27], v[168:171], v[208:211], v[24:27]
	v_mfma_f32_16x16x32_bf16 v[12:15], v[150:153], v[216:219], v[12:15]
	v_mfma_f32_16x16x32_bf16 v[8:11], v[168:171], v[216:219], v[8:11]
	v_mfma_f32_16x16x32_bf16 v[52:55], v[172:175], v[188:191], v[52:55]
	v_mfma_f32_16x16x32_bf16 v[48:51], v[180:183], v[188:191], v[48:51]
	v_mfma_f32_16x16x32_bf16 v[36:39], v[172:175], v[196:199], v[36:39]
	v_mfma_f32_16x16x32_bf16 v[32:35], v[180:183], v[196:199], v[32:35]
	v_mfma_f32_16x16x32_bf16 v[20:23], v[172:175], v[204:207], v[20:23]
	v_mfma_f32_16x16x32_bf16 v[16:19], v[180:183], v[204:207], v[16:19]
	v_mfma_f32_16x16x32_bf16 v[4:7], v[172:175], v[212:215], v[4:7]
	v_mfma_f32_16x16x32_bf16 v[0:3], v[180:183], v[212:215], v[0:3]
	v_mfma_f32_16x16x32_bf16 v[52:55], v[176:179], v[192:195], v[52:55]
	v_mfma_f32_16x16x32_bf16 v[48:51], v[184:187], v[192:195], v[48:51]
	v_mfma_f32_16x16x32_bf16 v[36:39], v[176:179], v[200:203], v[36:39]
	v_mfma_f32_16x16x32_bf16 v[32:35], v[184:187], v[200:203], v[32:35]
	v_mfma_f32_16x16x32_bf16 v[20:23], v[176:179], v[208:211], v[20:23]
	v_mfma_f32_16x16x32_bf16 v[16:19], v[184:187], v[208:211], v[16:19]
	v_mfma_f32_16x16x32_bf16 v[4:7], v[176:179], v[216:219], v[4:7]
	v_mfma_f32_16x16x32_bf16 v[0:3], v[184:187], v[216:219], v[0:3]
	s_barrier
	s_add_u32 s41, s41, 0x100
	s_addc_u32 s42, s42, 0
	s_add_u32 s12, s12, 0x100
	s_addc_u32 s13, s13, 0
	s_cmp_ge_i32 s43, s56
	s_mov_b32 s30, s43
	s_cbranch_scc0 .LBB0_86
; #define PG8_BAR __builtin_amdgcn_s_barrier()
; template <class Epi, class Sched, bool ALIGN_EPI = false, bool SP2 = false>
; __device__ __forceinline__ void gemm_phase(PG8_LAS unsigned char* lds, const Gemm g, const Sched& S, const Epi& E) {
;     ...
;         if constexpr (ALIGN_EPI) { if (wr == 0) PG8_BAR; }
.LBB0_87:
	s_and_b64 vcc, exec, s[20:21]
	s_cbranch_vccz .LBB0_89
	s_barrier

;     __host__ __device__ bool next(int i, Unit& u) const { return i < cnt ? so.next(base + i, u) : false; }
;     __host__ __device__ bool next(int i, Unit& u) const { const int L = i * G + c; if (L >= 32) return false; u.g = L >> 3; u.pm = L & 7; u.pn = 0; return true; }
; #define PG8_STAGE(bufoff, gbase, voff) do { _Pragma("unroll") for (int _i = 0; _i < 2; ++_i) \
;         __builtin_amdgcn_global_load_lds((const unsigned*)((const char*)(gbase) + (voff)[_i]), (PG8_LAS unsigned*)(lds + (bufoff) + ldsw + _i * 8192), 16, 0, 0); } while (0)
; #define PG8_LDA(dst, b, h) do { _Pragma("unroll") for (int m = 0; m < 4; ++m) _Pragma("unroll") for (int k = 0; k < 2; ++k) dst[m][k] = *(const PG8_LAS bf16x8*)(lds + PG8_SA(b, h) + aoff + m * 2048 + k * 1024); } while (0)
; #define PG8_SCHED __builtin_amdgcn_sched_barrier(0)
; template <class Epi, class Sched, bool ALIGN_EPI = false, bool SP2 = false>
; __device__ __forceinline__ void gemm_phase(PG8_LAS unsigned char* lds, const Gemm g, const Sched& S, const Epi& E) {
;     ...
;         const bool has_next = S.next(ui + 1, nxt);
;         const char* nA = has_next ? (const char*)(g.A + (size_t)nxt.g * g.gsA) + (size_t)nxt.pm * tstepA : cA; const char* nB = has_next ? (const char*)(g.Bt + (size_t)nxt.g * g.gsB) + (size_t)nxt.pn * tstepB : cB;
;         for (int t = 0; t < nt; t += 2) {
;             if constexpr (Epi::MIDK) { if (t == (nt >> 1)) { asm volatile("s_waitcnt vmcnt(0)" ::: "memory"); E.mid(acc, cur, wr, wc, fr, fq); asm volatile("s_waitcnt vmcnt(0)" ::: "memory"); } }
;             const bool last = (t == nt - 2);
;             const char* a1 = cA + (size_t)(t + 1) * kstep;
;             const char* a2 = last ? nA : cA + (size_t)(t + 2) * kstep; const char* b2 = last ? nB : cB + (size_t)(t + 2) * kstep;
;             const char* a3 = a2 + kstep; const char* b3 = b2 + kstep;
;             if (last && has_next) S.a_ready(nxt);
;             if constexpr (SP2) {
;             PG8_LDB(B0, 0, 0); PG8_LDB(B1, 0, 1); PG8_SCHED; PG8_LDA(At, 0, 0); PG8_STAGE(PG8_SA(1, 1), a1 + hstepA, voffA);
;     ...
; #pragma unroll
;         for (int a = 0; a < 2; ++a)
; #pragma unroll
;             for (int b = 0; b < 2; ++b)
; #pragma unroll
;                 for (int m = 0; m < 4; ++m)
; #pragma unroll
;                     for (int n = 0; n < 2; ++n) acc[a][b][m][n] = (f32x4){0.f, 0.f, 0.f, 0.f};
;         cur = nxt; cA = nA; cB = nB; ++ui;
.LBB0_252:
	s_add_i32 s55, s55, 1
	s_mul_i32 s28, s55, s33
	s_add_i32 s28, s28, s2
	s_mov_b32 s19, s64
	s_mov_b32 s30, s63
	s_and_b32 s64, s28, 7
	s_ashr_i32 s63, s28, 3
	s_cmp_lt_i32 s28, 32
	s_cselect_b64 s[34:35], -1, 0
	s_and_b64 s[28:29], s[34:35], exec
	s_cselect_b32 s30, s63, s30
	s_cselect_b32 s28, s64, s19
	s_ashr_i32 s31, s30, 31
	s_lshl_b64 s[44:45], s[30:31], 9
	s_add_u32 s19, s37, s44
	s_addc_u32 s44, s38, s45
	s_ashr_i32 s29, s28, 31
	s_lshl_b64 s[28:29], s[28:29], 19
	s_add_u32 s28, s19, s28
	s_addc_u32 s29, s44, s29
	s_lshl_b64 s[30:31], s[30:31], 17
	s_add_u32 s30, s39, s30
	v_mov_b32_e32 v127, 0
	s_addc_u32 s31, s46, s31
	s_and_b64 vcc, exec, s[4:5]
	v_mov_b32_e32 v126, v127
	v_mov_b32_e32 v125, v127
	v_mov_b32_e32 v124, v127
	v_mov_b32_e32 v123, v127
	v_mov_b32_e32 v122, v127
	v_mov_b32_e32 v121, v127
	v_mov_b32_e32 v120, v127
	v_mov_b32_e32 v111, v127
	v_mov_b32_e32 v110, v127
	v_mov_b32_e32 v109, v127
	v_mov_b32_e32 v108, v127
	v_mov_b32_e32 v107, v127
	v_mov_b32_e32 v106, v127
	v_mov_b32_e32 v105, v127
	v_mov_b32_e32 v104, v127
	v_mov_b32_e32 v95, v127
	v_mov_b32_e32 v94, v127
	v_mov_b32_e32 v93, v127
	v_mov_b32_e32 v92, v127
	v_mov_b32_e32 v91, v127
	v_mov_b32_e32 v90, v127
	v_mov_b32_e32 v89, v127
	v_mov_b32_e32 v88, v127
	v_mov_b32_e32 v79, v127
	v_mov_b32_e32 v78, v127
	v_mov_b32_e32 v77, v127
	v_mov_b32_e32 v76, v127
	v_mov_b32_e32 v75, v127
	v_mov_b32_e32 v74, v127
	v_mov_b32_e32 v73, v127
	v_mov_b32_e32 v72, v127
	v_mov_b32_e32 v119, v127
	v_mov_b32_e32 v118, v127
	v_mov_b32_e32 v117, v127
	v_mov_b32_e32 v116, v127
	v_mov_b32_e32 v115, v127
	v_mov_b32_e32 v114, v127
	v_mov_b32_e32 v113, v127
	v_mov_b32_e32 v112, v127
	v_mov_b32_e32 v103, v127
	v_mov_b32_e32 v102, v127
	v_mov_b32_e32 v101, v127
	v_mov_b32_e32 v100, v127
	v_mov_b32_e32 v99, v127
	v_mov_b32_e32 v98, v127
	v_mov_b32_e32 v97, v127
	v_mov_b32_e32 v96, v127
	v_mov_b32_e32 v87, v127
	v_mov_b32_e32 v86, v127
	v_mov_b32_e32 v85, v127
	v_mov_b32_e32 v84, v127
	v_mov_b32_e32 v83, v127
	v_mov_b32_e32 v82, v127
	v_mov_b32_e32 v81, v127
	v_mov_b32_e32 v80, v127
	v_mov_b32_e32 v71, v127
	v_mov_b32_e32 v70, v127
	v_mov_b32_e32 v69, v127
	v_mov_b32_e32 v68, v127
	v_mov_b32_e32 v67, v127
	v_mov_b32_e32 v66, v127
	v_mov_b32_e32 v65, v127
	v_mov_b32_e32 v64, v127
	v_mov_b32_e32 v63, v127
	v_mov_b32_e32 v62, v127
	v_mov_b32_e32 v61, v127
	v_mov_b32_e32 v60, v127
	v_mov_b32_e32 v59, v127
	v_mov_b32_e32 v58, v127
	v_mov_b32_e32 v57, v127
	v_mov_b32_e32 v56, v127
	v_mov_b32_e32 v47, v127
	v_mov_b32_e32 v46, v127
	v_mov_b32_e32 v45, v127
	v_mov_b32_e32 v44, v127
	v_mov_b32_e32 v43, v127
	v_mov_b32_e32 v42, v127
	v_mov_b32_e32 v41, v127
	v_mov_b32_e32 v40, v127
	v_mov_b32_e32 v31, v127
	v_mov_b32_e32 v30, v127
	v_mov_b32_e32 v29, v127
	v_mov_b32_e32 v28, v127
	v_mov_b32_e32 v27, v127
	v_mov_b32_e32 v26, v127
	v_mov_b32_e32 v25, v127
	v_mov_b32_e32 v24, v127
	v_mov_b32_e32 v15, v127
	v_mov_b32_e32 v14, v127
	v_mov_b32_e32 v13, v127
	v_mov_b32_e32 v12, v127
	v_mov_b32_e32 v11, v127
	v_mov_b32_e32 v10, v127
	v_mov_b32_e32 v9, v127
	v_mov_b32_e32 v8, v127
	v_mov_b32_e32 v55, v127
	v_mov_b32_e32 v54, v127
	v_mov_b32_e32 v53, v127
	v_mov_b32_e32 v52, v127
	v_mov_b32_e32 v51, v127
	v_mov_b32_e32 v50, v127
	v_mov_b32_e32 v49, v127
	v_mov_b32_e32 v48, v127
	v_mov_b32_e32 v39, v127
	v_mov_b32_e32 v38, v127
	v_mov_b32_e32 v37, v127
	v_mov_b32_e32 v36, v127
	v_mov_b32_e32 v35, v127
	v_mov_b32_e32 v34, v127
	v_mov_b32_e32 v33, v127
	v_mov_b32_e32 v32, v127
	v_mov_b32_e32 v23, v127
	v_mov_b32_e32 v22, v127
	v_mov_b32_e32 v21, v127
	v_mov_b32_e32 v20, v127
	v_mov_b32_e32 v19, v127
	v_mov_b32_e32 v18, v127
	v_mov_b32_e32 v17, v127
	v_mov_b32_e32 v16, v127
	v_mov_b32_e32 v7, v127
	v_mov_b32_e32 v6, v127
	v_mov_b32_e32 v5, v127
	v_mov_b32_e32 v4, v127
	v_mov_b32_e32 v3, v127
	v_mov_b32_e32 v2, v127
	v_mov_b32_e32 v1, v127
	v_mov_b32_e32 v0, v127
	s_cbranch_vccnz .LBB0_255
	s_and_b64 s[44:45], s[34:35], exec
	s_cselect_b32 s19, s29, s43
	s_cselect_b32 s65, s28, s42
	s_cselect_b32 s66, s31, s41
	s_cselect_b32 s67, s30, s40
	s_add_u32 s68, s40, 0x100
	s_addc_u32 s69, s41, 0
	s_add_u32 s40, s42, 0x40080
	s_addc_u32 s41, s43, 0
	s_mov_b32 s42, 0
.LBB0_254:
	ds_read_b128 v[148:151], v144
	ds_read_b128 v[152:155], v144 offset:1024
	ds_read_b128 v[156:159], v144 offset:2048
	ds_read_b128 v[160:163], v144 offset:3072
	ds_read_b128 v[164:167], v145
	ds_read_b128 v[168:171], v145 offset:1024
	ds_read_b128 v[172:175], v145 offset:2048
	ds_read_b128 v[176:179], v145 offset:3072
	s_add_i32 s70, s42, 2
	s_add_u32 s43, s40, 0xfffc0080
	s_addc_u32 s44, s41, -1
	s_cmp_eq_u32 s56, s42
	s_cselect_b32 s42, s67, s68
	s_cselect_b32 s45, s19, s44
	s_cselect_b32 s44, s65, s43
	s_cselect_b32 s43, s66, s69
	v_lshl_add_u64 v[212:213], s[40:41], 0, v[138:139]
	s_add_i32 m0, s48, 0xc000
	ds_read_b128 v[180:183], v146
	ds_read_b128 v[184:187], v146 offset:1024
	ds_read_b128 v[188:191], v146 offset:2048
	ds_read_b128 v[192:195], v146 offset:3072
	ds_read_b128 v[196:199], v146 offset:4096
	ds_read_b128 v[200:203], v146 offset:5120
	ds_read_b128 v[204:207], v146 offset:6144
	ds_read_b128 v[208:211], v146 offset:7168
	global_load_lds_dwordx4 v[212:213], off
	v_lshl_add_u64 v[212:213], s[40:41], 0, v[136:137]
	s_add_i32 m0, s48, 0xe000
	s_nop 0
	global_load_lds_dwordx4 v[212:213], off
	s_waitcnt vmcnt(8)
	s_waitcnt lgkmcnt(0)
	s_barrier
; #define PG8_STAGE(bufoff, gbase, voff) do { _Pragma("unroll") for (int _i = 0; _i < 2; ++_i) \
;         __builtin_amdgcn_global_load_lds((const unsigned*)((const char*)(gbase) + (voff)[_i]), (PG8_LAS unsigned*)(lds + (bufoff) + ldsw + _i * 8192), 16, 0, 0); } while (0)
; #define PG8_LDA(dst, b, h) do { _Pragma("unroll") for (int m = 0; m < 4; ++m) _Pragma("unroll") for (int k = 0; k < 2; ++k) dst[m][k] = *(const PG8_LAS bf16x8*)(lds + PG8_SA(b, h) + aoff + m * 2048 + k * 1024); } while (0)
; #define PG8_LDB(dst, b, h) do { _Pragma("unroll") for (int n = 0; n < 2; ++n) _Pragma("unroll") for (int k = 0; k < 2; ++k) dst[n][k] = *(const PG8_LAS bf16x8*)(lds + PG8_SB(b, h) + boff + n * 2048 + k * 1024); } while (0)
; #define PG8_MMA(ai, bj, At, Bt) do { __builtin_amdgcn_s_setprio(1); _Pragma("unroll") for (int m = 0; m < 4; ++m) _Pragma("unroll") for (int n = 0; n < 2; ++n) _Pragma("unroll") for (int k = 0; k < 2; ++k) \
;         acc[ai][bj][m][n] = __builtin_amdgcn_mfma_f32_16x16x32_bf16(Bt[n][k], At[m][k], acc[ai][bj][m][n], 0, 0, 0); __builtin_amdgcn_s_setprio(0); } while (0)
; #define PG8_WAIT_V(n) asm volatile("s_waitcnt vmcnt(" #n ")" ::: "memory")
; #define PG8_WAIT_L(n) asm volatile("s_waitcnt lgkmcnt(" #n ")" ::: "memory")
; #define PG8_BAR __builtin_amdgcn_s_barrier()
; #define PG8_SCHED __builtin_amdgcn_sched_barrier(0)
; template <class Epi, class Sched, bool ALIGN_EPI = false, bool SP2 = false>
; __device__ __forceinline__ void gemm_phase(PG8_LAS unsigned char* lds, const Gemm g, const Sched& S, const Epi& E) {
;     ...
;             PG8_WAIT_V(8); PG8_WAIT_L(0); PG8_BAR; PG8_MMA(0, 0, At, B0); PG8_MMA(0, 1, At, B1); PG8_BAR; PG8_SCHED;
;             PG8_LDA(At, 0, 1); PG8_STAGE(PG8_SB(0, 0), b2, voffB); PG8_STAGE(PG8_SB(0, 1), b2 + hstepB, voffB); PG8_STAGE(PG8_SA(0, 0), a2, voffA);
;             PG8_WAIT_V(8); PG8_WAIT_L(0); PG8_BAR; PG8_MMA(1, 0, At, B0); PG8_MMA(1, 1, At, B1); PG8_BAR; PG8_SCHED;
;             PG8_LDB(B0, 1, 0); PG8_LDB(B1, 1, 1); PG8_SCHED; PG8_LDA(At, 1, 0); PG8_STAGE(PG8_SA(0, 1), a2 + hstepA, voffA);
;             PG8_WAIT_V(8); PG8_WAIT_L(0); PG8_BAR; PG8_MMA(0, 0, At, B0); PG8_MMA(0, 1, At, B1); PG8_BAR; PG8_SCHED;
	s_waitcnt lgkmcnt(0)
	v_mfma_f32_16x16x32_bf16 v[124:127], v[148:151], v[180:183], v[124:127]
	v_mfma_f32_16x16x32_bf16 v[120:123], v[156:159], v[180:183], v[120:123]
	v_mfma_f32_16x16x32_bf16 v[108:111], v[148:151], v[188:191], v[108:111]
	v_mfma_f32_16x16x32_bf16 v[104:107], v[156:159], v[188:191], v[104:107]
	v_mfma_f32_16x16x32_bf16 v[92:95], v[148:151], v[196:199], v[92:95]
	v_mfma_f32_16x16x32_bf16 v[88:91], v[156:159], v[196:199], v[88:91]
	v_mfma_f32_16x16x32_bf16 v[76:79], v[148:151], v[204:207], v[76:79]
	v_mfma_f32_16x16x32_bf16 v[72:75], v[156:159], v[204:207], v[72:75]
	v_mfma_f32_16x16x32_bf16 v[124:127], v[152:155], v[184:187], v[124:127]
	v_mfma_f32_16x16x32_bf16 v[120:123], v[160:163], v[184:187], v[120:123]
	v_mfma_f32_16x16x32_bf16 v[108:111], v[152:155], v[192:195], v[108:111]
	v_mfma_f32_16x16x32_bf16 v[104:107], v[160:163], v[192:195], v[104:107]
	v_mfma_f32_16x16x32_bf16 v[92:95], v[152:155], v[200:203], v[92:95]
	v_mfma_f32_16x16x32_bf16 v[88:91], v[160:163], v[200:203], v[88:91]
	v_mfma_f32_16x16x32_bf16 v[76:79], v[152:155], v[208:211], v[76:79]
	v_mfma_f32_16x16x32_bf16 v[72:75], v[160:163], v[208:211], v[72:75]
	v_mfma_f32_16x16x32_bf16 v[116:119], v[164:167], v[180:183], v[116:119]
	v_mfma_f32_16x16x32_bf16 v[112:115], v[172:175], v[180:183], v[112:115]
	v_mfma_f32_16x16x32_bf16 v[100:103], v[164:167], v[188:191], v[100:103]
	v_mfma_f32_16x16x32_bf16 v[96:99], v[172:175], v[188:191], v[96:99]
	v_mfma_f32_16x16x32_bf16 v[84:87], v[164:167], v[196:199], v[84:87]
	v_mfma_f32_16x16x32_bf16 v[80:83], v[172:175], v[196:199], v[80:83]
	v_mfma_f32_16x16x32_bf16 v[68:71], v[164:167], v[204:207], v[68:71]
	v_mfma_f32_16x16x32_bf16 v[64:67], v[172:175], v[204:207], v[64:67]
	v_mfma_f32_16x16x32_bf16 v[116:119], v[168:171], v[184:187], v[116:119]
	v_mfma_f32_16x16x32_bf16 v[112:115], v[176:179], v[184:187], v[112:115]
	v_mfma_f32_16x16x32_bf16 v[100:103], v[168:171], v[192:195], v[100:103]
	v_mfma_f32_16x16x32_bf16 v[96:99], v[176:179], v[192:195], v[96:99]
	v_mfma_f32_16x16x32_bf16 v[84:87], v[168:171], v[200:203], v[84:87]
	v_mfma_f32_16x16x32_bf16 v[80:83], v[176:179], v[200:203], v[80:83]
	v_mfma_f32_16x16x32_bf16 v[68:71], v[168:171], v[208:211], v[68:71]
	v_mfma_f32_16x16x32_bf16 v[64:67], v[176:179], v[208:211], v[64:67]
	s_barrier
	s_add_i32 s71, s58, s47
	v_lshl_add_u64 v[212:213], s[42:43], 0, v[132:133]
	s_mov_b32 m0, s71
	ds_read_b128 v[180:183], v146 offset:16384
	ds_read_b128 v[184:187], v146 offset:17408
	ds_read_b128 v[188:191], v146 offset:18432
	ds_read_b128 v[192:195], v146 offset:19456
	ds_read_b128 v[196:199], v146 offset:20480
	ds_read_b128 v[200:203], v146 offset:21504
	ds_read_b128 v[204:207], v146 offset:22528
	ds_read_b128 v[208:211], v146 offset:23552
	global_load_lds_dwordx4 v[212:213], off
	s_add_i32 m0, s71, 0x2000
	s_add_u32 s72, s42, 0x10000
	v_lshl_add_u64 v[214:215], s[42:43], 0, v[128:129]
	s_addc_u32 s73, s43, 0
	s_add_i32 s71, s59, s47
	global_load_lds_dwordx4 v[214:215], off
	v_lshl_add_u64 v[216:217], s[72:73], 0, v[132:133]
	s_mov_b32 m0, s71
	v_lshl_add_u64 v[218:219], s[44:45], 0, v[130:131]
	global_load_lds_dwordx4 v[216:217], off
	v_lshl_add_u64 v[216:217], s[72:73], 0, v[128:129]
	s_add_i32 m0, s71, 0x2000
	s_nop 0
	global_load_lds_dwordx4 v[216:217], off
	v_lshl_add_u64 v[216:217], s[44:45], 0, v[134:135]
	s_mov_b32 m0, s48
	s_nop 0
	global_load_lds_dwordx4 v[216:217], off
	s_mov_b32 m0, s49
	s_nop 0
	global_load_lds_dwordx4 v[218:219], off
	s_waitcnt vmcnt(8)
	s_waitcnt lgkmcnt(0)
	s_barrier
	s_waitcnt lgkmcnt(0)
	v_mfma_f32_16x16x32_bf16 v[60:63], v[148:151], v[180:183], v[60:63]
	v_mfma_f32_16x16x32_bf16 v[56:59], v[156:159], v[180:183], v[56:59]
	v_mfma_f32_16x16x32_bf16 v[44:47], v[148:151], v[188:191], v[44:47]
	v_mfma_f32_16x16x32_bf16 v[40:43], v[156:159], v[188:191], v[40:43]
	v_mfma_f32_16x16x32_bf16 v[28:31], v[148:151], v[196:199], v[28:31]
	v_mfma_f32_16x16x32_bf16 v[24:27], v[156:159], v[196:199], v[24:27]
	v_mfma_f32_16x16x32_bf16 v[12:15], v[148:151], v[204:207], v[12:15]
	v_mfma_f32_16x16x32_bf16 v[8:11], v[156:159], v[204:207], v[8:11]
	v_mfma_f32_16x16x32_bf16 v[60:63], v[152:155], v[184:187], v[60:63]
	v_mfma_f32_16x16x32_bf16 v[56:59], v[160:163], v[184:187], v[56:59]
	v_mfma_f32_16x16x32_bf16 v[44:47], v[152:155], v[192:195], v[44:47]
	v_mfma_f32_16x16x32_bf16 v[40:43], v[160:163], v[192:195], v[40:43]
	v_mfma_f32_16x16x32_bf16 v[28:31], v[152:155], v[200:203], v[28:31]
	v_mfma_f32_16x16x32_bf16 v[24:27], v[160:163], v[200:203], v[24:27]
	v_mfma_f32_16x16x32_bf16 v[12:15], v[152:155], v[208:211], v[12:15]
	v_mfma_f32_16x16x32_bf16 v[8:11], v[160:163], v[208:211], v[8:11]
	v_mfma_f32_16x16x32_bf16 v[52:55], v[164:167], v[180:183], v[52:55]
	v_mfma_f32_16x16x32_bf16 v[48:51], v[172:175], v[180:183], v[48:51]
	v_mfma_f32_16x16x32_bf16 v[36:39], v[164:167], v[188:191], v[36:39]
	v_mfma_f32_16x16x32_bf16 v[32:35], v[172:175], v[188:191], v[32:35]
	v_mfma_f32_16x16x32_bf16 v[20:23], v[164:167], v[196:199], v[20:23]
	v_mfma_f32_16x16x32_bf16 v[16:19], v[172:175], v[196:199], v[16:19]
	v_mfma_f32_16x16x32_bf16 v[4:7], v[164:167], v[204:207], v[4:7]
	v_mfma_f32_16x16x32_bf16 v[0:3], v[172:175], v[204:207], v[0:3]
	v_mfma_f32_16x16x32_bf16 v[52:55], v[168:171], v[184:187], v[52:55]
	v_mfma_f32_16x16x32_bf16 v[48:51], v[176:179], v[184:187], v[48:51]
	v_mfma_f32_16x16x32_bf16 v[36:39], v[168:171], v[192:195], v[36:39]
	v_mfma_f32_16x16x32_bf16 v[32:35], v[176:179], v[192:195], v[32:35]
	v_mfma_f32_16x16x32_bf16 v[20:23], v[168:171], v[200:203], v[20:23]
	v_mfma_f32_16x16x32_bf16 v[16:19], v[176:179], v[200:203], v[16:19]
	v_mfma_f32_16x16x32_bf16 v[4:7], v[168:171], v[208:211], v[4:7]
	v_mfma_f32_16x16x32_bf16 v[0:3], v[176:179], v[208:211], v[0:3]
	s_barrier
; #define PG8_STAGE(bufoff, gbase, voff) do { _Pragma("unroll") for (int _i = 0; _i < 2; ++_i) \
;         __builtin_amdgcn_global_load_lds((const unsigned*)((const char*)(gbase) + (voff)[_i]), (PG8_LAS unsigned*)(lds + (bufoff) + ldsw + _i * 8192), 16, 0, 0); } while (0)
; #define PG8_LDA(dst, b, h) do { _Pragma("unroll") for (int m = 0; m < 4; ++m) _Pragma("unroll") for (int k = 0; k < 2; ++k) dst[m][k] = *(const PG8_LAS bf16x8*)(lds + PG8_SA(b, h) + aoff + m * 2048 + k * 1024); } while (0)
; #define PG8_LDB(dst, b, h) do { _Pragma("unroll") for (int n = 0; n < 2; ++n) _Pragma("unroll") for (int k = 0; k < 2; ++k) dst[n][k] = *(const PG8_LAS bf16x8*)(lds + PG8_SB(b, h) + boff + n * 2048 + k * 1024); } while (0)
; #define PG8_MMA(ai, bj, At, Bt) do { __builtin_amdgcn_s_setprio(1); _Pragma("unroll") for (int m = 0; m < 4; ++m) _Pragma("unroll") for (int n = 0; n < 2; ++n) _Pragma("unroll") for (int k = 0; k < 2; ++k) \
;         acc[ai][bj][m][n] = __builtin_amdgcn_mfma_f32_16x16x32_bf16(Bt[n][k], At[m][k], acc[ai][bj][m][n], 0, 0, 0); __builtin_amdgcn_s_setprio(0); } while (0)
; #define PG8_WAIT_V(n) asm volatile("s_waitcnt vmcnt(" #n ")" ::: "memory")
; #define PG8_WAIT_L(n) asm volatile("s_waitcnt lgkmcnt(" #n ")" ::: "memory")
; #define PG8_BAR __builtin_amdgcn_s_barrier()
; #define PG8_SCHED __builtin_amdgcn_sched_barrier(0)
; template <class Epi, class Sched, bool ALIGN_EPI = false, bool SP2 = false>
; __device__ __forceinline__ void gemm_phase(PG8_LAS unsigned char* lds, const Gemm g, const Sched& S, const Epi& E) {
;     ...
;             PG8_LDB(B0, 1, 0); PG8_LDB(B1, 1, 1); PG8_SCHED; PG8_LDA(At, 1, 0); PG8_STAGE(PG8_SA(0, 1), a2 + hstepA, voffA);
;             PG8_WAIT_V(8); PG8_WAIT_L(0); PG8_BAR; PG8_MMA(0, 0, At, B0); PG8_MMA(0, 1, At, B1); PG8_BAR; PG8_SCHED;
;             PG8_LDA(At, 1, 1); PG8_STAGE(PG8_SB(1, 0), b3, voffB); PG8_STAGE(PG8_SB(1, 1), b3 + hstepB, voffB); PG8_STAGE(PG8_SA(1, 0), a3, voffA);
;             PG8_WAIT_V(8); PG8_WAIT_L(0); PG8_BAR; PG8_MMA(1, 0, At, B0); PG8_MMA(1, 1, At, B1); PG8_BAR; PG8_SCHED;
	s_add_i32 s71, 0, 0x18000
	v_add_u32_e32 v147, s71, v142
	s_add_i32 s72, 0, 0x1c000
	ds_read_b128 v[148:151], v147
	ds_read_b128 v[152:155], v147 offset:1024
	ds_read_b128 v[156:159], v147 offset:2048
	ds_read_b128 v[160:163], v147 offset:3072
	v_add_u32_e32 v147, s72, v142
	ds_read_b128 v[164:167], v147
	ds_read_b128 v[168:171], v147 offset:1024
	ds_read_b128 v[172:175], v147 offset:2048
	ds_read_b128 v[176:179], v147 offset:3072
	s_add_u32 s44, s44, 0x40000
	s_addc_u32 s45, s45, 0
	s_mov_b32 m0, s50
	v_lshl_add_u64 v[220:221], s[44:45], 0, v[134:135]
	ds_read_b128 v[180:183], v146 offset:32768
	ds_read_b128 v[184:187], v146 offset:33792
	ds_read_b128 v[188:191], v146 offset:34816
	ds_read_b128 v[192:195], v146 offset:35840
	ds_read_b128 v[196:199], v146 offset:36864
	ds_read_b128 v[200:203], v146 offset:37888
	ds_read_b128 v[204:207], v146 offset:38912
	ds_read_b128 v[208:211], v146 offset:39936
	global_load_lds_dwordx4 v[220:221], off
	v_lshl_add_u64 v[220:221], s[44:45], 0, v[130:131]
	s_mov_b32 m0, s51
	s_nop 0
	global_load_lds_dwordx4 v[220:221], off
	s_waitcnt vmcnt(8)
	s_waitcnt lgkmcnt(0)
	s_barrier
	s_waitcnt lgkmcnt(0)
	v_mfma_f32_16x16x32_bf16 v[124:127], v[148:151], v[180:183], v[124:127]
	v_mfma_f32_16x16x32_bf16 v[120:123], v[156:159], v[180:183], v[120:123]
	v_mfma_f32_16x16x32_bf16 v[108:111], v[148:151], v[188:191], v[108:111]
	v_mfma_f32_16x16x32_bf16 v[104:107], v[156:159], v[188:191], v[104:107]
	v_mfma_f32_16x16x32_bf16 v[92:95], v[148:151], v[196:199], v[92:95]
	v_mfma_f32_16x16x32_bf16 v[88:91], v[156:159], v[196:199], v[88:91]
	v_mfma_f32_16x16x32_bf16 v[76:79], v[148:151], v[204:207], v[76:79]
	v_mfma_f32_16x16x32_bf16 v[72:75], v[156:159], v[204:207], v[72:75]
	v_mfma_f32_16x16x32_bf16 v[124:127], v[152:155], v[184:187], v[124:127]
	v_mfma_f32_16x16x32_bf16 v[120:123], v[160:163], v[184:187], v[120:123]
	v_mfma_f32_16x16x32_bf16 v[108:111], v[152:155], v[192:195], v[108:111]
	v_mfma_f32_16x16x32_bf16 v[104:107], v[160:163], v[192:195], v[104:107]
	v_mfma_f32_16x16x32_bf16 v[92:95], v[152:155], v[200:203], v[92:95]
	v_mfma_f32_16x16x32_bf16 v[88:91], v[160:163], v[200:203], v[88:91]
	v_mfma_f32_16x16x32_bf16 v[76:79], v[152:155], v[208:211], v[76:79]
	v_mfma_f32_16x16x32_bf16 v[72:75], v[160:163], v[208:211], v[72:75]
	v_mfma_f32_16x16x32_bf16 v[116:119], v[164:167], v[180:183], v[116:119]
	v_mfma_f32_16x16x32_bf16 v[112:115], v[172:175], v[180:183], v[112:115]
	v_mfma_f32_16x16x32_bf16 v[100:103], v[164:167], v[188:191], v[100:103]
	v_mfma_f32_16x16x32_bf16 v[96:99], v[172:175], v[188:191], v[96:99]
	v_mfma_f32_16x16x32_bf16 v[84:87], v[164:167], v[196:199], v[84:87]
	v_mfma_f32_16x16x32_bf16 v[80:83], v[172:175], v[196:199], v[80:83]
	v_mfma_f32_16x16x32_bf16 v[68:71], v[164:167], v[204:207], v[68:71]
	v_mfma_f32_16x16x32_bf16 v[64:67], v[172:175], v[204:207], v[64:67]
	v_mfma_f32_16x16x32_bf16 v[116:119], v[168:171], v[184:187], v[116:119]
	v_mfma_f32_16x16x32_bf16 v[112:115], v[176:179], v[184:187], v[112:115]
	v_mfma_f32_16x16x32_bf16 v[100:103], v[168:171], v[192:195], v[100:103]
	v_mfma_f32_16x16x32_bf16 v[96:99], v[176:179], v[192:195], v[96:99]
	v_mfma_f32_16x16x32_bf16 v[84:87], v[168:171], v[200:203], v[84:87]
	v_mfma_f32_16x16x32_bf16 v[80:83], v[176:179], v[200:203], v[80:83]
	v_mfma_f32_16x16x32_bf16 v[68:71], v[168:171], v[208:211], v[68:71]
	v_mfma_f32_16x16x32_bf16 v[64:67], v[176:179], v[208:211], v[64:67]
	s_barrier
	s_add_i32 s44, s71, s47
	v_lshl_add_u64 v[212:213], v[212:213], 0, s[8:9]
	s_mov_b32 m0, s44
	ds_read_b128 v[180:183], v146 offset:49152
	ds_read_b128 v[184:187], v146 offset:50176
	ds_read_b128 v[188:191], v146 offset:51200
	ds_read_b128 v[192:195], v146 offset:52224
	ds_read_b128 v[196:199], v146 offset:53248
	ds_read_b128 v[200:203], v146 offset:54272
	ds_read_b128 v[204:207], v146 offset:55296
	ds_read_b128 v[208:211], v146 offset:56320
	global_load_lds_dwordx4 v[212:213], off
	s_add_i32 m0, s44, 0x2000
	s_add_u32 s42, s42, 0x10080
	v_lshl_add_u64 v[212:213], v[214:215], 0, s[8:9]
	s_addc_u32 s43, s43, 0
	s_add_i32 s44, s72, s47
	global_load_lds_dwordx4 v[212:213], off
	v_lshl_add_u64 v[212:213], s[42:43], 0, v[132:133]
	s_mov_b32 m0, s44
	s_nop 0
	global_load_lds_dwordx4 v[212:213], off
	v_lshl_add_u64 v[212:213], s[42:43], 0, v[128:129]
	s_add_i32 m0, s44, 0x2000
	s_nop 0
	global_load_lds_dwordx4 v[212:213], off
	v_lshl_add_u64 v[212:213], v[216:217], 0, s[8:9]
	s_mov_b32 m0, s53
	s_nop 0
	global_load_lds_dwordx4 v[212:213], off
	v_lshl_add_u64 v[212:213], v[218:219], 0, s[8:9]
	s_mov_b32 m0, s54
	s_nop 0
	global_load_lds_dwordx4 v[212:213], off
	s_waitcnt vmcnt(8)
	s_waitcnt lgkmcnt(0)
	s_barrier
	s_waitcnt lgkmcnt(0)
	v_mfma_f32_16x16x32_bf16 v[60:63], v[148:151], v[180:183], v[60:63]
	v_mfma_f32_16x16x32_bf16 v[56:59], v[156:159], v[180:183], v[56:59]
	v_mfma_f32_16x16x32_bf16 v[44:47], v[148:151], v[188:191], v[44:47]
	v_mfma_f32_16x16x32_bf16 v[40:43], v[156:159], v[188:191], v[40:43]
	v_mfma_f32_16x16x32_bf16 v[28:31], v[148:151], v[196:199], v[28:31]
	v_mfma_f32_16x16x32_bf16 v[24:27], v[156:159], v[196:199], v[24:27]
	v_mfma_f32_16x16x32_bf16 v[12:15], v[148:151], v[204:207], v[12:15]
	v_mfma_f32_16x16x32_bf16 v[8:11], v[156:159], v[204:207], v[8:11]
	v_mfma_f32_16x16x32_bf16 v[60:63], v[152:155], v[184:187], v[60:63]
	v_mfma_f32_16x16x32_bf16 v[56:59], v[160:163], v[184:187], v[56:59]
	v_mfma_f32_16x16x32_bf16 v[44:47], v[152:155], v[192:195], v[44:47]
	v_mfma_f32_16x16x32_bf16 v[40:43], v[160:163], v[192:195], v[40:43]
	v_mfma_f32_16x16x32_bf16 v[28:31], v[152:155], v[200:203], v[28:31]
	v_mfma_f32_16x16x32_bf16 v[24:27], v[160:163], v[200:203], v[24:27]
	v_mfma_f32_16x16x32_bf16 v[12:15], v[152:155], v[208:211], v[12:15]
	v_mfma_f32_16x16x32_bf16 v[8:11], v[160:163], v[208:211], v[8:11]
	v_mfma_f32_16x16x32_bf16 v[52:55], v[164:167], v[180:183], v[52:55]
	v_mfma_f32_16x16x32_bf16 v[48:51], v[172:175], v[180:183], v[48:51]
	v_mfma_f32_16x16x32_bf16 v[36:39], v[164:167], v[188:191], v[36:39]
	v_mfma_f32_16x16x32_bf16 v[32:35], v[172:175], v[188:191], v[32:35]
	v_mfma_f32_16x16x32_bf16 v[20:23], v[164:167], v[196:199], v[20:23]
	v_mfma_f32_16x16x32_bf16 v[16:19], v[172:175], v[196:199], v[16:19]
	v_mfma_f32_16x16x32_bf16 v[4:7], v[164:167], v[204:207], v[4:7]
	v_mfma_f32_16x16x32_bf16 v[0:3], v[172:175], v[204:207], v[0:3]
	v_mfma_f32_16x16x32_bf16 v[52:55], v[168:171], v[184:187], v[52:55]
	v_mfma_f32_16x16x32_bf16 v[48:51], v[176:179], v[184:187], v[48:51]
	v_mfma_f32_16x16x32_bf16 v[36:39], v[168:171], v[192:195], v[36:39]
	v_mfma_f32_16x16x32_bf16 v[32:35], v[176:179], v[192:195], v[32:35]
	v_mfma_f32_16x16x32_bf16 v[20:23], v[168:171], v[200:203], v[20:23]
	v_mfma_f32_16x16x32_bf16 v[16:19], v[176:179], v[200:203], v[16:19]
	v_mfma_f32_16x16x32_bf16 v[4:7], v[168:171], v[208:211], v[4:7]
	v_mfma_f32_16x16x32_bf16 v[0:3], v[176:179], v[208:211], v[0:3]
	s_barrier
	s_add_u32 s68, s68, 0x100
	s_addc_u32 s69, s69, 0
	s_add_u32 s40, s40, 0x100
	s_addc_u32 s41, s41, 0
	s_cmp_ge_i32 s70, s52
	s_mov_b32 s42, s70
	s_cbranch_scc0 .LBB0_254
; #define PG8_BAR __builtin_amdgcn_s_barrier()
; template <class Epi, class Sched, bool ALIGN_EPI = false, bool SP2 = false>
; __device__ __forceinline__ void gemm_phase(PG8_LAS unsigned char* lds, const Gemm g, const Sched& S, const Epi& E) {
;     ...
;         if constexpr (ALIGN_EPI) { if (wr == 0) PG8_BAR; }
.LBB0_255:
	s_and_b64 vcc, exec, s[16:17]
	s_cbranch_vccz .LBB0_257
	s_barrier

; #define RT_(aw, pw, lo) ((lo ? bf_lo(aw) : bf_hi(aw)) * __builtin_amdgcn_rcpf(fmaxf(lo ? bf_lo(pw) : bf_hi(pw), 1e-30f)))
;     __device__ __forceinline__ void mid(f32x4 (&acc)[2][2][4][2], const Unit& u, int wr, int wc, int fr, int fq) const {
;         const int col0 = u.pn * BM + wc * 32 + 8 * fq, row0 = u.pm * BM + wr * 64 + fr;
;         unsigned long long ro_ = ((unsigned long long)row0 * 2048 + col0) * 2; asm volatile("" : "+v"(ro_));
;         const bf16_t* ga = (const bf16_t*)((const char*)GA + ro_); const bf16_t* gp = (const bf16_t*)((const char*)GP + ro_);
; #pragma unroll
;         for (int ai = 0; ai < 2; ++ai)
; #pragma unroll
;             for (int m = 0; m < 4; ++m)
; #pragma unroll
;                 for (int bj = 0; bj < 2; ++bj) { const size_t o_ = (size_t)(ai * HALF + m * 16) * 2048 + bj * HALF;
;                     const u32x4 a = *(const u32x4*)(ga + o_), p = *(const u32x4*)(gp + o_);
;     ...
;                     acc[ai][bj][m][0][0] *= RT_(a.x, p.x, 1); acc[ai][bj][m][0][1] *= RT_(a.x, p.x, 0); acc[ai][bj][m][0][2] *= RT_(a.y, p.y, 1); acc[ai][bj][m][0][3] *= RT_(a.y, p.y, 0);
;                     acc[ai][bj][m][1][0] *= RT_(a.z, p.z, 1); acc[ai][bj][m][1][1] *= RT_(a.z, p.z, 0); acc[ai][bj][m][1][2] *= RT_(a.w, p.w, 1); acc[ai][bj][m][1][3] *= RT_(a.w, p.w, 0);
;     ...
;                     asm volatile("" ::: "memory"); }
;     }
.LBB0_672:
	v_mov_b64_e32 v[128:129], v[180:181]
	s_waitcnt vmcnt(0)
	s_nop 0
	v_lshl_add_u64 v[182:183], s[12:13], 0, v[128:129]
	v_lshl_add_u64 v[184:185], s[10:11], 0, v[128:129]
	flat_load_dwordx4 v[136:139], v[182:183]
	flat_load_dwordx4 v[140:143], v[184:185]
	flat_load_dwordx4 v[150:153], v[182:183] offset:256
	flat_load_dwordx4 v[154:157], v[184:185] offset:256
	v_add_co_u32_e32 v144, vcc, s56, v184
	s_waitcnt vmcnt(0) lgkmcnt(0)
	v_lshlrev_b32_e32 v158, 16, v136
	v_addc_co_u32_e32 v145, vcc, 0, v185, vcc
	v_add_co_u32_e32 v148, vcc, s56, v182
	v_and_b32_e32 v159, 0xffff0000, v136
	s_nop 0
	v_addc_co_u32_e32 v149, vcc, 0, v183, vcc
	flat_load_dwordx4 v[128:131], v[144:145]
	flat_load_dwordx4 v[132:135], v[148:149]
	v_lshlrev_b32_e32 v146, 16, v140
	v_and_b32_e32 v147, 0xffff0000, v140
	v_lshlrev_b32_e32 v177, 16, v137
	v_and_b32_e32 v179, 0xffff0000, v137
	v_lshlrev_b32_e32 v136, 16, v141
	v_and_b32_e32 v137, 0xffff0000, v141
	v_lshlrev_b32_e32 v140, 16, v142
	v_and_b32_e32 v141, 0xffff0000, v142
	v_lshlrev_b32_e32 v142, 16, v139
	v_and_b32_e32 v194, 0xffff0000, v139
	v_lshlrev_b32_e32 v192, 16, v138
	v_and_b32_e32 v193, 0xffff0000, v138
	v_lshlrev_b32_e32 v138, 16, v143
	v_and_b32_e32 v139, 0xffff0000, v143
	v_max_f32_e32 v158, v158, v158
	v_max_f32_e32 v159, v159, v159
	v_max_f32_e32 v195, v142, v142
	v_max_f32_e32 v194, v194, v194
	v_lshlrev_b32_e32 v142, 16, v154
	v_and_b32_e32 v143, 0xffff0000, v154
	v_lshlrev_b32_e32 v154, 16, v151
	v_and_b32_e32 v198, 0xffff0000, v151
	v_lshlrev_b32_e32 v196, 16, v150
	v_and_b32_e32 v197, 0xffff0000, v150
	v_lshlrev_b32_e32 v150, 16, v155
	v_and_b32_e32 v151, 0xffff0000, v155
	v_max_f32_e32 v155, 0xda24260, v158
	v_max_f32_e32 v158, 0xda24260, v159
	v_max_f32_e32 v195, 0xda24260, v195
	v_max_f32_e32 v199, 0xda24260, v194
	v_max_f32_e32 v201, v154, v154
	v_max_f32_e32 v198, v198, v198
	v_rcp_f32_e32 v154, v155
	v_rcp_f32_e32 v155, v158
	v_rcp_f32_e32 v194, v195
	v_rcp_f32_e32 v195, v199
	v_max_f32_e32 v199, 0xda24260, v201
	v_max_f32_e32 v201, 0xda24260, v198
	v_rcp_f32_e32 v198, v199
	v_rcp_f32_e32 v199, v201
	v_max_f32_e32 v177, v177, v177
	v_max_f32_e32 v179, v179, v179
	v_max_f32_e32 v192, v192, v192
	v_pk_mul_f32 v[146:147], v[154:155], v[146:147]
	v_pk_mul_f32 v[138:139], v[194:195], v[138:139]
	v_max_f32_e32 v159, 0xda24260, v177
	v_max_f32_e32 v177, 0xda24260, v179
	v_max_f32_e32 v179, 0xda24260, v192
	v_max_f32_e32 v196, v196, v196
	v_max_f32_e32 v197, v197, v197
	v_pk_mul_f32 v[124:125], v[124:125], v[146:147]
	v_pk_mul_f32 v[122:123], v[122:123], v[138:139]
	v_pk_mul_f32 v[138:139], v[198:199], v[150:151]
	flat_load_dwordx4 v[144:147], v[144:145] offset:256
	s_nop 0
	flat_load_dwordx4 v[148:151], v[148:149] offset:256
	v_rcp_f32_e32 v158, v159
	v_rcp_f32_e32 v159, v177
	v_rcp_f32_e32 v192, v179
	v_max_f32_e32 v177, 0xda24260, v196
	v_max_f32_e32 v179, 0xda24260, v197
	v_rcp_f32_e32 v196, v177
	v_rcp_f32_e32 v197, v179
	v_pk_mul_f32 v[136:137], v[158:159], v[136:137]
	v_lshlrev_b32_e32 v200, 16, v152
	v_pk_mul_f32 v[126:127], v[126:127], v[136:137]
	v_pk_mul_f32 v[136:137], v[196:197], v[142:143]
	v_pk_mul_f32 v[118:119], v[118:119], v[138:139]
	v_pk_mul_f32 v[116:117], v[116:117], v[136:137]
	v_and_b32_e32 v137, 0xffff0000, v152
	v_max_f32_e32 v136, v200, v200
	v_max_f32_e32 v137, v137, v137
	v_max_f32_e32 v136, 0xda24260, v136
	v_max_f32_e32 v137, 0xda24260, v137
	v_rcp_f32_e32 v136, v136
	v_rcp_f32_e32 v137, v137
	v_lshlrev_b32_e32 v138, 16, v156
	v_and_b32_e32 v139, 0xffff0000, v156
	v_max_f32_e32 v193, v193, v193
	v_pk_mul_f32 v[136:137], v[136:137], v[138:139]
	v_lshlrev_b32_e32 v138, 16, v153
	v_and_b32_e32 v139, 0xffff0000, v153
	v_max_f32_e32 v138, v138, v138
	v_max_f32_e32 v139, v139, v139
	v_max_f32_e32 v138, 0xda24260, v138
	v_max_f32_e32 v139, 0xda24260, v139
	v_rcp_f32_e32 v138, v138
	v_rcp_f32_e32 v139, v139
	v_pk_mul_f32 v[112:113], v[112:113], v[136:137]
	v_lshlrev_b32_e32 v136, 16, v157
	v_and_b32_e32 v137, 0xffff0000, v157
	v_pk_mul_f32 v[136:137], v[138:139], v[136:137]
	s_waitcnt vmcnt(0) lgkmcnt(0)
	v_lshlrev_b32_e32 v138, 16, v132
	v_and_b32_e32 v132, 0xffff0000, v132
	v_max_f32_e32 v193, 0xda24260, v193
	v_max_f32_e32 v138, v138, v138
	v_max_f32_e32 v132, v132, v132
	v_rcp_f32_e32 v193, v193
	v_max_f32_e32 v138, 0xda24260, v138
	v_max_f32_e32 v132, 0xda24260, v132
	v_rcp_f32_e32 v138, v138
	v_rcp_f32_e32 v139, v132
	v_add_co_u32_e32 v154, vcc, s63, v184
	v_pk_mul_f32 v[140:141], v[192:193], v[140:141]
	s_nop 0
	v_addc_co_u32_e32 v155, vcc, 0, v185, vcc
	v_pk_mul_f32 v[114:115], v[114:115], v[136:137]
	v_lshlrev_b32_e32 v136, 16, v128
	v_and_b32_e32 v137, 0xffff0000, v128
	v_add_co_u32_e32 v156, vcc, s63, v182
	v_pk_mul_f32 v[120:121], v[120:121], v[140:141]
	v_pk_mul_f32 v[152:153], v[138:139], v[136:137]
	v_addc_co_u32_e32 v157, vcc, 0, v183, vcc
	flat_load_dwordx4 v[136:139], v[154:155]
	flat_load_dwordx4 v[140:143], v[156:157]
	v_lshlrev_b32_e32 v128, 16, v133
	v_max_f32_e32 v128, v128, v128
	v_max_f32_e32 v128, 0xda24260, v128
	v_rcp_f32_e32 v132, v128
	v_and_b32_e32 v128, 0xffff0000, v133
	v_max_f32_e32 v128, v128, v128
	v_max_f32_e32 v128, 0xda24260, v128
	v_rcp_f32_e32 v133, v128
	v_lshlrev_b32_e32 v128, 16, v129
	v_and_b32_e32 v129, 0xffff0000, v129
	v_pk_mul_f32 v[128:129], v[132:133], v[128:129]
	v_lshlrev_b32_e32 v132, 16, v134
	v_and_b32_e32 v133, 0xffff0000, v134
	v_max_f32_e32 v132, v132, v132
	v_max_f32_e32 v133, v133, v133
	v_max_f32_e32 v132, 0xda24260, v132
	v_max_f32_e32 v133, 0xda24260, v133
	v_rcp_f32_e32 v132, v132
	v_rcp_f32_e32 v133, v133
	v_pk_mul_f32 v[110:111], v[110:111], v[128:129]
	v_lshlrev_b32_e32 v128, 16, v130
; #define RT_(aw, pw, lo) ((lo ? bf_lo(aw) : bf_hi(aw)) * __builtin_amdgcn_rcpf(fmaxf(lo ? bf_lo(pw) : bf_hi(pw), 1e-30f)))
;     __device__ __forceinline__ void mid(f32x4 (&acc)[2][2][4][2], const Unit& u, int wr, int wc, int fr, int fq) const {
;         const int col0 = u.pn * BM + wc * 32 + 8 * fq, row0 = u.pm * BM + wr * 64 + fr;
;         unsigned long long ro_ = ((unsigned long long)row0 * 2048 + col0) * 2; asm volatile("" : "+v"(ro_));
;         const bf16_t* ga = (const bf16_t*)((const char*)GA + ro_); const bf16_t* gp = (const bf16_t*)((const char*)GP + ro_);
; #pragma unroll
;         for (int ai = 0; ai < 2; ++ai)
; #pragma unroll
;             for (int m = 0; m < 4; ++m)
; #pragma unroll
;                 for (int bj = 0; bj < 2; ++bj) { const size_t o_ = (size_t)(ai * HALF + m * 16) * 2048 + bj * HALF;
;                     const u32x4 a = *(const u32x4*)(ga + o_), p = *(const u32x4*)(gp + o_);
;     ...
;                     acc[ai][bj][m][0][0] *= RT_(a.x, p.x, 1); acc[ai][bj][m][0][1] *= RT_(a.x, p.x, 0); acc[ai][bj][m][0][2] *= RT_(a.y, p.y, 1); acc[ai][bj][m][0][3] *= RT_(a.y, p.y, 0);
;                     acc[ai][bj][m][1][0] *= RT_(a.z, p.z, 1); acc[ai][bj][m][1][1] *= RT_(a.z, p.z, 0); acc[ai][bj][m][1][2] *= RT_(a.w, p.w, 1); acc[ai][bj][m][1][3] *= RT_(a.w, p.w, 0);
;     ...
;                     asm volatile("" ::: "memory"); }
;     }
	v_and_b32_e32 v129, 0xffff0000, v130
	v_lshlrev_b32_e32 v130, 16, v135
	v_max_f32_e32 v130, v130, v130
	v_max_f32_e32 v130, 0xda24260, v130
	v_pk_mul_f32 v[128:129], v[132:133], v[128:129]
	v_rcp_f32_e32 v132, v130
	v_and_b32_e32 v130, 0xffff0000, v135
	v_max_f32_e32 v130, v130, v130
	v_max_f32_e32 v130, 0xda24260, v130
	v_rcp_f32_e32 v133, v130
	v_pk_mul_f32 v[104:105], v[104:105], v[128:129]
	v_lshlrev_b32_e32 v128, 16, v131
	v_and_b32_e32 v129, 0xffff0000, v131
	v_lshlrev_b32_e32 v130, 16, v148
	v_and_b32_e32 v131, 0xffff0000, v148
	v_max_f32_e32 v130, v130, v130
	v_max_f32_e32 v131, v131, v131
	v_max_f32_e32 v130, 0xda24260, v130
	v_max_f32_e32 v131, 0xda24260, v131
	v_rcp_f32_e32 v130, v130
	v_rcp_f32_e32 v131, v131
	v_pk_mul_f32 v[128:129], v[132:133], v[128:129]
	v_pk_mul_f32 v[108:109], v[108:109], v[152:153]
	v_pk_mul_f32 v[106:107], v[106:107], v[128:129]
	v_lshlrev_b32_e32 v128, 16, v144
	v_and_b32_e32 v129, 0xffff0000, v144
	v_pk_mul_f32 v[128:129], v[130:131], v[128:129]
	v_lshlrev_b32_e32 v130, 16, v149
	v_and_b32_e32 v131, 0xffff0000, v149
	v_max_f32_e32 v130, v130, v130
	v_max_f32_e32 v131, v131, v131
	v_max_f32_e32 v130, 0xda24260, v130
	v_max_f32_e32 v131, 0xda24260, v131
	v_rcp_f32_e32 v130, v130
	v_rcp_f32_e32 v131, v131
	v_pk_mul_f32 v[100:101], v[100:101], v[128:129]
	v_lshlrev_b32_e32 v128, 16, v145
	v_and_b32_e32 v129, 0xffff0000, v145
	v_pk_mul_f32 v[128:129], v[130:131], v[128:129]
	v_lshlrev_b32_e32 v130, 16, v150
	v_and_b32_e32 v131, 0xffff0000, v150
	v_max_f32_e32 v130, v130, v130
	v_max_f32_e32 v131, v131, v131
	v_max_f32_e32 v130, 0xda24260, v130
	v_max_f32_e32 v131, 0xda24260, v131
	v_rcp_f32_e32 v130, v130
	v_rcp_f32_e32 v131, v131
	flat_load_dwordx4 v[132:135], v[154:155] offset:256
	s_nop 0
	flat_load_dwordx4 v[152:155], v[156:157] offset:256
	v_pk_mul_f32 v[102:103], v[102:103], v[128:129]
	v_lshlrev_b32_e32 v128, 16, v146
	v_and_b32_e32 v129, 0xffff0000, v146
	v_pk_mul_f32 v[128:129], v[130:131], v[128:129]
	v_lshlrev_b32_e32 v130, 16, v151
	v_and_b32_e32 v131, 0xffff0000, v151
	v_max_f32_e32 v130, v130, v130
	v_max_f32_e32 v131, v131, v131
	v_max_f32_e32 v130, 0xda24260, v130
	v_max_f32_e32 v131, 0xda24260, v131
	v_rcp_f32_e32 v130, v130
	v_rcp_f32_e32 v131, v131
	v_pk_mul_f32 v[96:97], v[96:97], v[128:129]
	v_lshlrev_b32_e32 v128, 16, v147
	v_and_b32_e32 v129, 0xffff0000, v147
	v_pk_mul_f32 v[128:129], v[130:131], v[128:129]
	s_waitcnt vmcnt(0) lgkmcnt(0)
	v_lshlrev_b32_e32 v130, 16, v140
	v_and_b32_e32 v131, 0xffff0000, v140
	v_max_f32_e32 v130, v130, v130
	v_max_f32_e32 v131, v131, v131
	v_max_f32_e32 v130, 0xda24260, v130
	v_max_f32_e32 v131, 0xda24260, v131
	v_rcp_f32_e32 v130, v130
	v_rcp_f32_e32 v131, v131
	v_pk_mul_f32 v[98:99], v[98:99], v[128:129]
	v_lshlrev_b32_e32 v128, 16, v136
	v_and_b32_e32 v129, 0xffff0000, v136
	v_pk_mul_f32 v[148:149], v[130:131], v[128:129]
	v_lshlrev_b32_e32 v128, 16, v141
	v_max_f32_e32 v128, v128, v128
	v_max_f32_e32 v128, 0xda24260, v128
	v_rcp_f32_e32 v140, v128
	v_and_b32_e32 v128, 0xffff0000, v141
	v_add_co_u32_e32 v150, vcc, s64, v184
	v_max_f32_e32 v128, v128, v128
	s_nop 0
	v_addc_co_u32_e32 v151, vcc, 0, v185, vcc
	v_max_f32_e32 v128, 0xda24260, v128
	v_add_co_u32_e32 v156, vcc, s64, v182
	v_rcp_f32_e32 v141, v128
	s_nop 0
	v_addc_co_u32_e32 v157, vcc, 0, v183, vcc
	flat_load_dwordx4 v[128:131], v[150:151]
	flat_load_dwordx4 v[144:147], v[156:157]
	v_lshlrev_b32_e32 v136, 16, v137
	v_and_b32_e32 v137, 0xffff0000, v137
	v_pk_mul_f32 v[136:137], v[140:141], v[136:137]
	v_lshlrev_b32_e32 v140, 16, v142
	v_and_b32_e32 v141, 0xffff0000, v142
	v_max_f32_e32 v140, v140, v140
	v_max_f32_e32 v141, v141, v141
	v_max_f32_e32 v140, 0xda24260, v140
	v_max_f32_e32 v141, 0xda24260, v141
	v_rcp_f32_e32 v140, v140
	v_rcp_f32_e32 v141, v141
	v_pk_mul_f32 v[94:95], v[94:95], v[136:137]
	v_lshlrev_b32_e32 v136, 16, v138
	v_and_b32_e32 v137, 0xffff0000, v138
	v_lshlrev_b32_e32 v138, 16, v143
	v_max_f32_e32 v138, v138, v138
	v_max_f32_e32 v138, 0xda24260, v138
	v_pk_mul_f32 v[136:137], v[140:141], v[136:137]
	v_rcp_f32_e32 v140, v138
	v_and_b32_e32 v138, 0xffff0000, v143
	v_max_f32_e32 v138, v138, v138
	v_max_f32_e32 v138, 0xda24260, v138
	v_rcp_f32_e32 v141, v138
	v_pk_mul_f32 v[88:89], v[88:89], v[136:137]
	v_lshlrev_b32_e32 v136, 16, v139
	v_and_b32_e32 v137, 0xffff0000, v139
	v_pk_mul_f32 v[92:93], v[92:93], v[148:149]
	v_pk_mul_f32 v[136:137], v[140:141], v[136:137]
	flat_load_dwordx4 v[140:143], v[150:151] offset:256
	s_nop 0
	flat_load_dwordx4 v[148:151], v[156:157] offset:256
	v_pk_mul_f32 v[90:91], v[90:91], v[136:137]
	v_lshlrev_b32_e32 v136, 16, v132
	v_lshlrev_b32_e32 v138, 16, v152
	v_and_b32_e32 v139, 0xffff0000, v152
	v_max_f32_e32 v138, v138, v138
	v_max_f32_e32 v139, v139, v139
	v_max_f32_e32 v138, 0xda24260, v138
	v_max_f32_e32 v139, 0xda24260, v139
	v_rcp_f32_e32 v138, v138
	v_rcp_f32_e32 v139, v139
	v_and_b32_e32 v137, 0xffff0000, v132
	v_lshlrev_b32_e32 v132, 16, v153
	v_max_f32_e32 v132, v132, v132
	v_max_f32_e32 v132, 0xda24260, v132
	v_pk_mul_f32 v[136:137], v[138:139], v[136:137]
	v_rcp_f32_e32 v138, v132
	v_and_b32_e32 v132, 0xffff0000, v153
	v_max_f32_e32 v132, v132, v132
	v_max_f32_e32 v132, 0xda24260, v132
	v_rcp_f32_e32 v139, v132
	v_pk_mul_f32 v[84:85], v[84:85], v[136:137]
	v_lshlrev_b32_e32 v136, 16, v154
	v_and_b32_e32 v137, 0xffff0000, v154
	v_max_f32_e32 v136, v136, v136
	v_max_f32_e32 v137, v137, v137
	v_lshlrev_b32_e32 v132, 16, v133
	v_and_b32_e32 v133, 0xffff0000, v133
	v_max_f32_e32 v136, 0xda24260, v136
	v_max_f32_e32 v137, 0xda24260, v137
	v_pk_mul_f32 v[132:133], v[138:139], v[132:133]
	v_rcp_f32_e32 v136, v136
	v_rcp_f32_e32 v137, v137
	v_pk_mul_f32 v[86:87], v[86:87], v[132:133]
	v_lshlrev_b32_e32 v132, 16, v134
	v_and_b32_e32 v133, 0xffff0000, v134
	v_lshlrev_b32_e32 v134, 16, v155
	v_max_f32_e32 v134, v134, v134
	v_max_f32_e32 v134, 0xda24260, v134
	v_pk_mul_f32 v[132:133], v[136:137], v[132:133]
	v_rcp_f32_e32 v136, v134
	v_and_b32_e32 v134, 0xffff0000, v155
	v_max_f32_e32 v134, v134, v134
	v_max_f32_e32 v134, 0xda24260, v134
	v_rcp_f32_e32 v137, v134
	v_pk_mul_f32 v[80:81], v[80:81], v[132:133]
	v_lshlrev_b32_e32 v132, 16, v135
	v_and_b32_e32 v133, 0xffff0000, v135
	v_add_co_u32_e32 v154, vcc, s65, v184
	s_waitcnt vmcnt(0) lgkmcnt(0)
; #define RT_(aw, pw, lo) ((lo ? bf_lo(aw) : bf_hi(aw)) * __builtin_amdgcn_rcpf(fmaxf(lo ? bf_lo(pw) : bf_hi(pw), 1e-30f)))
;     __device__ __forceinline__ void mid(f32x4 (&acc)[2][2][4][2], const Unit& u, int wr, int wc, int fr, int fq) const {
;         const int col0 = u.pn * BM + wc * 32 + 8 * fq, row0 = u.pm * BM + wr * 64 + fr;
;         unsigned long long ro_ = ((unsigned long long)row0 * 2048 + col0) * 2; asm volatile("" : "+v"(ro_));
;         const bf16_t* ga = (const bf16_t*)((const char*)GA + ro_); const bf16_t* gp = (const bf16_t*)((const char*)GP + ro_);
; #pragma unroll
;         for (int ai = 0; ai < 2; ++ai)
; #pragma unroll
;             for (int m = 0; m < 4; ++m)
; #pragma unroll
;                 for (int bj = 0; bj < 2; ++bj) { const size_t o_ = (size_t)(ai * HALF + m * 16) * 2048 + bj * HALF;
;                     const u32x4 a = *(const u32x4*)(ga + o_), p = *(const u32x4*)(gp + o_);
;     ...
;                     acc[ai][bj][m][0][0] *= RT_(a.x, p.x, 1); acc[ai][bj][m][0][1] *= RT_(a.x, p.x, 0); acc[ai][bj][m][0][2] *= RT_(a.y, p.y, 1); acc[ai][bj][m][0][3] *= RT_(a.y, p.y, 0);
;                     acc[ai][bj][m][1][0] *= RT_(a.z, p.z, 1); acc[ai][bj][m][1][1] *= RT_(a.z, p.z, 0); acc[ai][bj][m][1][2] *= RT_(a.w, p.w, 1); acc[ai][bj][m][1][3] *= RT_(a.w, p.w, 0);
;     ...
;                     asm volatile("" ::: "memory"); }
;     }
	v_lshlrev_b32_e32 v134, 16, v144
	v_and_b32_e32 v135, 0xffff0000, v144
	v_max_f32_e32 v134, v134, v134
	v_max_f32_e32 v135, v135, v135
	v_max_f32_e32 v134, 0xda24260, v134
	v_max_f32_e32 v135, 0xda24260, v135
	v_rcp_f32_e32 v134, v134
	v_rcp_f32_e32 v135, v135
	v_pk_mul_f32 v[132:133], v[136:137], v[132:133]
	v_addc_co_u32_e32 v155, vcc, 0, v185, vcc
	v_pk_mul_f32 v[82:83], v[82:83], v[132:133]
	v_lshlrev_b32_e32 v132, 16, v128
	v_and_b32_e32 v133, 0xffff0000, v128
	v_add_co_u32_e32 v156, vcc, s65, v182
	v_pk_mul_f32 v[152:153], v[134:135], v[132:133]
	s_nop 0
	v_addc_co_u32_e32 v157, vcc, 0, v183, vcc
	flat_load_dwordx4 v[132:135], v[154:155]
	flat_load_dwordx4 v[136:139], v[156:157]
	v_lshlrev_b32_e32 v128, 16, v145
	v_max_f32_e32 v128, v128, v128
	v_max_f32_e32 v128, 0xda24260, v128
	v_rcp_f32_e32 v144, v128
	v_and_b32_e32 v128, 0xffff0000, v145
	v_max_f32_e32 v128, v128, v128
	v_max_f32_e32 v128, 0xda24260, v128
	v_rcp_f32_e32 v145, v128
	v_lshlrev_b32_e32 v128, 16, v129
	v_and_b32_e32 v129, 0xffff0000, v129
	v_pk_mul_f32 v[128:129], v[144:145], v[128:129]
	v_lshlrev_b32_e32 v144, 16, v146
	v_and_b32_e32 v145, 0xffff0000, v146
	v_max_f32_e32 v144, v144, v144
	v_max_f32_e32 v145, v145, v145
	v_max_f32_e32 v144, 0xda24260, v144
	v_max_f32_e32 v145, 0xda24260, v145
	v_rcp_f32_e32 v144, v144
	v_rcp_f32_e32 v145, v145
	v_pk_mul_f32 v[78:79], v[78:79], v[128:129]
	v_lshlrev_b32_e32 v128, 16, v130
	v_and_b32_e32 v129, 0xffff0000, v130
	v_lshlrev_b32_e32 v130, 16, v147
	v_max_f32_e32 v130, v130, v130
	v_max_f32_e32 v130, 0xda24260, v130
	v_pk_mul_f32 v[128:129], v[144:145], v[128:129]
	v_rcp_f32_e32 v144, v130
	v_and_b32_e32 v130, 0xffff0000, v147
	v_max_f32_e32 v130, v130, v130
	v_max_f32_e32 v130, 0xda24260, v130
	v_rcp_f32_e32 v145, v130
	v_pk_mul_f32 v[72:73], v[72:73], v[128:129]
	v_lshlrev_b32_e32 v128, 16, v131
	v_and_b32_e32 v129, 0xffff0000, v131
	v_lshlrev_b32_e32 v130, 16, v148
	v_and_b32_e32 v131, 0xffff0000, v148
	v_max_f32_e32 v130, v130, v130
	v_max_f32_e32 v131, v131, v131
	v_max_f32_e32 v130, 0xda24260, v130
	v_max_f32_e32 v131, 0xda24260, v131
	v_rcp_f32_e32 v130, v130
	v_rcp_f32_e32 v131, v131
	v_pk_mul_f32 v[128:129], v[144:145], v[128:129]
	v_pk_mul_f32 v[76:77], v[76:77], v[152:153]
	v_pk_mul_f32 v[74:75], v[74:75], v[128:129]
	v_lshlrev_b32_e32 v128, 16, v140
	v_and_b32_e32 v129, 0xffff0000, v140
	v_pk_mul_f32 v[128:129], v[130:131], v[128:129]
	v_lshlrev_b32_e32 v130, 16, v149
	v_and_b32_e32 v131, 0xffff0000, v149
	v_max_f32_e32 v130, v130, v130
	v_max_f32_e32 v131, v131, v131
	v_max_f32_e32 v130, 0xda24260, v130
	v_max_f32_e32 v131, 0xda24260, v131
	v_rcp_f32_e32 v130, v130
	v_rcp_f32_e32 v131, v131
	flat_load_dwordx4 v[144:147], v[154:155] offset:256
	s_nop 0
	flat_load_dwordx4 v[152:155], v[156:157] offset:256
	v_pk_mul_f32 v[68:69], v[68:69], v[128:129]
	v_lshlrev_b32_e32 v128, 16, v141
	v_and_b32_e32 v129, 0xffff0000, v141
	v_pk_mul_f32 v[128:129], v[130:131], v[128:129]
	v_lshlrev_b32_e32 v130, 16, v150
	v_and_b32_e32 v131, 0xffff0000, v150
	v_max_f32_e32 v130, v130, v130
	v_max_f32_e32 v131, v131, v131
	v_max_f32_e32 v130, 0xda24260, v130
	v_max_f32_e32 v131, 0xda24260, v131
	v_rcp_f32_e32 v130, v130
	v_rcp_f32_e32 v131, v131
	v_pk_mul_f32 v[70:71], v[70:71], v[128:129]
	v_lshlrev_b32_e32 v128, 16, v142
	v_and_b32_e32 v129, 0xffff0000, v142
	v_pk_mul_f32 v[128:129], v[130:131], v[128:129]
	v_lshlrev_b32_e32 v130, 16, v151
	v_and_b32_e32 v131, 0xffff0000, v151
	v_max_f32_e32 v130, v130, v130
	v_max_f32_e32 v131, v131, v131
	v_max_f32_e32 v130, 0xda24260, v130
	v_max_f32_e32 v131, 0xda24260, v131
	v_rcp_f32_e32 v130, v130
	v_rcp_f32_e32 v131, v131
	v_pk_mul_f32 v[64:65], v[64:65], v[128:129]
	v_lshlrev_b32_e32 v128, 16, v143
	v_and_b32_e32 v129, 0xffff0000, v143
	v_pk_mul_f32 v[128:129], v[130:131], v[128:129]
	s_waitcnt vmcnt(0) lgkmcnt(0)
	v_lshlrev_b32_e32 v130, 16, v136
	v_and_b32_e32 v131, 0xffff0000, v136
	v_max_f32_e32 v130, v130, v130
	v_max_f32_e32 v131, v131, v131
	v_max_f32_e32 v130, 0xda24260, v130
	v_max_f32_e32 v131, 0xda24260, v131
	v_rcp_f32_e32 v130, v130
	v_rcp_f32_e32 v131, v131
	v_pk_mul_f32 v[66:67], v[66:67], v[128:129]
	v_lshlrev_b32_e32 v128, 16, v132
	v_and_b32_e32 v129, 0xffff0000, v132
	v_pk_mul_f32 v[148:149], v[130:131], v[128:129]
	v_lshlrev_b32_e32 v128, 16, v137
	v_max_f32_e32 v128, v128, v128
	v_max_f32_e32 v128, 0xda24260, v128
	v_rcp_f32_e32 v136, v128
	v_and_b32_e32 v128, 0xffff0000, v137
	v_add_co_u32_e32 v150, vcc, s66, v184
	v_max_f32_e32 v128, v128, v128
	s_nop 0
	v_addc_co_u32_e32 v151, vcc, 0, v185, vcc
	v_max_f32_e32 v128, 0xda24260, v128
	v_add_co_u32_e32 v156, vcc, s66, v182
	v_rcp_f32_e32 v137, v128
	s_nop 0
	v_addc_co_u32_e32 v157, vcc, 0, v183, vcc
	flat_load_dwordx4 v[128:131], v[150:151]
	flat_load_dwordx4 v[140:143], v[156:157]
	v_pk_mul_f32 v[60:61], v[60:61], v[148:149]
	flat_load_dwordx4 v[148:151], v[150:151] offset:256
	s_nop 0
	flat_load_dwordx4 v[156:159], v[156:157] offset:256
	v_lshlrev_b32_e32 v132, 16, v133
	v_and_b32_e32 v133, 0xffff0000, v133
	v_pk_mul_f32 v[132:133], v[136:137], v[132:133]
	v_lshlrev_b32_e32 v136, 16, v138
	v_and_b32_e32 v137, 0xffff0000, v138
	v_max_f32_e32 v136, v136, v136
	v_max_f32_e32 v137, v137, v137
	v_max_f32_e32 v136, 0xda24260, v136
	v_max_f32_e32 v137, 0xda24260, v137
	v_rcp_f32_e32 v136, v136
	v_rcp_f32_e32 v137, v137
	v_pk_mul_f32 v[62:63], v[62:63], v[132:133]
	v_lshlrev_b32_e32 v132, 16, v134
	v_and_b32_e32 v133, 0xffff0000, v134
	v_lshlrev_b32_e32 v134, 16, v139
	v_max_f32_e32 v134, v134, v134
	v_max_f32_e32 v134, 0xda24260, v134
	v_pk_mul_f32 v[132:133], v[136:137], v[132:133]
	v_rcp_f32_e32 v136, v134
; #define RT_(aw, pw, lo) ((lo ? bf_lo(aw) : bf_hi(aw)) * __builtin_amdgcn_rcpf(fmaxf(lo ? bf_lo(pw) : bf_hi(pw), 1e-30f)))
;     __device__ __forceinline__ void mid(f32x4 (&acc)[2][2][4][2], const Unit& u, int wr, int wc, int fr, int fq) const {
;         const int col0 = u.pn * BM + wc * 32 + 8 * fq, row0 = u.pm * BM + wr * 64 + fr;
;         unsigned long long ro_ = ((unsigned long long)row0 * 2048 + col0) * 2; asm volatile("" : "+v"(ro_));
;         const bf16_t* ga = (const bf16_t*)((const char*)GA + ro_); const bf16_t* gp = (const bf16_t*)((const char*)GP + ro_);
; #pragma unroll
;         for (int ai = 0; ai < 2; ++ai)
; #pragma unroll
;             for (int m = 0; m < 4; ++m)
; #pragma unroll
;                 for (int bj = 0; bj < 2; ++bj) { const size_t o_ = (size_t)(ai * HALF + m * 16) * 2048 + bj * HALF;
;                     const u32x4 a = *(const u32x4*)(ga + o_), p = *(const u32x4*)(gp + o_);
;     ...
;                     acc[ai][bj][m][0][0] *= RT_(a.x, p.x, 1); acc[ai][bj][m][0][1] *= RT_(a.x, p.x, 0); acc[ai][bj][m][0][2] *= RT_(a.y, p.y, 1); acc[ai][bj][m][0][3] *= RT_(a.y, p.y, 0);
;                     acc[ai][bj][m][1][0] *= RT_(a.z, p.z, 1); acc[ai][bj][m][1][1] *= RT_(a.z, p.z, 0); acc[ai][bj][m][1][2] *= RT_(a.w, p.w, 1); acc[ai][bj][m][1][3] *= RT_(a.w, p.w, 0);
;     ...
;                     asm volatile("" ::: "memory"); }
;     }
	v_and_b32_e32 v134, 0xffff0000, v139
	v_max_f32_e32 v134, v134, v134
	v_max_f32_e32 v134, 0xda24260, v134
	v_rcp_f32_e32 v137, v134
	v_pk_mul_f32 v[56:57], v[56:57], v[132:133]
	v_lshlrev_b32_e32 v132, 16, v135
	v_and_b32_e32 v133, 0xffff0000, v135
	v_lshlrev_b32_e32 v134, 16, v152
	v_and_b32_e32 v135, 0xffff0000, v152
	v_max_f32_e32 v134, v134, v134
	v_max_f32_e32 v135, v135, v135
	v_max_f32_e32 v134, 0xda24260, v134
	v_max_f32_e32 v135, 0xda24260, v135
	v_rcp_f32_e32 v134, v134
	v_rcp_f32_e32 v135, v135
	v_pk_mul_f32 v[132:133], v[136:137], v[132:133]
	s_nop 0
	v_pk_mul_f32 v[58:59], v[58:59], v[132:133]
	v_lshlrev_b32_e32 v132, 16, v144
	v_and_b32_e32 v133, 0xffff0000, v144
	v_pk_mul_f32 v[132:133], v[134:135], v[132:133]
	v_lshlrev_b32_e32 v134, 16, v153
	v_and_b32_e32 v135, 0xffff0000, v153
	v_max_f32_e32 v134, v134, v134
	v_max_f32_e32 v135, v135, v135
	v_max_f32_e32 v134, 0xda24260, v134
	v_max_f32_e32 v135, 0xda24260, v135
	v_rcp_f32_e32 v134, v134
	v_rcp_f32_e32 v135, v135
	v_pk_mul_f32 v[52:53], v[52:53], v[132:133]
	v_lshlrev_b32_e32 v132, 16, v145
	v_and_b32_e32 v133, 0xffff0000, v145
	v_pk_mul_f32 v[132:133], v[134:135], v[132:133]
	v_lshlrev_b32_e32 v134, 16, v154
	v_and_b32_e32 v135, 0xffff0000, v154
	v_max_f32_e32 v134, v134, v134
	v_max_f32_e32 v135, v135, v135
	v_max_f32_e32 v134, 0xda24260, v134
	v_max_f32_e32 v135, 0xda24260, v135
	v_rcp_f32_e32 v134, v134
	v_rcp_f32_e32 v135, v135
	v_pk_mul_f32 v[54:55], v[54:55], v[132:133]
	v_lshlrev_b32_e32 v132, 16, v146
	v_and_b32_e32 v133, 0xffff0000, v146
	v_pk_mul_f32 v[132:133], v[134:135], v[132:133]
	v_lshlrev_b32_e32 v134, 16, v155
	v_and_b32_e32 v135, 0xffff0000, v155
	v_max_f32_e32 v134, v134, v134
	v_max_f32_e32 v135, v135, v135
	v_max_f32_e32 v134, 0xda24260, v134
	v_max_f32_e32 v135, 0xda24260, v135
	v_rcp_f32_e32 v134, v134
	v_rcp_f32_e32 v135, v135
	v_pk_mul_f32 v[48:49], v[48:49], v[132:133]
	v_lshlrev_b32_e32 v132, 16, v147
	v_and_b32_e32 v133, 0xffff0000, v147
	v_pk_mul_f32 v[132:133], v[134:135], v[132:133]
	s_waitcnt vmcnt(0) lgkmcnt(0)
	v_lshlrev_b32_e32 v134, 16, v140
	v_pk_mul_f32 v[50:51], v[50:51], v[132:133]
	v_lshlrev_b32_e32 v132, 16, v128
	v_and_b32_e32 v133, 0xffff0000, v128
	v_lshlrev_b32_e32 v128, 16, v141
	v_max_f32_e32 v128, v128, v128
	v_and_b32_e32 v135, 0xffff0000, v140
	v_max_f32_e32 v128, 0xda24260, v128
	v_max_f32_e32 v134, v134, v134
	v_max_f32_e32 v135, v135, v135
	v_rcp_f32_e32 v140, v128
	v_and_b32_e32 v128, 0xffff0000, v141
	v_max_f32_e32 v134, 0xda24260, v134
	v_max_f32_e32 v135, 0xda24260, v135
	v_max_f32_e32 v128, v128, v128
	v_rcp_f32_e32 v134, v134
	v_rcp_f32_e32 v135, v135
	v_max_f32_e32 v128, 0xda24260, v128
	v_rcp_f32_e32 v141, v128
	v_add_co_u32_e32 v146, vcc, s67, v184
	v_pk_mul_f32 v[144:145], v[134:135], v[132:133]
	s_nop 0
	v_addc_co_u32_e32 v147, vcc, 0, v185, vcc
	v_add_co_u32_e32 v152, vcc, s67, v182
	v_lshlrev_b32_e32 v128, 16, v129
	s_nop 0
	v_addc_co_u32_e32 v153, vcc, 0, v183, vcc
	flat_load_dwordx4 v[132:135], v[146:147]
	flat_load_dwordx4 v[136:139], v[152:153]
	v_and_b32_e32 v129, 0xffff0000, v129
	v_pk_mul_f32 v[128:129], v[140:141], v[128:129]
	v_lshlrev_b32_e32 v140, 16, v142
	v_and_b32_e32 v141, 0xffff0000, v142
	v_max_f32_e32 v140, v140, v140
	v_max_f32_e32 v141, v141, v141
	v_max_f32_e32 v140, 0xda24260, v140
	v_max_f32_e32 v141, 0xda24260, v141
	v_rcp_f32_e32 v140, v140
	v_rcp_f32_e32 v141, v141
	v_pk_mul_f32 v[46:47], v[46:47], v[128:129]
	v_lshlrev_b32_e32 v128, 16, v130
	v_and_b32_e32 v129, 0xffff0000, v130
	v_lshlrev_b32_e32 v130, 16, v143
	v_max_f32_e32 v130, v130, v130
	v_max_f32_e32 v130, 0xda24260, v130
	v_pk_mul_f32 v[128:129], v[140:141], v[128:129]
	v_rcp_f32_e32 v140, v130
	v_and_b32_e32 v130, 0xffff0000, v143
	v_max_f32_e32 v130, v130, v130
	v_max_f32_e32 v130, 0xda24260, v130
	v_rcp_f32_e32 v141, v130
	v_pk_mul_f32 v[40:41], v[40:41], v[128:129]
	v_lshlrev_b32_e32 v128, 16, v131
	v_and_b32_e32 v129, 0xffff0000, v131
	v_lshlrev_b32_e32 v130, 16, v156
	v_and_b32_e32 v131, 0xffff0000, v156
	v_max_f32_e32 v130, v130, v130
	v_max_f32_e32 v131, v131, v131
	v_max_f32_e32 v130, 0xda24260, v130
	v_max_f32_e32 v131, 0xda24260, v131
	v_rcp_f32_e32 v130, v130
	v_rcp_f32_e32 v131, v131
	v_pk_mul_f32 v[128:129], v[140:141], v[128:129]
	v_pk_mul_f32 v[44:45], v[44:45], v[144:145]
	v_pk_mul_f32 v[42:43], v[42:43], v[128:129]
	v_lshlrev_b32_e32 v128, 16, v148
	v_and_b32_e32 v129, 0xffff0000, v148
	v_pk_mul_f32 v[128:129], v[130:131], v[128:129]
	v_lshlrev_b32_e32 v130, 16, v157
	v_and_b32_e32 v131, 0xffff0000, v157
	v_max_f32_e32 v130, v130, v130
	v_max_f32_e32 v131, v131, v131
	v_max_f32_e32 v130, 0xda24260, v130
	v_max_f32_e32 v131, 0xda24260, v131
	v_rcp_f32_e32 v130, v130
	v_rcp_f32_e32 v131, v131
	v_pk_mul_f32 v[36:37], v[36:37], v[128:129]
	v_lshlrev_b32_e32 v128, 16, v149
	v_and_b32_e32 v129, 0xffff0000, v149
	v_pk_mul_f32 v[144:145], v[130:131], v[128:129]
	v_lshlrev_b32_e32 v128, 16, v158
	v_max_f32_e32 v128, v128, v128
	v_max_f32_e32 v128, 0xda24260, v128
	v_rcp_f32_e32 v148, v128
	flat_load_dwordx4 v[128:131], v[146:147] offset:256
	flat_load_dwordx4 v[140:143], v[152:153] offset:256
	v_and_b32_e32 v146, 0xffff0000, v158
	v_max_f32_e32 v146, v146, v146
	v_max_f32_e32 v146, 0xda24260, v146
	v_rcp_f32_e32 v149, v146
	v_lshlrev_b32_e32 v146, 16, v159
	v_and_b32_e32 v147, 0xffff0000, v159
	v_max_f32_e32 v146, v146, v146
	v_max_f32_e32 v147, v147, v147
	v_max_f32_e32 v146, 0xda24260, v146
	v_max_f32_e32 v147, 0xda24260, v147
	v_rcp_f32_e32 v146, v146
	v_rcp_f32_e32 v147, v147
	v_pk_mul_f32 v[38:39], v[38:39], v[144:145]
	v_lshlrev_b32_e32 v144, 16, v150
	v_and_b32_e32 v145, 0xffff0000, v150
	v_pk_mul_f32 v[144:145], v[148:149], v[144:145]
	v_add_co_u32_e32 v154, vcc, s68, v184
	v_pk_mul_f32 v[32:33], v[32:33], v[144:145]
	v_lshlrev_b32_e32 v144, 16, v151
	v_and_b32_e32 v145, 0xffff0000, v151
	v_pk_mul_f32 v[144:145], v[146:147], v[144:145]
	s_waitcnt vmcnt(0) lgkmcnt(0)
; #define RT_(aw, pw, lo) ((lo ? bf_lo(aw) : bf_hi(aw)) * __builtin_amdgcn_rcpf(fmaxf(lo ? bf_lo(pw) : bf_hi(pw), 1e-30f)))
;     __device__ __forceinline__ void mid(f32x4 (&acc)[2][2][4][2], const Unit& u, int wr, int wc, int fr, int fq) const {
;         const int col0 = u.pn * BM + wc * 32 + 8 * fq, row0 = u.pm * BM + wr * 64 + fr;
;         unsigned long long ro_ = ((unsigned long long)row0 * 2048 + col0) * 2; asm volatile("" : "+v"(ro_));
;         const bf16_t* ga = (const bf16_t*)((const char*)GA + ro_); const bf16_t* gp = (const bf16_t*)((const char*)GP + ro_);
; #pragma unroll
;         for (int ai = 0; ai < 2; ++ai)
; #pragma unroll
;             for (int m = 0; m < 4; ++m)
; #pragma unroll
;                 for (int bj = 0; bj < 2; ++bj) { const size_t o_ = (size_t)(ai * HALF + m * 16) * 2048 + bj * HALF;
;                     const u32x4 a = *(const u32x4*)(ga + o_), p = *(const u32x4*)(gp + o_);
;     ...
;                     acc[ai][bj][m][0][0] *= RT_(a.x, p.x, 1); acc[ai][bj][m][0][1] *= RT_(a.x, p.x, 0); acc[ai][bj][m][0][2] *= RT_(a.y, p.y, 1); acc[ai][bj][m][0][3] *= RT_(a.y, p.y, 0);
;                     acc[ai][bj][m][1][0] *= RT_(a.z, p.z, 1); acc[ai][bj][m][1][1] *= RT_(a.z, p.z, 0); acc[ai][bj][m][1][2] *= RT_(a.w, p.w, 1); acc[ai][bj][m][1][3] *= RT_(a.w, p.w, 0);
;     ...
;                     asm volatile("" ::: "memory"); }
;     }
	v_lshlrev_b32_e32 v146, 16, v136
	v_and_b32_e32 v136, 0xffff0000, v136
	v_max_f32_e32 v146, v146, v146
	v_max_f32_e32 v136, v136, v136
	v_max_f32_e32 v146, 0xda24260, v146
	v_max_f32_e32 v136, 0xda24260, v136
	v_rcp_f32_e32 v146, v146
	v_rcp_f32_e32 v147, v136
	v_addc_co_u32_e32 v155, vcc, 0, v185, vcc
	v_pk_mul_f32 v[34:35], v[34:35], v[144:145]
	v_lshlrev_b32_e32 v144, 16, v132
	v_and_b32_e32 v145, 0xffff0000, v132
	v_add_co_u32_e32 v156, vcc, s68, v182
	v_pk_mul_f32 v[152:153], v[146:147], v[144:145]
	s_nop 0
	v_addc_co_u32_e32 v157, vcc, 0, v183, vcc
	flat_load_dwordx4 v[144:147], v[154:155]
	flat_load_dwordx4 v[148:151], v[156:157]
	v_lshlrev_b32_e32 v132, 16, v137
	v_max_f32_e32 v132, v132, v132
	v_max_f32_e32 v132, 0xda24260, v132
	v_rcp_f32_e32 v136, v132
	v_and_b32_e32 v132, 0xffff0000, v137
	v_max_f32_e32 v132, v132, v132
	v_max_f32_e32 v132, 0xda24260, v132
	v_rcp_f32_e32 v137, v132
	v_lshlrev_b32_e32 v132, 16, v133
	v_and_b32_e32 v133, 0xffff0000, v133
	v_pk_mul_f32 v[132:133], v[136:137], v[132:133]
	v_lshlrev_b32_e32 v136, 16, v138
	v_and_b32_e32 v137, 0xffff0000, v138
	v_max_f32_e32 v136, v136, v136
	v_max_f32_e32 v137, v137, v137
	v_max_f32_e32 v136, 0xda24260, v136
	v_max_f32_e32 v137, 0xda24260, v137
	v_rcp_f32_e32 v136, v136
	v_rcp_f32_e32 v137, v137
	v_pk_mul_f32 v[30:31], v[30:31], v[132:133]
	v_lshlrev_b32_e32 v132, 16, v134
	v_and_b32_e32 v133, 0xffff0000, v134
	v_lshlrev_b32_e32 v134, 16, v139
	v_max_f32_e32 v134, v134, v134
	v_max_f32_e32 v134, 0xda24260, v134
	v_pk_mul_f32 v[132:133], v[136:137], v[132:133]
	v_rcp_f32_e32 v136, v134
	v_and_b32_e32 v134, 0xffff0000, v139
	v_max_f32_e32 v134, v134, v134
	v_max_f32_e32 v134, 0xda24260, v134
	v_rcp_f32_e32 v137, v134
	v_pk_mul_f32 v[24:25], v[24:25], v[132:133]
	v_lshlrev_b32_e32 v132, 16, v135
	v_and_b32_e32 v133, 0xffff0000, v135
	v_pk_mul_f32 v[132:133], v[136:137], v[132:133]
	v_pk_mul_f32 v[28:29], v[28:29], v[152:153]
	v_lshlrev_b32_e32 v134, 16, v140
	v_and_b32_e32 v135, 0xffff0000, v140
	v_max_f32_e32 v134, v134, v134
	v_max_f32_e32 v135, v135, v135
	v_max_f32_e32 v134, 0xda24260, v134
	v_max_f32_e32 v135, 0xda24260, v135
	v_rcp_f32_e32 v134, v134
	v_rcp_f32_e32 v135, v135
	v_pk_mul_f32 v[26:27], v[26:27], v[132:133]
	v_lshlrev_b32_e32 v132, 16, v128
	v_and_b32_e32 v133, 0xffff0000, v128
	v_pk_mul_f32 v[152:153], v[134:135], v[132:133]
	flat_load_dwordx4 v[132:135], v[154:155] offset:256
	flat_load_dwordx4 v[136:139], v[156:157] offset:256
	v_lshlrev_b32_e32 v128, 16, v141
	v_max_f32_e32 v128, v128, v128
	v_max_f32_e32 v128, 0xda24260, v128
	v_rcp_f32_e32 v140, v128
	v_and_b32_e32 v128, 0xffff0000, v141
	v_max_f32_e32 v128, v128, v128
	v_max_f32_e32 v128, 0xda24260, v128
	v_rcp_f32_e32 v141, v128
	v_lshlrev_b32_e32 v128, 16, v129
	v_and_b32_e32 v129, 0xffff0000, v129
	v_pk_mul_f32 v[128:129], v[140:141], v[128:129]
	v_lshlrev_b32_e32 v140, 16, v142
	v_and_b32_e32 v141, 0xffff0000, v142
	v_max_f32_e32 v140, v140, v140
	v_max_f32_e32 v141, v141, v141
	v_max_f32_e32 v140, 0xda24260, v140
	v_max_f32_e32 v141, 0xda24260, v141
	v_rcp_f32_e32 v140, v140
	v_rcp_f32_e32 v141, v141
	v_pk_mul_f32 v[22:23], v[22:23], v[128:129]
	v_lshlrev_b32_e32 v128, 16, v130
	v_and_b32_e32 v129, 0xffff0000, v130
	v_lshlrev_b32_e32 v130, 16, v143
	v_max_f32_e32 v130, v130, v130
	v_max_f32_e32 v130, 0xda24260, v130
	v_pk_mul_f32 v[128:129], v[140:141], v[128:129]
	v_rcp_f32_e32 v140, v130
	v_and_b32_e32 v130, 0xffff0000, v143
	v_max_f32_e32 v130, v130, v130
	v_max_f32_e32 v130, 0xda24260, v130
	v_rcp_f32_e32 v141, v130
	v_pk_mul_f32 v[16:17], v[16:17], v[128:129]
	v_lshlrev_b32_e32 v128, 16, v131
	v_and_b32_e32 v129, 0xffff0000, v131
	s_waitcnt vmcnt(0) lgkmcnt(0)
	v_lshlrev_b32_e32 v130, 16, v148
	v_and_b32_e32 v131, 0xffff0000, v148
	v_max_f32_e32 v130, v130, v130
	v_max_f32_e32 v131, v131, v131
	v_max_f32_e32 v130, 0xda24260, v130
	v_max_f32_e32 v131, 0xda24260, v131
	v_rcp_f32_e32 v130, v130
	v_rcp_f32_e32 v131, v131
	v_pk_mul_f32 v[128:129], v[140:141], v[128:129]
	s_waitcnt vmcnt(0)
	v_pk_mul_f32 v[20:21], v[20:21], v[152:153]
	v_pk_mul_f32 v[18:19], v[18:19], v[128:129]
	v_lshlrev_b32_e32 v128, 16, v144
	v_and_b32_e32 v129, 0xffff0000, v144
	v_pk_mul_f32 v[128:129], v[130:131], v[128:129]
	v_lshlrev_b32_e32 v130, 16, v149
	v_and_b32_e32 v131, 0xffff0000, v149
	v_max_f32_e32 v130, v130, v130
	v_max_f32_e32 v131, v131, v131
	v_max_f32_e32 v130, 0xda24260, v130
	v_max_f32_e32 v131, 0xda24260, v131
	v_rcp_f32_e32 v130, v130
	v_rcp_f32_e32 v131, v131
	v_pk_mul_f32 v[12:13], v[12:13], v[128:129]
	v_lshlrev_b32_e32 v128, 16, v145
	v_and_b32_e32 v129, 0xffff0000, v145
	v_pk_mul_f32 v[128:129], v[130:131], v[128:129]
	v_lshlrev_b32_e32 v130, 16, v150
	v_and_b32_e32 v131, 0xffff0000, v150
	v_max_f32_e32 v130, v130, v130
	v_max_f32_e32 v131, v131, v131
	v_max_f32_e32 v130, 0xda24260, v130
	v_max_f32_e32 v131, 0xda24260, v131
	v_rcp_f32_e32 v130, v130
	v_rcp_f32_e32 v131, v131
	v_pk_mul_f32 v[14:15], v[14:15], v[128:129]
	v_lshlrev_b32_e32 v128, 16, v146
	v_and_b32_e32 v129, 0xffff0000, v146
	v_pk_mul_f32 v[128:129], v[130:131], v[128:129]
	v_lshlrev_b32_e32 v130, 16, v151
	v_and_b32_e32 v131, 0xffff0000, v151
	v_max_f32_e32 v130, v130, v130
	v_max_f32_e32 v131, v131, v131
	v_max_f32_e32 v130, 0xda24260, v130
	v_max_f32_e32 v131, 0xda24260, v131
	v_rcp_f32_e32 v130, v130
	v_rcp_f32_e32 v131, v131
	v_pk_mul_f32 v[8:9], v[8:9], v[128:129]
	v_lshlrev_b32_e32 v128, 16, v147
	v_and_b32_e32 v129, 0xffff0000, v147
	v_pk_mul_f32 v[128:129], v[130:131], v[128:129]
	v_lshlrev_b32_e32 v130, 16, v136
	v_and_b32_e32 v131, 0xffff0000, v136
	v_max_f32_e32 v130, v130, v130
	v_max_f32_e32 v131, v131, v131
; #define RT_(aw, pw, lo) ((lo ? bf_lo(aw) : bf_hi(aw)) * __builtin_amdgcn_rcpf(fmaxf(lo ? bf_lo(pw) : bf_hi(pw), 1e-30f)))
; #define PG8_STAGE(bufoff, gbase, voff) do { _Pragma("unroll") for (int _i = 0; _i < 2; ++_i) \
;         __builtin_amdgcn_global_load_lds((const unsigned*)((const char*)(gbase) + (voff)[_i]), (PG8_LAS unsigned*)(lds + (bufoff) + ldsw + _i * 8192), 16, 0, 0); } while (0)
; #define PG8_LDA(dst, b, h) do { _Pragma("unroll") for (int m = 0; m < 4; ++m) _Pragma("unroll") for (int k = 0; k < 2; ++k) dst[m][k] = *(const PG8_LAS bf16x8*)(lds + PG8_SA(b, h) + aoff + m * 2048 + k * 1024); } while (0)
; #define PG8_LDB(dst, b, h) do { _Pragma("unroll") for (int n = 0; n < 2; ++n) _Pragma("unroll") for (int k = 0; k < 2; ++k) dst[n][k] = *(const PG8_LAS bf16x8*)(lds + PG8_SB(b, h) + boff + n * 2048 + k * 1024); } while (0)
; #define PG8_WAIT_V(n) asm volatile("s_waitcnt vmcnt(" #n ")" ::: "memory")
; #define PG8_WAIT_L(n) asm volatile("s_waitcnt lgkmcnt(" #n ")" ::: "memory")
; #define PG8_BAR __builtin_amdgcn_s_barrier()
; #define PG8_SCHED __builtin_amdgcn_sched_barrier(0)
;     __device__ __forceinline__ void mid(f32x4 (&acc)[2][2][4][2], const Unit& u, int wr, int wc, int fr, int fq) const {
;     ...
;                 for (int bj = 0; bj < 2; ++bj) { const size_t o_ = (size_t)(ai * HALF + m * 16) * 2048 + bj * HALF;
;                     const u32x4 a = *(const u32x4*)(ga + o_), p = *(const u32x4*)(gp + o_);
;     ...
;                     acc[ai][bj][m][0][0] *= RT_(a.x, p.x, 1); acc[ai][bj][m][0][1] *= RT_(a.x, p.x, 0); acc[ai][bj][m][0][2] *= RT_(a.y, p.y, 1); acc[ai][bj][m][0][3] *= RT_(a.y, p.y, 0);
;                     acc[ai][bj][m][1][0] *= RT_(a.z, p.z, 1); acc[ai][bj][m][1][1] *= RT_(a.z, p.z, 0); acc[ai][bj][m][1][2] *= RT_(a.w, p.w, 1); acc[ai][bj][m][1][3] *= RT_(a.w, p.w, 0);
;     ...
;                     asm volatile("" ::: "memory"); }
; template <class Epi, class Sched, bool ALIGN_EPI = false, bool SP2 = false>
; __device__ __forceinline__ void gemm_phase(PG8_LAS unsigned char* lds, const Gemm g, const Sched& S, const Epi& E) {
;     ...
;             PG8_LDB(B0, 0, 0); PG8_LDB(B1, 0, 1); PG8_SCHED; PG8_LDA(At, 0, 0); PG8_STAGE(PG8_SA(1, 1), a1 + hstepA, voffA);
;             PG8_WAIT_V(8); PG8_WAIT_L(0); PG8_BAR; PG8_MMA(0, 0, At, B0); PG8_MMA(0, 1, At, B1); PG8_BAR; PG8_SCHED;
	v_max_f32_e32 v130, 0xda24260, v130
	v_max_f32_e32 v131, 0xda24260, v131
	v_rcp_f32_e32 v130, v130
	v_rcp_f32_e32 v131, v131
	v_pk_mul_f32 v[10:11], v[10:11], v[128:129]
	v_lshlrev_b32_e32 v128, 16, v132
	v_and_b32_e32 v129, 0xffff0000, v132
	v_pk_mul_f32 v[128:129], v[130:131], v[128:129]
	v_lshlrev_b32_e32 v130, 16, v137
	v_and_b32_e32 v131, 0xffff0000, v137
	v_max_f32_e32 v130, v130, v130
	v_max_f32_e32 v131, v131, v131
	v_max_f32_e32 v130, 0xda24260, v130
	v_max_f32_e32 v131, 0xda24260, v131
	v_rcp_f32_e32 v130, v130
	v_rcp_f32_e32 v131, v131
	v_pk_mul_f32 v[4:5], v[4:5], v[128:129]
	v_lshlrev_b32_e32 v128, 16, v133
	v_and_b32_e32 v129, 0xffff0000, v133
	v_pk_mul_f32 v[128:129], v[130:131], v[128:129]
	v_lshlrev_b32_e32 v130, 16, v138
	v_and_b32_e32 v131, 0xffff0000, v138
	v_max_f32_e32 v130, v130, v130
	v_max_f32_e32 v131, v131, v131
	v_max_f32_e32 v130, 0xda24260, v130
	v_max_f32_e32 v131, 0xda24260, v131
	v_rcp_f32_e32 v130, v130
	v_rcp_f32_e32 v131, v131
	v_pk_mul_f32 v[6:7], v[6:7], v[128:129]
	v_lshlrev_b32_e32 v128, 16, v134
	v_and_b32_e32 v129, 0xffff0000, v134
	v_pk_mul_f32 v[128:129], v[130:131], v[128:129]
	v_lshlrev_b32_e32 v130, 16, v139
	v_and_b32_e32 v131, 0xffff0000, v139
	v_max_f32_e32 v130, v130, v130
	v_max_f32_e32 v131, v131, v131
	v_max_f32_e32 v130, 0xda24260, v130
	v_max_f32_e32 v131, 0xda24260, v131
	v_rcp_f32_e32 v130, v130
	v_rcp_f32_e32 v131, v131
	v_pk_mul_f32 v[0:1], v[0:1], v[128:129]
	v_lshlrev_b32_e32 v128, 16, v135
	v_and_b32_e32 v129, 0xffff0000, v135
	v_pk_mul_f32 v[128:129], v[130:131], v[128:129]
	s_nop 0
	v_pk_mul_f32 v[2:3], v[2:3], v[128:129]
.LBB0_673:
	s_add_i32 s74, s44, 2
	s_add_u32 s45, s42, 0xfff80080
	s_addc_u32 s46, s43, -1
	s_add_i32 s75, 0, 0x10000
	v_add_u32_e32 v140, s75, v189
	v_add_u32_e32 v156, s69, v189
	ds_read_b128 v[128:131], v140
	ds_read_b128 v[132:135], v140 offset:1024
	ds_read_b128 v[136:139], v140 offset:2048
	ds_read_b128 v[140:143], v140 offset:3072
	ds_read_b128 v[144:147], v156
	ds_read_b128 v[148:151], v156 offset:1024
	ds_read_b128 v[152:155], v156 offset:2048
	ds_read_b128 v[156:159], v156 offset:3072
	s_cmp_eq_u32 s62, s44
	s_cselect_b32 s47, s29, s46
	s_cselect_b32 s46, s31, s45
	s_cselect_b32 s45, s70, s73
	s_cselect_b32 s44, s71, s72
	v_lshl_add_u64 v[220:221], s[42:43], 0, v[170:171]
	s_add_i32 m0, s52, 0xc000
	ds_read_b128 v[182:185], v191
	ds_read_b128 v[192:195], v191 offset:1024
	ds_read_b128 v[196:199], v191 offset:2048
	ds_read_b128 v[200:203], v191 offset:3072
	ds_read_b128 v[204:207], v191 offset:4096
	ds_read_b128 v[208:211], v191 offset:5120
	ds_read_b128 v[212:215], v191 offset:6144
	ds_read_b128 v[216:219], v191 offset:7168
	global_load_lds_dwordx4 v[220:221], off
	v_lshl_add_u64 v[220:221], s[42:43], 0, v[168:169]
	s_add_i32 m0, s52, 0xe000
	s_nop 0
	global_load_lds_dwordx4 v[220:221], off
	s_waitcnt vmcnt(8)
	s_waitcnt lgkmcnt(0)
	s_barrier
	s_waitcnt lgkmcnt(0)
	v_mfma_f32_16x16x32_bf16 v[124:127], v[128:131], v[182:185], v[124:127]
	v_mfma_f32_16x16x32_bf16 v[120:123], v[136:139], v[182:185], v[120:123]
	v_mfma_f32_16x16x32_bf16 v[108:111], v[128:131], v[196:199], v[108:111]
	v_mfma_f32_16x16x32_bf16 v[104:107], v[136:139], v[196:199], v[104:107]
	v_mfma_f32_16x16x32_bf16 v[92:95], v[128:131], v[204:207], v[92:95]
	v_mfma_f32_16x16x32_bf16 v[88:91], v[136:139], v[204:207], v[88:91]
	v_mfma_f32_16x16x32_bf16 v[76:79], v[128:131], v[212:215], v[76:79]
	v_mfma_f32_16x16x32_bf16 v[72:75], v[136:139], v[212:215], v[72:75]
	v_mfma_f32_16x16x32_bf16 v[124:127], v[132:135], v[192:195], v[124:127]
	v_mfma_f32_16x16x32_bf16 v[120:123], v[140:143], v[192:195], v[120:123]
	v_mfma_f32_16x16x32_bf16 v[108:111], v[132:135], v[200:203], v[108:111]
	v_mfma_f32_16x16x32_bf16 v[104:107], v[140:143], v[200:203], v[104:107]
	v_mfma_f32_16x16x32_bf16 v[92:95], v[132:135], v[208:211], v[92:95]
	v_mfma_f32_16x16x32_bf16 v[88:91], v[140:143], v[208:211], v[88:91]
	v_mfma_f32_16x16x32_bf16 v[76:79], v[132:135], v[216:219], v[76:79]
	v_mfma_f32_16x16x32_bf16 v[72:75], v[140:143], v[216:219], v[72:75]
	v_mfma_f32_16x16x32_bf16 v[116:119], v[144:147], v[182:185], v[116:119]
	v_mfma_f32_16x16x32_bf16 v[112:115], v[152:155], v[182:185], v[112:115]
	v_mfma_f32_16x16x32_bf16 v[100:103], v[144:147], v[196:199], v[100:103]
	v_mfma_f32_16x16x32_bf16 v[96:99], v[152:155], v[196:199], v[96:99]
	v_mfma_f32_16x16x32_bf16 v[84:87], v[144:147], v[204:207], v[84:87]
	v_mfma_f32_16x16x32_bf16 v[80:83], v[152:155], v[204:207], v[80:83]
	v_mfma_f32_16x16x32_bf16 v[68:71], v[144:147], v[212:215], v[68:71]
	v_mfma_f32_16x16x32_bf16 v[64:67], v[152:155], v[212:215], v[64:67]
	v_mfma_f32_16x16x32_bf16 v[116:119], v[148:151], v[192:195], v[116:119]
	v_mfma_f32_16x16x32_bf16 v[112:115], v[156:159], v[192:195], v[112:115]
	v_mfma_f32_16x16x32_bf16 v[100:103], v[148:151], v[200:203], v[100:103]
	v_mfma_f32_16x16x32_bf16 v[96:99], v[156:159], v[200:203], v[96:99]
	v_mfma_f32_16x16x32_bf16 v[84:87], v[148:151], v[208:211], v[84:87]
	v_mfma_f32_16x16x32_bf16 v[80:83], v[156:159], v[208:211], v[80:83]
	v_mfma_f32_16x16x32_bf16 v[68:71], v[148:151], v[216:219], v[68:71]
	v_mfma_f32_16x16x32_bf16 v[64:67], v[156:159], v[216:219], v[64:67]
	s_barrier
; #define PG8_STAGE(bufoff, gbase, voff) do { _Pragma("unroll") for (int _i = 0; _i < 2; ++_i) \
;         __builtin_amdgcn_global_load_lds((const unsigned*)((const char*)(gbase) + (voff)[_i]), (PG8_LAS unsigned*)(lds + (bufoff) + ldsw + _i * 8192), 16, 0, 0); } while (0)
; #define PG8_LDA(dst, b, h) do { _Pragma("unroll") for (int m = 0; m < 4; ++m) _Pragma("unroll") for (int k = 0; k < 2; ++k) dst[m][k] = *(const PG8_LAS bf16x8*)(lds + PG8_SA(b, h) + aoff + m * 2048 + k * 1024); } while (0)
; #define PG8_LDB(dst, b, h) do { _Pragma("unroll") for (int n = 0; n < 2; ++n) _Pragma("unroll") for (int k = 0; k < 2; ++k) dst[n][k] = *(const PG8_LAS bf16x8*)(lds + PG8_SB(b, h) + boff + n * 2048 + k * 1024); } while (0)
; #define PG8_MMA(ai, bj, At, Bt) do { __builtin_amdgcn_s_setprio(1); _Pragma("unroll") for (int m = 0; m < 4; ++m) _Pragma("unroll") for (int n = 0; n < 2; ++n) _Pragma("unroll") for (int k = 0; k < 2; ++k) \
;         acc[ai][bj][m][n] = __builtin_amdgcn_mfma_f32_16x16x32_bf16(Bt[n][k], At[m][k], acc[ai][bj][m][n], 0, 0, 0); __builtin_amdgcn_s_setprio(0); } while (0)
; #define PG8_WAIT_V(n) asm volatile("s_waitcnt vmcnt(" #n ")" ::: "memory")
; #define PG8_WAIT_L(n) asm volatile("s_waitcnt lgkmcnt(" #n ")" ::: "memory")
; #define PG8_BAR __builtin_amdgcn_s_barrier()
; #define PG8_SCHED __builtin_amdgcn_sched_barrier(0)
; template <class Epi, class Sched, bool ALIGN_EPI = false, bool SP2 = false>
; __device__ __forceinline__ void gemm_phase(PG8_LAS unsigned char* lds, const Gemm g, const Sched& S, const Epi& E) {
;     ...
;             PG8_LDA(At, 0, 1); PG8_STAGE(PG8_SB(0, 0), b2, voffB); PG8_STAGE(PG8_SB(0, 1), b2 + hstepB, voffB); PG8_STAGE(PG8_SA(0, 0), a2, voffA);
;             PG8_WAIT_V(8); PG8_WAIT_L(0); PG8_BAR; PG8_MMA(1, 0, At, B0); PG8_MMA(1, 1, At, B1); PG8_BAR; PG8_SCHED;
;             PG8_LDB(B0, 1, 0); PG8_LDB(B1, 1, 1); PG8_SCHED; PG8_LDA(At, 1, 0); PG8_STAGE(PG8_SA(0, 1), a2 + hstepA, voffA);
;             PG8_WAIT_V(8); PG8_WAIT_L(0); PG8_BAR; PG8_MMA(0, 0, At, B0); PG8_MMA(0, 1, At, B1); PG8_BAR; PG8_SCHED;
	s_add_i32 s75, s75, s51
	v_lshl_add_u64 v[220:221], s[44:45], 0, v[164:165]
	s_mov_b32 m0, s75
	ds_read_b128 v[182:185], v191 offset:16384
	ds_read_b128 v[192:195], v191 offset:17408
	ds_read_b128 v[196:199], v191 offset:18432
	ds_read_b128 v[200:203], v191 offset:19456
	ds_read_b128 v[204:207], v191 offset:20480
	ds_read_b128 v[208:211], v191 offset:21504
	ds_read_b128 v[212:215], v191 offset:22528
	ds_read_b128 v[216:219], v191 offset:23552
	global_load_lds_dwordx4 v[220:221], off
	s_add_i32 m0, s75, 0x2000
	s_add_u32 s76, s44, 0x80000
	v_lshl_add_u64 v[222:223], s[44:45], 0, v[160:161]
	s_addc_u32 s77, s45, 0
	s_add_i32 s75, s69, s51
	global_load_lds_dwordx4 v[222:223], off
	v_lshl_add_u64 v[224:225], s[76:77], 0, v[164:165]
	s_mov_b32 m0, s75
	v_lshl_add_u64 v[228:229], s[46:47], 0, v[162:163]
	global_load_lds_dwordx4 v[224:225], off
	v_lshl_add_u64 v[224:225], s[76:77], 0, v[160:161]
	s_add_i32 m0, s75, 0x2000
	s_nop 0
	global_load_lds_dwordx4 v[224:225], off
	v_lshl_add_u64 v[224:225], s[46:47], 0, v[166:167]
	s_mov_b32 m0, s52
	s_nop 0
	global_load_lds_dwordx4 v[224:225], off
	s_mov_b32 m0, s53
	s_nop 0
	global_load_lds_dwordx4 v[228:229], off
	s_waitcnt vmcnt(8)
	s_waitcnt lgkmcnt(0)
	s_barrier
	s_waitcnt lgkmcnt(0)
	v_mfma_f32_16x16x32_bf16 v[60:63], v[128:131], v[182:185], v[60:63]
	v_mfma_f32_16x16x32_bf16 v[56:59], v[136:139], v[182:185], v[56:59]
	v_mfma_f32_16x16x32_bf16 v[44:47], v[128:131], v[196:199], v[44:47]
	v_mfma_f32_16x16x32_bf16 v[40:43], v[136:139], v[196:199], v[40:43]
	v_mfma_f32_16x16x32_bf16 v[28:31], v[128:131], v[204:207], v[28:31]
	v_mfma_f32_16x16x32_bf16 v[24:27], v[136:139], v[204:207], v[24:27]
	v_mfma_f32_16x16x32_bf16 v[12:15], v[128:131], v[212:215], v[12:15]
	v_mfma_f32_16x16x32_bf16 v[8:11], v[136:139], v[212:215], v[8:11]
	v_mfma_f32_16x16x32_bf16 v[60:63], v[132:135], v[192:195], v[60:63]
	v_mfma_f32_16x16x32_bf16 v[56:59], v[140:143], v[192:195], v[56:59]
	v_mfma_f32_16x16x32_bf16 v[44:47], v[132:135], v[200:203], v[44:47]
	v_mfma_f32_16x16x32_bf16 v[40:43], v[140:143], v[200:203], v[40:43]
	v_mfma_f32_16x16x32_bf16 v[28:31], v[132:135], v[208:211], v[28:31]
	v_mfma_f32_16x16x32_bf16 v[24:27], v[140:143], v[208:211], v[24:27]
	v_mfma_f32_16x16x32_bf16 v[12:15], v[132:135], v[216:219], v[12:15]
	v_mfma_f32_16x16x32_bf16 v[8:11], v[140:143], v[216:219], v[8:11]
	v_mfma_f32_16x16x32_bf16 v[52:55], v[144:147], v[182:185], v[52:55]
	v_mfma_f32_16x16x32_bf16 v[48:51], v[152:155], v[182:185], v[48:51]
	v_mfma_f32_16x16x32_bf16 v[36:39], v[144:147], v[196:199], v[36:39]
	v_mfma_f32_16x16x32_bf16 v[32:35], v[152:155], v[196:199], v[32:35]
	v_mfma_f32_16x16x32_bf16 v[20:23], v[144:147], v[204:207], v[20:23]
	v_mfma_f32_16x16x32_bf16 v[16:19], v[152:155], v[204:207], v[16:19]
	v_mfma_f32_16x16x32_bf16 v[4:7], v[144:147], v[212:215], v[4:7]
	v_mfma_f32_16x16x32_bf16 v[0:3], v[152:155], v[212:215], v[0:3]
	v_mfma_f32_16x16x32_bf16 v[52:55], v[148:151], v[192:195], v[52:55]
	v_mfma_f32_16x16x32_bf16 v[48:51], v[156:159], v[192:195], v[48:51]
	v_mfma_f32_16x16x32_bf16 v[36:39], v[148:151], v[200:203], v[36:39]
	v_mfma_f32_16x16x32_bf16 v[32:35], v[156:159], v[200:203], v[32:35]
	v_mfma_f32_16x16x32_bf16 v[20:23], v[148:151], v[208:211], v[20:23]
	v_mfma_f32_16x16x32_bf16 v[16:19], v[156:159], v[208:211], v[16:19]
	v_mfma_f32_16x16x32_bf16 v[4:7], v[148:151], v[216:219], v[4:7]
	v_mfma_f32_16x16x32_bf16 v[0:3], v[156:159], v[216:219], v[0:3]
	s_barrier
	s_add_i32 s75, 0, 0x18000
	s_add_i32 s76, 0, 0x1c000
	v_add_u32_e32 v140, s75, v189
	v_add_u32_e32 v156, s76, v189
	ds_read_b128 v[128:131], v140
	ds_read_b128 v[132:135], v140 offset:1024
	ds_read_b128 v[136:139], v140 offset:2048
	ds_read_b128 v[140:143], v140 offset:3072
	ds_read_b128 v[144:147], v156
	ds_read_b128 v[148:151], v156 offset:1024
	ds_read_b128 v[152:155], v156 offset:2048
	ds_read_b128 v[156:159], v156 offset:3072
	s_add_u32 s46, s46, 0x80000
	s_addc_u32 s47, s47, 0
	s_mov_b32 m0, s54
	v_lshl_add_u64 v[230:231], s[46:47], 0, v[166:167]
	ds_read_b128 v[182:185], v191 offset:32768
	ds_read_b128 v[192:195], v191 offset:33792
	ds_read_b128 v[196:199], v191 offset:34816
	ds_read_b128 v[200:203], v191 offset:35840
	ds_read_b128 v[204:207], v191 offset:36864
	ds_read_b128 v[208:211], v191 offset:37888
	ds_read_b128 v[212:215], v191 offset:38912
	ds_read_b128 v[216:219], v191 offset:39936
	global_load_lds_dwordx4 v[230:231], off
	v_lshl_add_u64 v[230:231], s[46:47], 0, v[162:163]
	s_mov_b32 m0, s55
	s_nop 0
	global_load_lds_dwordx4 v[230:231], off
	s_waitcnt vmcnt(8)
	s_waitcnt lgkmcnt(0)
	s_barrier
; #define PG8_STAGE(bufoff, gbase, voff) do { _Pragma("unroll") for (int _i = 0; _i < 2; ++_i) \
;         __builtin_amdgcn_global_load_lds((const unsigned*)((const char*)(gbase) + (voff)[_i]), (PG8_LAS unsigned*)(lds + (bufoff) + ldsw + _i * 8192), 16, 0, 0); } while (0)
; #define PG8_LDA(dst, b, h) do { _Pragma("unroll") for (int m = 0; m < 4; ++m) _Pragma("unroll") for (int k = 0; k < 2; ++k) dst[m][k] = *(const PG8_LAS bf16x8*)(lds + PG8_SA(b, h) + aoff + m * 2048 + k * 1024); } while (0)
; #define PG8_MMA(ai, bj, At, Bt) do { __builtin_amdgcn_s_setprio(1); _Pragma("unroll") for (int m = 0; m < 4; ++m) _Pragma("unroll") for (int n = 0; n < 2; ++n) _Pragma("unroll") for (int k = 0; k < 2; ++k) \
;         acc[ai][bj][m][n] = __builtin_amdgcn_mfma_f32_16x16x32_bf16(Bt[n][k], At[m][k], acc[ai][bj][m][n], 0, 0, 0); __builtin_amdgcn_s_setprio(0); } while (0)
; #define PG8_WAIT_V(n) asm volatile("s_waitcnt vmcnt(" #n ")" ::: "memory")
; #define PG8_WAIT_L(n) asm volatile("s_waitcnt lgkmcnt(" #n ")" ::: "memory")
; #define PG8_BAR __builtin_amdgcn_s_barrier()
; #define PG8_SCHED __builtin_amdgcn_sched_barrier(0)
; template <class Epi, class Sched, bool ALIGN_EPI = false, bool SP2 = false>
; __device__ __forceinline__ void gemm_phase(PG8_LAS unsigned char* lds, const Gemm g, const Sched& S, const Epi& E) {
;     ...
;             PG8_WAIT_V(8); PG8_WAIT_L(0); PG8_BAR; PG8_MMA(0, 0, At, B0); PG8_MMA(0, 1, At, B1); PG8_BAR; PG8_SCHED;
;             PG8_LDA(At, 1, 1); PG8_STAGE(PG8_SB(1, 0), b3, voffB); PG8_STAGE(PG8_SB(1, 1), b3 + hstepB, voffB); PG8_STAGE(PG8_SA(1, 0), a3, voffA);
;             PG8_WAIT_V(8); PG8_WAIT_L(0); PG8_BAR; PG8_MMA(1, 0, At, B0); PG8_MMA(1, 1, At, B1); PG8_BAR; PG8_SCHED;
	s_waitcnt lgkmcnt(0)
	v_mfma_f32_16x16x32_bf16 v[124:127], v[128:131], v[182:185], v[124:127]
	v_mfma_f32_16x16x32_bf16 v[120:123], v[136:139], v[182:185], v[120:123]
	v_mfma_f32_16x16x32_bf16 v[108:111], v[128:131], v[196:199], v[108:111]
	v_mfma_f32_16x16x32_bf16 v[104:107], v[136:139], v[196:199], v[104:107]
	v_mfma_f32_16x16x32_bf16 v[92:95], v[128:131], v[204:207], v[92:95]
	v_mfma_f32_16x16x32_bf16 v[88:91], v[136:139], v[204:207], v[88:91]
	v_mfma_f32_16x16x32_bf16 v[76:79], v[128:131], v[212:215], v[76:79]
	v_mfma_f32_16x16x32_bf16 v[72:75], v[136:139], v[212:215], v[72:75]
	v_mfma_f32_16x16x32_bf16 v[124:127], v[132:135], v[192:195], v[124:127]
	v_mfma_f32_16x16x32_bf16 v[120:123], v[140:143], v[192:195], v[120:123]
	v_mfma_f32_16x16x32_bf16 v[108:111], v[132:135], v[200:203], v[108:111]
	v_mfma_f32_16x16x32_bf16 v[104:107], v[140:143], v[200:203], v[104:107]
	v_mfma_f32_16x16x32_bf16 v[92:95], v[132:135], v[208:211], v[92:95]
	v_mfma_f32_16x16x32_bf16 v[88:91], v[140:143], v[208:211], v[88:91]
	v_mfma_f32_16x16x32_bf16 v[76:79], v[132:135], v[216:219], v[76:79]
	v_mfma_f32_16x16x32_bf16 v[72:75], v[140:143], v[216:219], v[72:75]
	v_mfma_f32_16x16x32_bf16 v[116:119], v[144:147], v[182:185], v[116:119]
	v_mfma_f32_16x16x32_bf16 v[112:115], v[152:155], v[182:185], v[112:115]
	v_mfma_f32_16x16x32_bf16 v[100:103], v[144:147], v[196:199], v[100:103]
	v_mfma_f32_16x16x32_bf16 v[96:99], v[152:155], v[196:199], v[96:99]
	v_mfma_f32_16x16x32_bf16 v[84:87], v[144:147], v[204:207], v[84:87]
	v_mfma_f32_16x16x32_bf16 v[80:83], v[152:155], v[204:207], v[80:83]
	v_mfma_f32_16x16x32_bf16 v[68:71], v[144:147], v[212:215], v[68:71]
	v_mfma_f32_16x16x32_bf16 v[64:67], v[152:155], v[212:215], v[64:67]
	v_mfma_f32_16x16x32_bf16 v[116:119], v[148:151], v[192:195], v[116:119]
	v_mfma_f32_16x16x32_bf16 v[112:115], v[156:159], v[192:195], v[112:115]
	v_mfma_f32_16x16x32_bf16 v[100:103], v[148:151], v[200:203], v[100:103]
	v_mfma_f32_16x16x32_bf16 v[96:99], v[156:159], v[200:203], v[96:99]
	v_mfma_f32_16x16x32_bf16 v[84:87], v[148:151], v[208:211], v[84:87]
	v_mfma_f32_16x16x32_bf16 v[80:83], v[156:159], v[208:211], v[80:83]
	v_mfma_f32_16x16x32_bf16 v[68:71], v[148:151], v[216:219], v[68:71]
	v_mfma_f32_16x16x32_bf16 v[64:67], v[156:159], v[216:219], v[64:67]
	s_barrier
	s_add_i32 s46, s75, s51
	v_lshl_add_u64 v[220:221], v[220:221], 0, s[16:17]
	s_mov_b32 m0, s46
	ds_read_b128 v[182:185], v191 offset:49152
	ds_read_b128 v[192:195], v191 offset:50176
	ds_read_b128 v[196:199], v191 offset:51200
	ds_read_b128 v[200:203], v191 offset:52224
	ds_read_b128 v[204:207], v191 offset:53248
	ds_read_b128 v[208:211], v191 offset:54272
	ds_read_b128 v[212:215], v191 offset:55296
	ds_read_b128 v[216:219], v191 offset:56320
	global_load_lds_dwordx4 v[220:221], off
	s_add_i32 m0, s46, 0x2000
	s_add_u32 s44, s44, 0x80080
	v_lshl_add_u64 v[220:221], v[222:223], 0, s[16:17]
	s_addc_u32 s45, s45, 0
	s_add_i32 s46, s76, s51
	global_load_lds_dwordx4 v[220:221], off
	v_lshl_add_u64 v[220:221], s[44:45], 0, v[164:165]
	s_mov_b32 m0, s46
	s_nop 0
	global_load_lds_dwordx4 v[220:221], off
	v_lshl_add_u64 v[220:221], s[44:45], 0, v[160:161]
	s_add_i32 m0, s46, 0x2000
	s_nop 0
	global_load_lds_dwordx4 v[220:221], off
	v_lshl_add_u64 v[220:221], v[224:225], 0, s[16:17]
	s_mov_b32 m0, s58
	s_nop 0
	global_load_lds_dwordx4 v[220:221], off
	v_lshl_add_u64 v[220:221], v[228:229], 0, s[16:17]
	s_mov_b32 m0, s59
	s_nop 0
	global_load_lds_dwordx4 v[220:221], off
	s_waitcnt vmcnt(8)
	s_waitcnt lgkmcnt(0)
	s_barrier
	s_waitcnt lgkmcnt(0)
	v_mfma_f32_16x16x32_bf16 v[60:63], v[128:131], v[182:185], v[60:63]
	v_mfma_f32_16x16x32_bf16 v[56:59], v[136:139], v[182:185], v[56:59]
	v_mfma_f32_16x16x32_bf16 v[44:47], v[128:131], v[196:199], v[44:47]
	v_mfma_f32_16x16x32_bf16 v[40:43], v[136:139], v[196:199], v[40:43]
	v_mfma_f32_16x16x32_bf16 v[28:31], v[128:131], v[204:207], v[28:31]
	v_mfma_f32_16x16x32_bf16 v[24:27], v[136:139], v[204:207], v[24:27]
	v_mfma_f32_16x16x32_bf16 v[12:15], v[128:131], v[212:215], v[12:15]
	v_mfma_f32_16x16x32_bf16 v[8:11], v[136:139], v[212:215], v[8:11]
	v_mfma_f32_16x16x32_bf16 v[60:63], v[132:135], v[192:195], v[60:63]
	v_mfma_f32_16x16x32_bf16 v[56:59], v[140:143], v[192:195], v[56:59]
	v_mfma_f32_16x16x32_bf16 v[44:47], v[132:135], v[200:203], v[44:47]
	v_mfma_f32_16x16x32_bf16 v[40:43], v[140:143], v[200:203], v[40:43]
	v_mfma_f32_16x16x32_bf16 v[28:31], v[132:135], v[208:211], v[28:31]
	v_mfma_f32_16x16x32_bf16 v[24:27], v[140:143], v[208:211], v[24:27]
	v_mfma_f32_16x16x32_bf16 v[12:15], v[132:135], v[216:219], v[12:15]
	v_mfma_f32_16x16x32_bf16 v[8:11], v[140:143], v[216:219], v[8:11]
	v_mfma_f32_16x16x32_bf16 v[52:55], v[144:147], v[182:185], v[52:55]
	v_mfma_f32_16x16x32_bf16 v[48:51], v[152:155], v[182:185], v[48:51]
	v_mfma_f32_16x16x32_bf16 v[36:39], v[144:147], v[196:199], v[36:39]
	v_mfma_f32_16x16x32_bf16 v[32:35], v[152:155], v[196:199], v[32:35]
	v_mfma_f32_16x16x32_bf16 v[20:23], v[144:147], v[204:207], v[20:23]
	v_mfma_f32_16x16x32_bf16 v[16:19], v[152:155], v[204:207], v[16:19]
	v_mfma_f32_16x16x32_bf16 v[4:7], v[144:147], v[212:215], v[4:7]
	v_mfma_f32_16x16x32_bf16 v[0:3], v[152:155], v[212:215], v[0:3]
	v_mfma_f32_16x16x32_bf16 v[52:55], v[148:151], v[192:195], v[52:55]
	v_mfma_f32_16x16x32_bf16 v[48:51], v[156:159], v[192:195], v[48:51]
	v_mfma_f32_16x16x32_bf16 v[36:39], v[148:151], v[200:203], v[36:39]
	v_mfma_f32_16x16x32_bf16 v[32:35], v[156:159], v[200:203], v[32:35]
	v_mfma_f32_16x16x32_bf16 v[20:23], v[148:151], v[208:211], v[20:23]
	v_mfma_f32_16x16x32_bf16 v[16:19], v[156:159], v[208:211], v[16:19]
	v_mfma_f32_16x16x32_bf16 v[4:7], v[148:151], v[216:219], v[4:7]
	v_mfma_f32_16x16x32_bf16 v[0:3], v[156:159], v[216:219], v[0:3]
	s_barrier
	s_add_u32 s72, s72, 0x100
	s_addc_u32 s73, s73, 0
	s_add_u32 s42, s42, 0x100
	s_addc_u32 s43, s43, 0
	s_cmp_ge_i32 s74, s57
	s_cbranch_scc1 .LBB0_675
	s_mov_b32 s44, s74
	s_cmp_lg_u32 s61, s44
	s_cbranch_scc0 .LBB0_672
	s_branch .LBB0_673
.LBB0_675:
	s_and_b64 vcc, exec, s[20:21]
	s_cbranch_vccz .LBB0_677
	s_barrier

;     __host__ __device__ bool next(int i, Unit& u) const { return i < cnt ? so.next(base + i, u) : false; }
;     __host__ __device__ bool next(int i, Unit& u) const { const int L = i * G + c; if (L >= 32) return false; u.g = L >> 3; u.pm = L & 7; u.pn = 0; return true; }
; #define PG8_STAGE(bufoff, gbase, voff) do { _Pragma("unroll") for (int _i = 0; _i < 2; ++_i) \
;         __builtin_amdgcn_global_load_lds((const unsigned*)((const char*)(gbase) + (voff)[_i]), (PG8_LAS unsigned*)(lds + (bufoff) + ldsw + _i * 8192), 16, 0, 0); } while (0)
; #define PG8_LDA(dst, b, h) do { _Pragma("unroll") for (int m = 0; m < 4; ++m) _Pragma("unroll") for (int k = 0; k < 2; ++k) dst[m][k] = *(const PG8_LAS bf16x8*)(lds + PG8_SA(b, h) + aoff + m * 2048 + k * 1024); } while (0)
; #define PG8_SCHED __builtin_amdgcn_sched_barrier(0)
; template <class Epi, class Sched, bool ALIGN_EPI = false, bool SP2 = false>
; __device__ __forceinline__ void gemm_phase(PG8_LAS unsigned char* lds, const Gemm g, const Sched& S, const Epi& E) {
;     ...
;         const bool has_next = S.next(ui + 1, nxt);
;         const char* nA = has_next ? (const char*)(g.A + (size_t)nxt.g * g.gsA) + (size_t)nxt.pm * tstepA : cA; const char* nB = has_next ? (const char*)(g.Bt + (size_t)nxt.g * g.gsB) + (size_t)nxt.pn * tstepB : cB;
;         for (int t = 0; t < nt; t += 2) {
;             if constexpr (Epi::MIDK) { if (t == (nt >> 1)) { asm volatile("s_waitcnt vmcnt(0)" ::: "memory"); E.mid(acc, cur, wr, wc, fr, fq); asm volatile("s_waitcnt vmcnt(0)" ::: "memory"); } }
;             const bool last = (t == nt - 2);
;             const char* a1 = cA + (size_t)(t + 1) * kstep;
;             const char* a2 = last ? nA : cA + (size_t)(t + 2) * kstep; const char* b2 = last ? nB : cB + (size_t)(t + 2) * kstep;
;             const char* a3 = a2 + kstep; const char* b3 = b2 + kstep;
;             if (last && has_next) S.a_ready(nxt);
;             if constexpr (SP2) {
;             PG8_LDB(B0, 0, 0); PG8_LDB(B1, 0, 1); PG8_SCHED; PG8_LDA(At, 0, 0); PG8_STAGE(PG8_SA(1, 1), a1 + hstepA, voffA);
;     ...
; #pragma unroll
;         for (int a = 0; a < 2; ++a)
; #pragma unroll
;             for (int b = 0; b < 2; ++b)
; #pragma unroll
;                 for (int m = 0; m < 4; ++m)
; #pragma unroll
;                     for (int n = 0; n < 2; ++n) acc[a][b][m][n] = (f32x4){0.f, 0.f, 0.f, 0.f};
;         cur = nxt; cA = nA; cB = nB; ++ui;
.LBB0_742:
	s_ashr_i32 s31, s30, 31
	s_lshl_b64 s[34:35], s[30:31], 20
	s_add_u32 s34, s39, s34
	s_addc_u32 s35, s48, s35
	s_ashr_i32 s29, s28, 31
	s_lshl_b64 s[36:37], s[28:29], 20
	s_add_u32 s36, s49, s36
	v_mov_b32_e32 v123, 0
	s_addc_u32 s37, s50, s37
	s_andn2_b64 vcc, exec, s[16:17]
	v_mov_b32_e32 v122, v123
	v_mov_b32_e32 v121, v123
	v_mov_b32_e32 v120, v123
	v_mov_b32_e32 v127, v123
	v_mov_b32_e32 v126, v123
	v_mov_b32_e32 v125, v123
	v_mov_b32_e32 v124, v123
	v_mov_b32_e32 v111, v123
	v_mov_b32_e32 v110, v123
	v_mov_b32_e32 v109, v123
	v_mov_b32_e32 v108, v123
	v_mov_b32_e32 v107, v123
	v_mov_b32_e32 v106, v123
	v_mov_b32_e32 v105, v123
	v_mov_b32_e32 v104, v123
	v_mov_b32_e32 v95, v123
	v_mov_b32_e32 v94, v123
	v_mov_b32_e32 v93, v123
	v_mov_b32_e32 v92, v123
	v_mov_b32_e32 v91, v123
	v_mov_b32_e32 v90, v123
	v_mov_b32_e32 v89, v123
	v_mov_b32_e32 v88, v123
	v_mov_b32_e32 v79, v123
	v_mov_b32_e32 v78, v123
	v_mov_b32_e32 v77, v123
	v_mov_b32_e32 v76, v123
	v_mov_b32_e32 v75, v123
	v_mov_b32_e32 v74, v123
	v_mov_b32_e32 v73, v123
	v_mov_b32_e32 v72, v123
	v_mov_b32_e32 v119, v123
	v_mov_b32_e32 v118, v123
	v_mov_b32_e32 v117, v123
	v_mov_b32_e32 v116, v123
	v_mov_b32_e32 v115, v123
	v_mov_b32_e32 v114, v123
	v_mov_b32_e32 v113, v123
	v_mov_b32_e32 v112, v123
	v_mov_b32_e32 v103, v123
	v_mov_b32_e32 v102, v123
	v_mov_b32_e32 v101, v123
	v_mov_b32_e32 v100, v123
	v_mov_b32_e32 v99, v123
	v_mov_b32_e32 v98, v123
	v_mov_b32_e32 v97, v123
	v_mov_b32_e32 v96, v123
	v_mov_b32_e32 v87, v123
	v_mov_b32_e32 v86, v123
	v_mov_b32_e32 v85, v123
	v_mov_b32_e32 v84, v123
	v_mov_b32_e32 v83, v123
	v_mov_b32_e32 v82, v123
	v_mov_b32_e32 v81, v123
	v_mov_b32_e32 v80, v123
	v_mov_b32_e32 v71, v123
	v_mov_b32_e32 v70, v123
	v_mov_b32_e32 v69, v123
	v_mov_b32_e32 v68, v123
	v_mov_b32_e32 v67, v123
	v_mov_b32_e32 v66, v123
	v_mov_b32_e32 v65, v123
	v_mov_b32_e32 v64, v123
	v_mov_b32_e32 v63, v123
	v_mov_b32_e32 v62, v123
	v_mov_b32_e32 v61, v123
	v_mov_b32_e32 v60, v123
	v_mov_b32_e32 v59, v123
	v_mov_b32_e32 v58, v123
	v_mov_b32_e32 v57, v123
	v_mov_b32_e32 v56, v123
	v_mov_b32_e32 v47, v123
	v_mov_b32_e32 v46, v123
	v_mov_b32_e32 v45, v123
	v_mov_b32_e32 v44, v123
	v_mov_b32_e32 v43, v123
	v_mov_b32_e32 v42, v123
	v_mov_b32_e32 v41, v123
	v_mov_b32_e32 v40, v123
	v_mov_b32_e32 v31, v123
	v_mov_b32_e32 v30, v123
	v_mov_b32_e32 v29, v123
	v_mov_b32_e32 v28, v123
	v_mov_b32_e32 v27, v123
	v_mov_b32_e32 v26, v123
	v_mov_b32_e32 v25, v123
	v_mov_b32_e32 v24, v123
	v_mov_b32_e32 v15, v123
	v_mov_b32_e32 v14, v123
	v_mov_b32_e32 v13, v123
	v_mov_b32_e32 v12, v123
	v_mov_b32_e32 v11, v123
	v_mov_b32_e32 v10, v123
	v_mov_b32_e32 v9, v123
	v_mov_b32_e32 v8, v123
	v_mov_b32_e32 v55, v123
	v_mov_b32_e32 v54, v123
	v_mov_b32_e32 v53, v123
	v_mov_b32_e32 v52, v123
	v_mov_b32_e32 v51, v123
	v_mov_b32_e32 v50, v123
	v_mov_b32_e32 v49, v123
	v_mov_b32_e32 v48, v123
	v_mov_b32_e32 v39, v123
	v_mov_b32_e32 v38, v123
	v_mov_b32_e32 v37, v123
	v_mov_b32_e32 v36, v123
	v_mov_b32_e32 v35, v123
	v_mov_b32_e32 v34, v123
	v_mov_b32_e32 v33, v123
	v_mov_b32_e32 v32, v123
	v_mov_b32_e32 v23, v123
	v_mov_b32_e32 v22, v123
	v_mov_b32_e32 v21, v123
	v_mov_b32_e32 v20, v123
	v_mov_b32_e32 v19, v123
	v_mov_b32_e32 v18, v123
	v_mov_b32_e32 v17, v123
	v_mov_b32_e32 v16, v123
	v_mov_b32_e32 v7, v123
	v_mov_b32_e32 v6, v123
	v_mov_b32_e32 v5, v123
	v_mov_b32_e32 v4, v123
	s_waitcnt lgkmcnt(0)
	v_mov_b32_e32 v3, v123
	v_mov_b32_e32 v2, v123
	v_mov_b32_e32 v1, v123
	v_mov_b32_e32 v0, v123
	s_cbranch_vccnz .LBB0_745
	s_and_b64 s[46:47], s[6:7], exec
	s_cselect_b32 s29, s35, s45
	s_cselect_b32 s31, s34, s44
	s_cselect_b32 s63, s37, s43
	s_cselect_b32 s64, s36, s42
	s_add_u32 s65, s42, 0x100
	s_addc_u32 s66, s43, 0
	s_add_u32 s42, s44, 0x80080
	s_addc_u32 s43, s45, 0
	s_mov_b32 s44, 0
.LBB0_744:
	ds_read_b128 v[146:149], v158
	ds_read_b128 v[150:153], v158 offset:1024
	ds_read_b128 v[162:165], v158 offset:2048
	ds_read_b128 v[166:169], v158 offset:3072
	ds_read_b128 v[170:173], v159
	ds_read_b128 v[174:177], v159 offset:1024
	ds_read_b128 v[178:181], v159 offset:2048
	ds_read_b128 v[182:185], v159 offset:3072
	s_add_i32 s67, s44, 2
	s_add_u32 s45, s42, 0xfff80080
	s_addc_u32 s46, s43, -1
	s_cmp_eq_u32 s60, s44
	s_cselect_b32 s44, s64, s65
	s_cselect_b32 s47, s29, s46
	s_cselect_b32 s46, s31, s45
	s_cselect_b32 s45, s63, s66
	v_lshl_add_u64 v[220:221], s[42:43], 0, v[140:141]
	s_add_i32 m0, s52, 0xc000
	ds_read_b128 v[188:191], v160
	ds_read_b128 v[192:195], v160 offset:1024
	ds_read_b128 v[196:199], v160 offset:2048
	ds_read_b128 v[200:203], v160 offset:3072
	ds_read_b128 v[204:207], v160 offset:4096
	ds_read_b128 v[208:211], v160 offset:5120
	ds_read_b128 v[212:215], v160 offset:6144
	ds_read_b128 v[216:219], v160 offset:7168
	global_load_lds_dwordx4 v[220:221], off
	v_lshl_add_u64 v[220:221], s[42:43], 0, v[138:139]
	s_add_i32 m0, s52, 0xe000
	s_nop 0
	global_load_lds_dwordx4 v[220:221], off
	s_waitcnt vmcnt(8)
	s_waitcnt lgkmcnt(0)
	s_barrier
; #define PG8_STAGE(bufoff, gbase, voff) do { _Pragma("unroll") for (int _i = 0; _i < 2; ++_i) \
;         __builtin_amdgcn_global_load_lds((const unsigned*)((const char*)(gbase) + (voff)[_i]), (PG8_LAS unsigned*)(lds + (bufoff) + ldsw + _i * 8192), 16, 0, 0); } while (0)
; #define PG8_LDA(dst, b, h) do { _Pragma("unroll") for (int m = 0; m < 4; ++m) _Pragma("unroll") for (int k = 0; k < 2; ++k) dst[m][k] = *(const PG8_LAS bf16x8*)(lds + PG8_SA(b, h) + aoff + m * 2048 + k * 1024); } while (0)
; #define PG8_LDB(dst, b, h) do { _Pragma("unroll") for (int n = 0; n < 2; ++n) _Pragma("unroll") for (int k = 0; k < 2; ++k) dst[n][k] = *(const PG8_LAS bf16x8*)(lds + PG8_SB(b, h) + boff + n * 2048 + k * 1024); } while (0)
; #define PG8_MMA(ai, bj, At, Bt) do { __builtin_amdgcn_s_setprio(1); _Pragma("unroll") for (int m = 0; m < 4; ++m) _Pragma("unroll") for (int n = 0; n < 2; ++n) _Pragma("unroll") for (int k = 0; k < 2; ++k) \
;         acc[ai][bj][m][n] = __builtin_amdgcn_mfma_f32_16x16x32_bf16(Bt[n][k], At[m][k], acc[ai][bj][m][n], 0, 0, 0); __builtin_amdgcn_s_setprio(0); } while (0)
; #define PG8_WAIT_V(n) asm volatile("s_waitcnt vmcnt(" #n ")" ::: "memory")
; #define PG8_WAIT_L(n) asm volatile("s_waitcnt lgkmcnt(" #n ")" ::: "memory")
; #define PG8_BAR __builtin_amdgcn_s_barrier()
; #define PG8_SCHED __builtin_amdgcn_sched_barrier(0)
; template <class Epi, class Sched, bool ALIGN_EPI = false, bool SP2 = false>
; __device__ __forceinline__ void gemm_phase(PG8_LAS unsigned char* lds, const Gemm g, const Sched& S, const Epi& E) {
;     ...
;             PG8_WAIT_V(8); PG8_WAIT_L(0); PG8_BAR; PG8_MMA(0, 0, At, B0); PG8_MMA(0, 1, At, B1); PG8_BAR; PG8_SCHED;
;             PG8_LDA(At, 0, 1); PG8_STAGE(PG8_SB(0, 0), b2, voffB); PG8_STAGE(PG8_SB(0, 1), b2 + hstepB, voffB); PG8_STAGE(PG8_SA(0, 0), a2, voffA);
;             PG8_WAIT_V(8); PG8_WAIT_L(0); PG8_BAR; PG8_MMA(1, 0, At, B0); PG8_MMA(1, 1, At, B1); PG8_BAR; PG8_SCHED;
;             PG8_LDB(B0, 1, 0); PG8_LDB(B1, 1, 1); PG8_SCHED; PG8_LDA(At, 1, 0); PG8_STAGE(PG8_SA(0, 1), a2 + hstepA, voffA);
;             PG8_WAIT_V(8); PG8_WAIT_L(0); PG8_BAR; PG8_MMA(0, 0, At, B0); PG8_MMA(0, 1, At, B1); PG8_BAR; PG8_SCHED;
	s_waitcnt lgkmcnt(0)
	v_mfma_f32_16x16x32_bf16 v[120:123], v[146:149], v[188:191], v[120:123]
	v_mfma_f32_16x16x32_bf16 v[124:127], v[162:165], v[188:191], v[124:127]
	v_mfma_f32_16x16x32_bf16 v[108:111], v[146:149], v[196:199], v[108:111]
	v_mfma_f32_16x16x32_bf16 v[104:107], v[162:165], v[196:199], v[104:107]
	v_mfma_f32_16x16x32_bf16 v[92:95], v[146:149], v[204:207], v[92:95]
	v_mfma_f32_16x16x32_bf16 v[88:91], v[162:165], v[204:207], v[88:91]
	v_mfma_f32_16x16x32_bf16 v[76:79], v[146:149], v[212:215], v[76:79]
	v_mfma_f32_16x16x32_bf16 v[72:75], v[162:165], v[212:215], v[72:75]
	v_mfma_f32_16x16x32_bf16 v[120:123], v[150:153], v[192:195], v[120:123]
	v_mfma_f32_16x16x32_bf16 v[124:127], v[166:169], v[192:195], v[124:127]
	v_mfma_f32_16x16x32_bf16 v[108:111], v[150:153], v[200:203], v[108:111]
	v_mfma_f32_16x16x32_bf16 v[104:107], v[166:169], v[200:203], v[104:107]
	v_mfma_f32_16x16x32_bf16 v[92:95], v[150:153], v[208:211], v[92:95]
	v_mfma_f32_16x16x32_bf16 v[88:91], v[166:169], v[208:211], v[88:91]
	v_mfma_f32_16x16x32_bf16 v[76:79], v[150:153], v[216:219], v[76:79]
	v_mfma_f32_16x16x32_bf16 v[72:75], v[166:169], v[216:219], v[72:75]
	v_mfma_f32_16x16x32_bf16 v[116:119], v[170:173], v[188:191], v[116:119]
	v_mfma_f32_16x16x32_bf16 v[112:115], v[178:181], v[188:191], v[112:115]
	v_mfma_f32_16x16x32_bf16 v[100:103], v[170:173], v[196:199], v[100:103]
	v_mfma_f32_16x16x32_bf16 v[96:99], v[178:181], v[196:199], v[96:99]
	v_mfma_f32_16x16x32_bf16 v[84:87], v[170:173], v[204:207], v[84:87]
	v_mfma_f32_16x16x32_bf16 v[80:83], v[178:181], v[204:207], v[80:83]
	v_mfma_f32_16x16x32_bf16 v[68:71], v[170:173], v[212:215], v[68:71]
	v_mfma_f32_16x16x32_bf16 v[64:67], v[178:181], v[212:215], v[64:67]
	v_mfma_f32_16x16x32_bf16 v[116:119], v[174:177], v[192:195], v[116:119]
	v_mfma_f32_16x16x32_bf16 v[112:115], v[182:185], v[192:195], v[112:115]
	v_mfma_f32_16x16x32_bf16 v[100:103], v[174:177], v[200:203], v[100:103]
	v_mfma_f32_16x16x32_bf16 v[96:99], v[182:185], v[200:203], v[96:99]
	v_mfma_f32_16x16x32_bf16 v[84:87], v[174:177], v[208:211], v[84:87]
	v_mfma_f32_16x16x32_bf16 v[80:83], v[182:185], v[208:211], v[80:83]
	v_mfma_f32_16x16x32_bf16 v[68:71], v[174:177], v[216:219], v[68:71]
	v_mfma_f32_16x16x32_bf16 v[64:67], v[182:185], v[216:219], v[64:67]
	s_barrier
	s_add_i32 s68, s61, s51
	v_lshl_add_u64 v[220:221], s[44:45], 0, v[130:131]
	s_mov_b32 m0, s68
	ds_read_b128 v[188:191], v160 offset:16384
	ds_read_b128 v[192:195], v160 offset:17408
	ds_read_b128 v[196:199], v160 offset:18432
	ds_read_b128 v[200:203], v160 offset:19456
	ds_read_b128 v[204:207], v160 offset:20480
	ds_read_b128 v[208:211], v160 offset:21504
	ds_read_b128 v[212:215], v160 offset:22528
	ds_read_b128 v[216:219], v160 offset:23552
	global_load_lds_dwordx4 v[220:221], off
	s_add_i32 m0, s68, 0x2000
	s_add_u32 s68, s44, 0x80000
	v_lshl_add_u64 v[222:223], s[44:45], 0, v[134:135]
	s_addc_u32 s69, s45, 0
	s_add_i32 s70, s62, s51
	global_load_lds_dwordx4 v[222:223], off
	v_lshl_add_u64 v[224:225], s[68:69], 0, v[130:131]
	s_mov_b32 m0, s70
	v_lshl_add_u64 v[228:229], s[46:47], 0, v[132:133]
	global_load_lds_dwordx4 v[224:225], off
	v_lshl_add_u64 v[224:225], s[68:69], 0, v[134:135]
	s_add_i32 m0, s70, 0x2000
	s_nop 0
	global_load_lds_dwordx4 v[224:225], off
	v_lshl_add_u64 v[224:225], s[46:47], 0, v[128:129]
	s_mov_b32 m0, s52
	s_nop 0
	global_load_lds_dwordx4 v[224:225], off
	s_mov_b32 m0, s53
	s_nop 0
	global_load_lds_dwordx4 v[228:229], off
	s_waitcnt vmcnt(8)
	s_waitcnt lgkmcnt(0)
	s_barrier
	s_waitcnt lgkmcnt(0)
	v_mfma_f32_16x16x32_bf16 v[60:63], v[146:149], v[188:191], v[60:63]
	v_mfma_f32_16x16x32_bf16 v[56:59], v[162:165], v[188:191], v[56:59]
	v_mfma_f32_16x16x32_bf16 v[44:47], v[146:149], v[196:199], v[44:47]
	v_mfma_f32_16x16x32_bf16 v[40:43], v[162:165], v[196:199], v[40:43]
	v_mfma_f32_16x16x32_bf16 v[28:31], v[146:149], v[204:207], v[28:31]
	v_mfma_f32_16x16x32_bf16 v[24:27], v[162:165], v[204:207], v[24:27]
	v_mfma_f32_16x16x32_bf16 v[12:15], v[146:149], v[212:215], v[12:15]
	v_mfma_f32_16x16x32_bf16 v[8:11], v[162:165], v[212:215], v[8:11]
	v_mfma_f32_16x16x32_bf16 v[60:63], v[150:153], v[192:195], v[60:63]
	v_mfma_f32_16x16x32_bf16 v[56:59], v[166:169], v[192:195], v[56:59]
	v_mfma_f32_16x16x32_bf16 v[44:47], v[150:153], v[200:203], v[44:47]
	v_mfma_f32_16x16x32_bf16 v[40:43], v[166:169], v[200:203], v[40:43]
	v_mfma_f32_16x16x32_bf16 v[28:31], v[150:153], v[208:211], v[28:31]
	v_mfma_f32_16x16x32_bf16 v[24:27], v[166:169], v[208:211], v[24:27]
	v_mfma_f32_16x16x32_bf16 v[12:15], v[150:153], v[216:219], v[12:15]
	v_mfma_f32_16x16x32_bf16 v[8:11], v[166:169], v[216:219], v[8:11]
	v_mfma_f32_16x16x32_bf16 v[52:55], v[170:173], v[188:191], v[52:55]
	v_mfma_f32_16x16x32_bf16 v[48:51], v[178:181], v[188:191], v[48:51]
	v_mfma_f32_16x16x32_bf16 v[36:39], v[170:173], v[196:199], v[36:39]
	v_mfma_f32_16x16x32_bf16 v[32:35], v[178:181], v[196:199], v[32:35]
	v_mfma_f32_16x16x32_bf16 v[20:23], v[170:173], v[204:207], v[20:23]
	v_mfma_f32_16x16x32_bf16 v[16:19], v[178:181], v[204:207], v[16:19]
	v_mfma_f32_16x16x32_bf16 v[4:7], v[170:173], v[212:215], v[4:7]
	v_mfma_f32_16x16x32_bf16 v[0:3], v[178:181], v[212:215], v[0:3]
	v_mfma_f32_16x16x32_bf16 v[52:55], v[174:177], v[192:195], v[52:55]
	v_mfma_f32_16x16x32_bf16 v[48:51], v[182:185], v[192:195], v[48:51]
	v_mfma_f32_16x16x32_bf16 v[36:39], v[174:177], v[200:203], v[36:39]
	v_mfma_f32_16x16x32_bf16 v[32:35], v[182:185], v[200:203], v[32:35]
	v_mfma_f32_16x16x32_bf16 v[20:23], v[174:177], v[208:211], v[20:23]
	v_mfma_f32_16x16x32_bf16 v[16:19], v[182:185], v[208:211], v[16:19]
	v_mfma_f32_16x16x32_bf16 v[4:7], v[174:177], v[216:219], v[4:7]
	v_mfma_f32_16x16x32_bf16 v[0:3], v[182:185], v[216:219], v[0:3]
	s_barrier
; #define PG8_STAGE(bufoff, gbase, voff) do { _Pragma("unroll") for (int _i = 0; _i < 2; ++_i) \
;         __builtin_amdgcn_global_load_lds((const unsigned*)((const char*)(gbase) + (voff)[_i]), (PG8_LAS unsigned*)(lds + (bufoff) + ldsw + _i * 8192), 16, 0, 0); } while (0)
; #define PG8_LDA(dst, b, h) do { _Pragma("unroll") for (int m = 0; m < 4; ++m) _Pragma("unroll") for (int k = 0; k < 2; ++k) dst[m][k] = *(const PG8_LAS bf16x8*)(lds + PG8_SA(b, h) + aoff + m * 2048 + k * 1024); } while (0)
; #define PG8_LDB(dst, b, h) do { _Pragma("unroll") for (int n = 0; n < 2; ++n) _Pragma("unroll") for (int k = 0; k < 2; ++k) dst[n][k] = *(const PG8_LAS bf16x8*)(lds + PG8_SB(b, h) + boff + n * 2048 + k * 1024); } while (0)
; #define PG8_MMA(ai, bj, At, Bt) do { __builtin_amdgcn_s_setprio(1); _Pragma("unroll") for (int m = 0; m < 4; ++m) _Pragma("unroll") for (int n = 0; n < 2; ++n) _Pragma("unroll") for (int k = 0; k < 2; ++k) \
;         acc[ai][bj][m][n] = __builtin_amdgcn_mfma_f32_16x16x32_bf16(Bt[n][k], At[m][k], acc[ai][bj][m][n], 0, 0, 0); __builtin_amdgcn_s_setprio(0); } while (0)
; #define PG8_WAIT_V(n) asm volatile("s_waitcnt vmcnt(" #n ")" ::: "memory")
; #define PG8_WAIT_L(n) asm volatile("s_waitcnt lgkmcnt(" #n ")" ::: "memory")
; #define PG8_BAR __builtin_amdgcn_s_barrier()
; #define PG8_SCHED __builtin_amdgcn_sched_barrier(0)
; template <class Epi, class Sched, bool ALIGN_EPI = false, bool SP2 = false>
; __device__ __forceinline__ void gemm_phase(PG8_LAS unsigned char* lds, const Gemm g, const Sched& S, const Epi& E) {
;     ...
;             PG8_LDB(B0, 1, 0); PG8_LDB(B1, 1, 1); PG8_SCHED; PG8_LDA(At, 1, 0); PG8_STAGE(PG8_SA(0, 1), a2 + hstepA, voffA);
;             PG8_WAIT_V(8); PG8_WAIT_L(0); PG8_BAR; PG8_MMA(0, 0, At, B0); PG8_MMA(0, 1, At, B1); PG8_BAR; PG8_SCHED;
;             PG8_LDA(At, 1, 1); PG8_STAGE(PG8_SB(1, 0), b3, voffB); PG8_STAGE(PG8_SB(1, 1), b3 + hstepB, voffB); PG8_STAGE(PG8_SA(1, 0), a3, voffA);
;             PG8_WAIT_V(8); PG8_WAIT_L(0); PG8_BAR; PG8_MMA(1, 0, At, B0); PG8_MMA(1, 1, At, B1); PG8_BAR; PG8_SCHED;
	s_add_i32 s68, 0, 0x18000
	v_add_u32_e32 v161, s68, v156
	s_add_i32 s69, 0, 0x1c000
	ds_read_b128 v[146:149], v161
	ds_read_b128 v[150:153], v161 offset:1024
	ds_read_b128 v[162:165], v161 offset:2048
	ds_read_b128 v[166:169], v161 offset:3072
	v_add_u32_e32 v161, s69, v156
	ds_read_b128 v[170:173], v161
	ds_read_b128 v[174:177], v161 offset:1024
	ds_read_b128 v[178:181], v161 offset:2048
	ds_read_b128 v[182:185], v161 offset:3072
	s_add_u32 s46, s46, 0x80000
	s_addc_u32 s47, s47, 0
	s_mov_b32 m0, s54
	v_lshl_add_u64 v[230:231], s[46:47], 0, v[128:129]
	ds_read_b128 v[188:191], v160 offset:32768
	ds_read_b128 v[192:195], v160 offset:33792
	ds_read_b128 v[196:199], v160 offset:34816
	ds_read_b128 v[200:203], v160 offset:35840
	ds_read_b128 v[204:207], v160 offset:36864
	ds_read_b128 v[208:211], v160 offset:37888
	ds_read_b128 v[212:215], v160 offset:38912
	ds_read_b128 v[216:219], v160 offset:39936
	global_load_lds_dwordx4 v[230:231], off
	v_lshl_add_u64 v[230:231], s[46:47], 0, v[132:133]
	s_mov_b32 m0, s55
	s_nop 0
	global_load_lds_dwordx4 v[230:231], off
	s_waitcnt vmcnt(8)
	s_waitcnt lgkmcnt(0)
	s_barrier
	s_waitcnt lgkmcnt(0)
	v_mfma_f32_16x16x32_bf16 v[120:123], v[146:149], v[188:191], v[120:123]
	v_mfma_f32_16x16x32_bf16 v[124:127], v[162:165], v[188:191], v[124:127]
	v_mfma_f32_16x16x32_bf16 v[108:111], v[146:149], v[196:199], v[108:111]
	v_mfma_f32_16x16x32_bf16 v[104:107], v[162:165], v[196:199], v[104:107]
	v_mfma_f32_16x16x32_bf16 v[92:95], v[146:149], v[204:207], v[92:95]
	v_mfma_f32_16x16x32_bf16 v[88:91], v[162:165], v[204:207], v[88:91]
	v_mfma_f32_16x16x32_bf16 v[76:79], v[146:149], v[212:215], v[76:79]
	v_mfma_f32_16x16x32_bf16 v[72:75], v[162:165], v[212:215], v[72:75]
	v_mfma_f32_16x16x32_bf16 v[120:123], v[150:153], v[192:195], v[120:123]
	v_mfma_f32_16x16x32_bf16 v[124:127], v[166:169], v[192:195], v[124:127]
	v_mfma_f32_16x16x32_bf16 v[108:111], v[150:153], v[200:203], v[108:111]
	v_mfma_f32_16x16x32_bf16 v[104:107], v[166:169], v[200:203], v[104:107]
	v_mfma_f32_16x16x32_bf16 v[92:95], v[150:153], v[208:211], v[92:95]
	v_mfma_f32_16x16x32_bf16 v[88:91], v[166:169], v[208:211], v[88:91]
	v_mfma_f32_16x16x32_bf16 v[76:79], v[150:153], v[216:219], v[76:79]
	v_mfma_f32_16x16x32_bf16 v[72:75], v[166:169], v[216:219], v[72:75]
	v_mfma_f32_16x16x32_bf16 v[116:119], v[170:173], v[188:191], v[116:119]
	v_mfma_f32_16x16x32_bf16 v[112:115], v[178:181], v[188:191], v[112:115]
	v_mfma_f32_16x16x32_bf16 v[100:103], v[170:173], v[196:199], v[100:103]
	v_mfma_f32_16x16x32_bf16 v[96:99], v[178:181], v[196:199], v[96:99]
	v_mfma_f32_16x16x32_bf16 v[84:87], v[170:173], v[204:207], v[84:87]
	v_mfma_f32_16x16x32_bf16 v[80:83], v[178:181], v[204:207], v[80:83]
	v_mfma_f32_16x16x32_bf16 v[68:71], v[170:173], v[212:215], v[68:71]
	v_mfma_f32_16x16x32_bf16 v[64:67], v[178:181], v[212:215], v[64:67]
	v_mfma_f32_16x16x32_bf16 v[116:119], v[174:177], v[192:195], v[116:119]
	v_mfma_f32_16x16x32_bf16 v[112:115], v[182:185], v[192:195], v[112:115]
	v_mfma_f32_16x16x32_bf16 v[100:103], v[174:177], v[200:203], v[100:103]
	v_mfma_f32_16x16x32_bf16 v[96:99], v[182:185], v[200:203], v[96:99]
	v_mfma_f32_16x16x32_bf16 v[84:87], v[174:177], v[208:211], v[84:87]
	v_mfma_f32_16x16x32_bf16 v[80:83], v[182:185], v[208:211], v[80:83]
	v_mfma_f32_16x16x32_bf16 v[68:71], v[174:177], v[216:219], v[68:71]
	v_mfma_f32_16x16x32_bf16 v[64:67], v[182:185], v[216:219], v[64:67]
	s_barrier
	s_add_i32 s46, s68, s51
	v_lshl_add_u64 v[220:221], v[220:221], 0, s[12:13]
	s_mov_b32 m0, s46
	ds_read_b128 v[188:191], v160 offset:49152
	ds_read_b128 v[192:195], v160 offset:50176
	ds_read_b128 v[196:199], v160 offset:51200
	ds_read_b128 v[200:203], v160 offset:52224
	ds_read_b128 v[204:207], v160 offset:53248
	ds_read_b128 v[208:211], v160 offset:54272
	ds_read_b128 v[212:215], v160 offset:55296
	ds_read_b128 v[216:219], v160 offset:56320
	global_load_lds_dwordx4 v[220:221], off
	s_add_i32 m0, s46, 0x2000
	s_add_u32 s44, s44, 0x80080
	v_lshl_add_u64 v[220:221], v[222:223], 0, s[12:13]
	s_addc_u32 s45, s45, 0
	s_add_i32 s46, s69, s51
	global_load_lds_dwordx4 v[220:221], off
	v_lshl_add_u64 v[220:221], s[44:45], 0, v[130:131]
	s_mov_b32 m0, s46
	s_nop 0
	global_load_lds_dwordx4 v[220:221], off
	v_lshl_add_u64 v[220:221], s[44:45], 0, v[134:135]
	s_add_i32 m0, s46, 0x2000
	s_nop 0
	global_load_lds_dwordx4 v[220:221], off
	v_lshl_add_u64 v[220:221], v[224:225], 0, s[12:13]
	s_mov_b32 m0, s58
	s_nop 0
	global_load_lds_dwordx4 v[220:221], off
	v_lshl_add_u64 v[220:221], v[228:229], 0, s[12:13]
	s_mov_b32 m0, s59
	s_nop 0
	global_load_lds_dwordx4 v[220:221], off
	s_waitcnt vmcnt(8)
	s_waitcnt lgkmcnt(0)
	s_barrier
	s_waitcnt lgkmcnt(0)
	v_mfma_f32_16x16x32_bf16 v[60:63], v[146:149], v[188:191], v[60:63]
	v_mfma_f32_16x16x32_bf16 v[56:59], v[162:165], v[188:191], v[56:59]
	v_mfma_f32_16x16x32_bf16 v[44:47], v[146:149], v[196:199], v[44:47]
	v_mfma_f32_16x16x32_bf16 v[40:43], v[162:165], v[196:199], v[40:43]
	v_mfma_f32_16x16x32_bf16 v[28:31], v[146:149], v[204:207], v[28:31]
	v_mfma_f32_16x16x32_bf16 v[24:27], v[162:165], v[204:207], v[24:27]
	v_mfma_f32_16x16x32_bf16 v[12:15], v[146:149], v[212:215], v[12:15]
	v_mfma_f32_16x16x32_bf16 v[8:11], v[162:165], v[212:215], v[8:11]
	v_mfma_f32_16x16x32_bf16 v[60:63], v[150:153], v[192:195], v[60:63]
	v_mfma_f32_16x16x32_bf16 v[56:59], v[166:169], v[192:195], v[56:59]
	v_mfma_f32_16x16x32_bf16 v[44:47], v[150:153], v[200:203], v[44:47]
	v_mfma_f32_16x16x32_bf16 v[40:43], v[166:169], v[200:203], v[40:43]
	v_mfma_f32_16x16x32_bf16 v[28:31], v[150:153], v[208:211], v[28:31]
	v_mfma_f32_16x16x32_bf16 v[24:27], v[166:169], v[208:211], v[24:27]
	v_mfma_f32_16x16x32_bf16 v[12:15], v[150:153], v[216:219], v[12:15]
	v_mfma_f32_16x16x32_bf16 v[8:11], v[166:169], v[216:219], v[8:11]
	v_mfma_f32_16x16x32_bf16 v[52:55], v[170:173], v[188:191], v[52:55]
	v_mfma_f32_16x16x32_bf16 v[48:51], v[178:181], v[188:191], v[48:51]
	v_mfma_f32_16x16x32_bf16 v[36:39], v[170:173], v[196:199], v[36:39]
	v_mfma_f32_16x16x32_bf16 v[32:35], v[178:181], v[196:199], v[32:35]
	v_mfma_f32_16x16x32_bf16 v[20:23], v[170:173], v[204:207], v[20:23]
	v_mfma_f32_16x16x32_bf16 v[16:19], v[178:181], v[204:207], v[16:19]
	v_mfma_f32_16x16x32_bf16 v[4:7], v[170:173], v[212:215], v[4:7]
	v_mfma_f32_16x16x32_bf16 v[0:3], v[178:181], v[212:215], v[0:3]
	v_mfma_f32_16x16x32_bf16 v[52:55], v[174:177], v[192:195], v[52:55]
	v_mfma_f32_16x16x32_bf16 v[48:51], v[182:185], v[192:195], v[48:51]
	v_mfma_f32_16x16x32_bf16 v[36:39], v[174:177], v[200:203], v[36:39]
	v_mfma_f32_16x16x32_bf16 v[32:35], v[182:185], v[200:203], v[32:35]
	v_mfma_f32_16x16x32_bf16 v[20:23], v[174:177], v[208:211], v[20:23]
	v_mfma_f32_16x16x32_bf16 v[16:19], v[182:185], v[208:211], v[16:19]
	v_mfma_f32_16x16x32_bf16 v[4:7], v[174:177], v[216:219], v[4:7]
	v_mfma_f32_16x16x32_bf16 v[0:3], v[182:185], v[216:219], v[0:3]
	s_barrier
	s_add_u32 s65, s65, 0x100
	s_addc_u32 s66, s66, 0
	s_add_u32 s42, s42, 0x100
	s_addc_u32 s43, s43, 0
	s_cmp_ge_i32 s67, s57
	s_mov_b32 s44, s67
	s_cbranch_scc0 .LBB0_744
; #define PG8_BAR __builtin_amdgcn_s_barrier()
; template <class Epi, class Sched, bool ALIGN_EPI = false, bool SP2 = false>
; __device__ __forceinline__ void gemm_phase(PG8_LAS unsigned char* lds, const Gemm g, const Sched& S, const Epi& E) {
;     ...
;         if constexpr (ALIGN_EPI) { if (wr == 0) PG8_BAR; }
.LBB0_745:
	s_and_b64 vcc, exec, s[18:19]
	s_cbranch_vccz .LBB0_747
	s_barrier

; template <class Epi, class Sched, bool ALIGN_EPI = false, bool SP2 = false>
; __device__ __forceinline__ void gemm_phase(PG8_LAS unsigned char* lds, const Gemm g, const Sched& S, const Epi& E) {
;     ...
; #pragma unroll
;     for (int a = 0; a < 2; ++a)
; #pragma unroll
;         for (int b = 0; b < 2; ++b)
; #pragma unroll
;             for (int m = 0; m < 4; ++m)
; #pragma unroll
;                 for (int n = 0; n < 2; ++n) acc[a][b][m][n] = (f32x4){0.f, 0.f, 0.f, 0.f};
;     bf16x8 At[4][2], B0[2][2], B1[2][2];
;     const char* cA = (const char*)(g.A + (size_t)cur.g * g.gsA) + (size_t)cur.pm * tstepA; const char* cB = (const char*)(g.Bt + (size_t)cur.g * g.gsB) + (size_t)cur.pn * tstepB;
;     S.a_ready(cur);
;     if constexpr (SP2) {
;         PG8_STAGE(PG8_SB(0, 0), cB, voffB); PG8_STAGE(PG8_SB(0, 1), cB + hstepB, voffB); PG8_STAGE(PG8_SA(0, 0), cA, voffA); PG8_STAGE(PG8_SA(0, 1), cA + hstepA, voffA);
;         if (wr == 1) PG8_BAR;
;         PG8_WAIT_V(2); PG8_BAR;
;         PG8_STAGE(PG8_SB(1, 0), cB + kstep, voffB); PG8_STAGE(PG8_SA(1, 0), cA + kstep, voffA); PG8_STAGE(PG8_SB(1, 1), cB + hstepB + kstep, voffB);
;         PG8_WAIT_V(6); PG8_BAR;
;     } else {
;         PG8_STAGE(PG8_SB(0, 0), cB, voffB); PG8_STAGE(PG8_SA(0, 0), cA, voffA); PG8_STAGE(PG8_SB(0, 1), cB + hstepB, voffB); PG8_STAGE(PG8_SA(0, 1), cA + hstepA, voffA);
;         if (wr == 1) PG8_BAR;
;         PG8_WAIT_V(4); PG8_BAR;
;         PG8_STAGE(PG8_SB(1, 0), cB + kstep, voffB); PG8_STAGE(PG8_SA(1, 0), cA + kstep, voffA); PG8_STAGE(PG8_SB(1, 1), cB + hstepB + kstep, voffB);
;         PG8_WAIT_V(6); PG8_BAR;
;     }
;     for (;;) {
;         const bool has_next = S.next(ui + 1, nxt);
;         const char* nA = has_next ? (const char*)(g.A + (size_t)nxt.g * g.gsA) + (size_t)nxt.pm * tstepA : cA; const char* nB = has_next ? (const char*)(g.Bt + (size_t)nxt.g * g.gsB) + (size_t)nxt.pn * tstepB : cB;
;         for (int t = 0; t < nt; t += 2) {
;             if constexpr (Epi::MIDK) { if (t == (nt >> 1)) { asm volatile("s_waitcnt vmcnt(0)" ::: "memory"); E.mid(acc, cur, wr, wc, fr, fq); asm volatile("s_waitcnt vmcnt(0)" ::: "memory"); } }
;             const bool last = (t == nt - 2);
;             const char* a1 = cA + (size_t)(t + 1) * kstep;
;             const char* a2 = last ? nA : cA + (size_t)(t + 2) * kstep; const char* b2 = last ? nB : cB + (size_t)(t + 2) * kstep;
.LBB0_827:
	s_ashr_i32 s35, s34, 31
	s_lshl_b64 s[36:37], s[34:35], 20
	s_add_u32 s36, s47, s36
	s_addc_u32 s37, s48, s37
	s_ashr_i32 s31, s30, 31
	s_lshl_b64 s[38:39], s[30:31], 20
	s_add_u32 s38, s49, s38
	v_mov_b32_e32 v123, 0
	s_addc_u32 s39, s50, s39
	s_andn2_b64 vcc, exec, s[18:19]
	v_mov_b32_e32 v122, v123
	v_mov_b32_e32 v121, v123
	v_mov_b32_e32 v120, v123
	v_mov_b32_e32 v127, v123
	v_mov_b32_e32 v126, v123
	v_mov_b32_e32 v125, v123
	v_mov_b32_e32 v124, v123
	v_mov_b32_e32 v111, v123
	v_mov_b32_e32 v110, v123
	v_mov_b32_e32 v109, v123
	v_mov_b32_e32 v108, v123
	v_mov_b32_e32 v107, v123
	v_mov_b32_e32 v106, v123
	v_mov_b32_e32 v105, v123
	v_mov_b32_e32 v104, v123
	v_mov_b32_e32 v95, v123
	v_mov_b32_e32 v94, v123
	v_mov_b32_e32 v93, v123
	v_mov_b32_e32 v92, v123
	v_mov_b32_e32 v91, v123
	v_mov_b32_e32 v90, v123
	v_mov_b32_e32 v89, v123
	v_mov_b32_e32 v88, v123
	v_mov_b32_e32 v79, v123
	v_mov_b32_e32 v78, v123
	v_mov_b32_e32 v77, v123
	v_mov_b32_e32 v76, v123
	v_mov_b32_e32 v75, v123
	v_mov_b32_e32 v74, v123
	v_mov_b32_e32 v73, v123
	v_mov_b32_e32 v72, v123
	v_mov_b32_e32 v119, v123
	v_mov_b32_e32 v118, v123
	v_mov_b32_e32 v117, v123
	v_mov_b32_e32 v116, v123
	v_mov_b32_e32 v115, v123
	v_mov_b32_e32 v114, v123
	v_mov_b32_e32 v113, v123
	v_mov_b32_e32 v112, v123
	v_mov_b32_e32 v103, v123
	v_mov_b32_e32 v102, v123
	v_mov_b32_e32 v101, v123
	v_mov_b32_e32 v100, v123
	v_mov_b32_e32 v99, v123
	v_mov_b32_e32 v98, v123
	v_mov_b32_e32 v97, v123
	v_mov_b32_e32 v96, v123
	v_mov_b32_e32 v87, v123
	v_mov_b32_e32 v86, v123
	v_mov_b32_e32 v85, v123
	v_mov_b32_e32 v84, v123
	v_mov_b32_e32 v83, v123
	v_mov_b32_e32 v82, v123
	v_mov_b32_e32 v81, v123
	v_mov_b32_e32 v80, v123
	v_mov_b32_e32 v71, v123
	v_mov_b32_e32 v70, v123
	v_mov_b32_e32 v69, v123
	v_mov_b32_e32 v68, v123
	v_mov_b32_e32 v67, v123
	v_mov_b32_e32 v66, v123
	v_mov_b32_e32 v65, v123
	v_mov_b32_e32 v64, v123
	v_mov_b32_e32 v63, v123
	v_mov_b32_e32 v62, v123
	v_mov_b32_e32 v61, v123
	v_mov_b32_e32 v60, v123
	v_mov_b32_e32 v59, v123
	v_mov_b32_e32 v58, v123
	v_mov_b32_e32 v57, v123
	v_mov_b32_e32 v56, v123
	v_mov_b32_e32 v47, v123
	v_mov_b32_e32 v46, v123
	v_mov_b32_e32 v45, v123
	v_mov_b32_e32 v44, v123
	v_mov_b32_e32 v43, v123
	v_mov_b32_e32 v42, v123
	v_mov_b32_e32 v41, v123
	v_mov_b32_e32 v40, v123
	v_mov_b32_e32 v31, v123
	v_mov_b32_e32 v30, v123
	v_mov_b32_e32 v29, v123
	v_mov_b32_e32 v28, v123
	v_mov_b32_e32 v27, v123
	v_mov_b32_e32 v26, v123
	v_mov_b32_e32 v25, v123
	v_mov_b32_e32 v24, v123
	v_mov_b32_e32 v15, v123
	v_mov_b32_e32 v14, v123
	v_mov_b32_e32 v13, v123
	v_mov_b32_e32 v12, v123
	v_mov_b32_e32 v11, v123
	v_mov_b32_e32 v10, v123
	v_mov_b32_e32 v9, v123
	v_mov_b32_e32 v8, v123
	v_mov_b32_e32 v55, v123
	v_mov_b32_e32 v54, v123
	v_mov_b32_e32 v53, v123
	v_mov_b32_e32 v52, v123
	v_mov_b32_e32 v51, v123
	v_mov_b32_e32 v50, v123
	v_mov_b32_e32 v49, v123
	v_mov_b32_e32 v48, v123
	v_mov_b32_e32 v39, v123
	v_mov_b32_e32 v38, v123
	v_mov_b32_e32 v37, v123
	v_mov_b32_e32 v36, v123
	v_mov_b32_e32 v35, v123
	v_mov_b32_e32 v34, v123
	v_mov_b32_e32 v33, v123
	v_mov_b32_e32 v32, v123
	v_mov_b32_e32 v23, v123
	v_mov_b32_e32 v22, v123
	v_mov_b32_e32 v21, v123
	v_mov_b32_e32 v20, v123
	v_mov_b32_e32 v19, v123
	v_mov_b32_e32 v18, v123
	v_mov_b32_e32 v17, v123
	v_mov_b32_e32 v16, v123
	v_mov_b32_e32 v7, v123
	v_mov_b32_e32 v6, v123
	v_mov_b32_e32 v5, v123
	v_mov_b32_e32 v4, v123
	v_mov_b32_e32 v3, v123
	v_mov_b32_e32 v2, v123
	v_mov_b32_e32 v1, v123
	v_mov_b32_e32 v0, v123
	s_cbranch_vccnz .LBB0_830
	s_and_b64 s[44:45], s[6:7], exec
	s_cselect_b32 s31, s37, s43
	s_cselect_b32 s35, s36, s42
	s_cselect_b32 s67, s39, s41
	s_cselect_b32 s68, s38, s40
	s_add_u32 s69, s40, 0x100
	s_addc_u32 s70, s41, 0
	s_add_u32 s40, s42, 0x80080
	s_addc_u32 s41, s43, 0
	s_mov_b32 s42, 0
.LBB0_829:
	ds_read_b128 v[144:147], v155
	ds_read_b128 v[148:151], v155 offset:1024
	ds_read_b128 v[160:163], v155 offset:2048
	ds_read_b128 v[164:167], v155 offset:3072
	ds_read_b128 v[168:171], v156
	ds_read_b128 v[172:175], v156 offset:1024
	ds_read_b128 v[176:179], v156 offset:2048
	ds_read_b128 v[180:183], v156 offset:3072
	s_add_i32 s71, s42, 2
	s_add_u32 s43, s40, 0xfff80080
	s_addc_u32 s44, s41, -1
	s_cmp_eq_u32 s60, s42
	s_cselect_b32 s42, s68, s69
	s_cselect_b32 s45, s31, s44
	s_cselect_b32 s44, s35, s43
	s_cselect_b32 s43, s67, s70
	v_lshl_add_u64 v[184:185], s[40:41], 0, v[138:139]
	s_add_i32 m0, s52, 0xc000
	ds_read_b128 v[188:191], v157
	ds_read_b128 v[192:195], v157 offset:1024
	ds_read_b128 v[196:199], v157 offset:2048
	ds_read_b128 v[200:203], v157 offset:3072
	ds_read_b128 v[204:207], v157 offset:4096
	ds_read_b128 v[208:211], v157 offset:5120
	ds_read_b128 v[212:215], v157 offset:6144
	ds_read_b128 v[216:219], v157 offset:7168
	global_load_lds_dwordx4 v[184:185], off
	v_lshl_add_u64 v[184:185], s[40:41], 0, v[136:137]
	s_add_i32 m0, s52, 0xe000
	s_nop 0
	global_load_lds_dwordx4 v[184:185], off
	s_waitcnt vmcnt(8)
	s_waitcnt lgkmcnt(0)
	s_barrier
; #define PG8_STAGE(bufoff, gbase, voff) do { _Pragma("unroll") for (int _i = 0; _i < 2; ++_i) \
;         __builtin_amdgcn_global_load_lds((const unsigned*)((const char*)(gbase) + (voff)[_i]), (PG8_LAS unsigned*)(lds + (bufoff) + ldsw + _i * 8192), 16, 0, 0); } while (0)
; #define PG8_LDA(dst, b, h) do { _Pragma("unroll") for (int m = 0; m < 4; ++m) _Pragma("unroll") for (int k = 0; k < 2; ++k) dst[m][k] = *(const PG8_LAS bf16x8*)(lds + PG8_SA(b, h) + aoff + m * 2048 + k * 1024); } while (0)
; #define PG8_MMA(ai, bj, At, Bt) do { __builtin_amdgcn_s_setprio(1); _Pragma("unroll") for (int m = 0; m < 4; ++m) _Pragma("unroll") for (int n = 0; n < 2; ++n) _Pragma("unroll") for (int k = 0; k < 2; ++k) \
;         acc[ai][bj][m][n] = __builtin_amdgcn_mfma_f32_16x16x32_bf16(Bt[n][k], At[m][k], acc[ai][bj][m][n], 0, 0, 0); __builtin_amdgcn_s_setprio(0); } while (0)
; #define PG8_WAIT_V(n) asm volatile("s_waitcnt vmcnt(" #n ")" ::: "memory")
; #define PG8_WAIT_L(n) asm volatile("s_waitcnt lgkmcnt(" #n ")" ::: "memory")
; #define PG8_BAR __builtin_amdgcn_s_barrier()
; #define PG8_SCHED __builtin_amdgcn_sched_barrier(0)
; template <class Epi, class Sched, bool ALIGN_EPI = false, bool SP2 = false>
; __device__ __forceinline__ void gemm_phase(PG8_LAS unsigned char* lds, const Gemm g, const Sched& S, const Epi& E) {
;     ...
;             PG8_WAIT_V(8); PG8_WAIT_L(0); PG8_BAR; PG8_MMA(0, 0, At, B0); PG8_MMA(0, 1, At, B1); PG8_BAR; PG8_SCHED;
;             PG8_LDA(At, 0, 1); PG8_STAGE(PG8_SB(0, 0), b2, voffB); PG8_STAGE(PG8_SB(0, 1), b2 + hstepB, voffB); PG8_STAGE(PG8_SA(0, 0), a2, voffA);
;             PG8_WAIT_V(8); PG8_WAIT_L(0); PG8_BAR; PG8_MMA(1, 0, At, B0); PG8_MMA(1, 1, At, B1); PG8_BAR; PG8_SCHED;
	s_waitcnt lgkmcnt(0)
	v_mfma_f32_16x16x32_bf16 v[120:123], v[144:147], v[188:191], v[120:123]
	v_mfma_f32_16x16x32_bf16 v[124:127], v[160:163], v[188:191], v[124:127]
	v_mfma_f32_16x16x32_bf16 v[108:111], v[144:147], v[196:199], v[108:111]
	v_mfma_f32_16x16x32_bf16 v[104:107], v[160:163], v[196:199], v[104:107]
	v_mfma_f32_16x16x32_bf16 v[92:95], v[144:147], v[204:207], v[92:95]
	v_mfma_f32_16x16x32_bf16 v[88:91], v[160:163], v[204:207], v[88:91]
	v_mfma_f32_16x16x32_bf16 v[76:79], v[144:147], v[212:215], v[76:79]
	v_mfma_f32_16x16x32_bf16 v[72:75], v[160:163], v[212:215], v[72:75]
	v_mfma_f32_16x16x32_bf16 v[120:123], v[148:151], v[192:195], v[120:123]
	v_mfma_f32_16x16x32_bf16 v[124:127], v[164:167], v[192:195], v[124:127]
	v_mfma_f32_16x16x32_bf16 v[108:111], v[148:151], v[200:203], v[108:111]
	v_mfma_f32_16x16x32_bf16 v[104:107], v[164:167], v[200:203], v[104:107]
	v_mfma_f32_16x16x32_bf16 v[92:95], v[148:151], v[208:211], v[92:95]
	v_mfma_f32_16x16x32_bf16 v[88:91], v[164:167], v[208:211], v[88:91]
	v_mfma_f32_16x16x32_bf16 v[76:79], v[148:151], v[216:219], v[76:79]
	v_mfma_f32_16x16x32_bf16 v[72:75], v[164:167], v[216:219], v[72:75]
	v_mfma_f32_16x16x32_bf16 v[116:119], v[168:171], v[188:191], v[116:119]
	v_mfma_f32_16x16x32_bf16 v[112:115], v[176:179], v[188:191], v[112:115]
	v_mfma_f32_16x16x32_bf16 v[100:103], v[168:171], v[196:199], v[100:103]
	v_mfma_f32_16x16x32_bf16 v[96:99], v[176:179], v[196:199], v[96:99]
	v_mfma_f32_16x16x32_bf16 v[84:87], v[168:171], v[204:207], v[84:87]
	v_mfma_f32_16x16x32_bf16 v[80:83], v[176:179], v[204:207], v[80:83]
	v_mfma_f32_16x16x32_bf16 v[68:71], v[168:171], v[212:215], v[68:71]
	v_mfma_f32_16x16x32_bf16 v[64:67], v[176:179], v[212:215], v[64:67]
	v_mfma_f32_16x16x32_bf16 v[116:119], v[172:175], v[192:195], v[116:119]
	v_mfma_f32_16x16x32_bf16 v[112:115], v[180:183], v[192:195], v[112:115]
	v_mfma_f32_16x16x32_bf16 v[100:103], v[172:175], v[200:203], v[100:103]
	v_mfma_f32_16x16x32_bf16 v[96:99], v[180:183], v[200:203], v[96:99]
	v_mfma_f32_16x16x32_bf16 v[84:87], v[172:175], v[208:211], v[84:87]
	v_mfma_f32_16x16x32_bf16 v[80:83], v[180:183], v[208:211], v[80:83]
	v_mfma_f32_16x16x32_bf16 v[68:71], v[172:175], v[216:219], v[68:71]
	v_mfma_f32_16x16x32_bf16 v[64:67], v[180:183], v[216:219], v[64:67]
	s_barrier
	s_add_i32 s72, s61, s51
	v_lshl_add_u64 v[184:185], s[42:43], 0, v[132:133]
	s_mov_b32 m0, s72
	ds_read_b128 v[188:191], v157 offset:16384
	ds_read_b128 v[192:195], v157 offset:17408
	ds_read_b128 v[196:199], v157 offset:18432
	ds_read_b128 v[200:203], v157 offset:19456
	ds_read_b128 v[204:207], v157 offset:20480
	ds_read_b128 v[208:211], v157 offset:21504
	ds_read_b128 v[212:215], v157 offset:22528
	ds_read_b128 v[216:219], v157 offset:23552
	global_load_lds_dwordx4 v[184:185], off
	s_add_i32 m0, s72, 0x2000
	s_add_u32 s72, s42, 0x80000
	v_lshl_add_u64 v[220:221], s[42:43], 0, v[128:129]
	s_addc_u32 s73, s43, 0
	s_add_i32 s74, s62, s51
	global_load_lds_dwordx4 v[220:221], off
	v_lshl_add_u64 v[222:223], s[72:73], 0, v[132:133]
	s_mov_b32 m0, s74
	v_lshl_add_u64 v[224:225], s[44:45], 0, v[130:131]
	global_load_lds_dwordx4 v[222:223], off
	v_lshl_add_u64 v[222:223], s[72:73], 0, v[128:129]
	s_add_i32 m0, s74, 0x2000
	s_nop 0
	global_load_lds_dwordx4 v[222:223], off
	v_lshl_add_u64 v[222:223], s[44:45], 0, v[134:135]
	s_mov_b32 m0, s52
	s_nop 0
	global_load_lds_dwordx4 v[222:223], off
	s_mov_b32 m0, s53
	s_nop 0
	global_load_lds_dwordx4 v[224:225], off
	s_waitcnt vmcnt(8)
	s_waitcnt lgkmcnt(0)
	s_barrier
	s_waitcnt lgkmcnt(0)
	v_mfma_f32_16x16x32_bf16 v[60:63], v[144:147], v[188:191], v[60:63]
	v_mfma_f32_16x16x32_bf16 v[56:59], v[160:163], v[188:191], v[56:59]
	v_mfma_f32_16x16x32_bf16 v[44:47], v[144:147], v[196:199], v[44:47]
	v_mfma_f32_16x16x32_bf16 v[40:43], v[160:163], v[196:199], v[40:43]
	v_mfma_f32_16x16x32_bf16 v[28:31], v[144:147], v[204:207], v[28:31]
	v_mfma_f32_16x16x32_bf16 v[24:27], v[160:163], v[204:207], v[24:27]
	v_mfma_f32_16x16x32_bf16 v[12:15], v[144:147], v[212:215], v[12:15]
	v_mfma_f32_16x16x32_bf16 v[8:11], v[160:163], v[212:215], v[8:11]
	v_mfma_f32_16x16x32_bf16 v[60:63], v[148:151], v[192:195], v[60:63]
	v_mfma_f32_16x16x32_bf16 v[56:59], v[164:167], v[192:195], v[56:59]
	v_mfma_f32_16x16x32_bf16 v[44:47], v[148:151], v[200:203], v[44:47]
	v_mfma_f32_16x16x32_bf16 v[40:43], v[164:167], v[200:203], v[40:43]
	v_mfma_f32_16x16x32_bf16 v[28:31], v[148:151], v[208:211], v[28:31]
	v_mfma_f32_16x16x32_bf16 v[24:27], v[164:167], v[208:211], v[24:27]
	v_mfma_f32_16x16x32_bf16 v[12:15], v[148:151], v[216:219], v[12:15]
	v_mfma_f32_16x16x32_bf16 v[8:11], v[164:167], v[216:219], v[8:11]
	v_mfma_f32_16x16x32_bf16 v[52:55], v[168:171], v[188:191], v[52:55]
	v_mfma_f32_16x16x32_bf16 v[48:51], v[176:179], v[188:191], v[48:51]
	v_mfma_f32_16x16x32_bf16 v[36:39], v[168:171], v[196:199], v[36:39]
	v_mfma_f32_16x16x32_bf16 v[32:35], v[176:179], v[196:199], v[32:35]
	v_mfma_f32_16x16x32_bf16 v[20:23], v[168:171], v[204:207], v[20:23]
	v_mfma_f32_16x16x32_bf16 v[16:19], v[176:179], v[204:207], v[16:19]
	v_mfma_f32_16x16x32_bf16 v[4:7], v[168:171], v[212:215], v[4:7]
	v_mfma_f32_16x16x32_bf16 v[0:3], v[176:179], v[212:215], v[0:3]
	v_mfma_f32_16x16x32_bf16 v[52:55], v[172:175], v[192:195], v[52:55]
	v_mfma_f32_16x16x32_bf16 v[48:51], v[180:183], v[192:195], v[48:51]
	v_mfma_f32_16x16x32_bf16 v[36:39], v[172:175], v[200:203], v[36:39]
	v_mfma_f32_16x16x32_bf16 v[32:35], v[180:183], v[200:203], v[32:35]
	v_mfma_f32_16x16x32_bf16 v[20:23], v[172:175], v[208:211], v[20:23]
	v_mfma_f32_16x16x32_bf16 v[16:19], v[180:183], v[208:211], v[16:19]
	v_mfma_f32_16x16x32_bf16 v[4:7], v[172:175], v[216:219], v[4:7]
	v_mfma_f32_16x16x32_bf16 v[0:3], v[180:183], v[216:219], v[0:3]
	s_barrier
; #define PG8_STAGE(bufoff, gbase, voff) do { _Pragma("unroll") for (int _i = 0; _i < 2; ++_i) \
;         __builtin_amdgcn_global_load_lds((const unsigned*)((const char*)(gbase) + (voff)[_i]), (PG8_LAS unsigned*)(lds + (bufoff) + ldsw + _i * 8192), 16, 0, 0); } while (0)
; #define PG8_LDA(dst, b, h) do { _Pragma("unroll") for (int m = 0; m < 4; ++m) _Pragma("unroll") for (int k = 0; k < 2; ++k) dst[m][k] = *(const PG8_LAS bf16x8*)(lds + PG8_SA(b, h) + aoff + m * 2048 + k * 1024); } while (0)
; #define PG8_LDB(dst, b, h) do { _Pragma("unroll") for (int n = 0; n < 2; ++n) _Pragma("unroll") for (int k = 0; k < 2; ++k) dst[n][k] = *(const PG8_LAS bf16x8*)(lds + PG8_SB(b, h) + boff + n * 2048 + k * 1024); } while (0)
; #define PG8_MMA(ai, bj, At, Bt) do { __builtin_amdgcn_s_setprio(1); _Pragma("unroll") for (int m = 0; m < 4; ++m) _Pragma("unroll") for (int n = 0; n < 2; ++n) _Pragma("unroll") for (int k = 0; k < 2; ++k) \
;         acc[ai][bj][m][n] = __builtin_amdgcn_mfma_f32_16x16x32_bf16(Bt[n][k], At[m][k], acc[ai][bj][m][n], 0, 0, 0); __builtin_amdgcn_s_setprio(0); } while (0)
; #define PG8_WAIT_V(n) asm volatile("s_waitcnt vmcnt(" #n ")" ::: "memory")
; #define PG8_WAIT_L(n) asm volatile("s_waitcnt lgkmcnt(" #n ")" ::: "memory")
; #define PG8_BAR __builtin_amdgcn_s_barrier()
; #define PG8_SCHED __builtin_amdgcn_sched_barrier(0)
; template <class Epi, class Sched, bool ALIGN_EPI = false, bool SP2 = false>
; __device__ __forceinline__ void gemm_phase(PG8_LAS unsigned char* lds, const Gemm g, const Sched& S, const Epi& E) {
;     ...
;             PG8_LDB(B0, 1, 0); PG8_LDB(B1, 1, 1); PG8_SCHED; PG8_LDA(At, 1, 0); PG8_STAGE(PG8_SA(0, 1), a2 + hstepA, voffA);
;             PG8_WAIT_V(8); PG8_WAIT_L(0); PG8_BAR; PG8_MMA(0, 0, At, B0); PG8_MMA(0, 1, At, B1); PG8_BAR; PG8_SCHED;
;             PG8_LDA(At, 1, 1); PG8_STAGE(PG8_SB(1, 0), b3, voffB); PG8_STAGE(PG8_SB(1, 1), b3 + hstepB, voffB); PG8_STAGE(PG8_SA(1, 0), a3, voffA);
;             PG8_WAIT_V(8); PG8_WAIT_L(0); PG8_BAR; PG8_MMA(1, 0, At, B0); PG8_MMA(1, 1, At, B1); PG8_BAR; PG8_SCHED;
	s_add_i32 s72, 0, 0x18000
	v_add_u32_e32 v159, s72, v153
	s_add_i32 s73, 0, 0x1c000
	ds_read_b128 v[144:147], v159
	ds_read_b128 v[148:151], v159 offset:1024
	ds_read_b128 v[160:163], v159 offset:2048
	ds_read_b128 v[164:167], v159 offset:3072
	v_add_u32_e32 v159, s73, v153
	ds_read_b128 v[168:171], v159
	ds_read_b128 v[172:175], v159 offset:1024
	ds_read_b128 v[176:179], v159 offset:2048
	ds_read_b128 v[180:183], v159 offset:3072
	s_add_u32 s44, s44, 0x80000
	s_addc_u32 s45, s45, 0
	s_mov_b32 m0, s54
	v_lshl_add_u64 v[228:229], s[44:45], 0, v[134:135]
	ds_read_b128 v[188:191], v157 offset:32768
	ds_read_b128 v[192:195], v157 offset:33792
	ds_read_b128 v[196:199], v157 offset:34816
	ds_read_b128 v[200:203], v157 offset:35840
	ds_read_b128 v[204:207], v157 offset:36864
	ds_read_b128 v[208:211], v157 offset:37888
	ds_read_b128 v[212:215], v157 offset:38912
	ds_read_b128 v[216:219], v157 offset:39936
	global_load_lds_dwordx4 v[228:229], off
	v_lshl_add_u64 v[228:229], s[44:45], 0, v[130:131]
	s_mov_b32 m0, s55
	s_nop 0
	global_load_lds_dwordx4 v[228:229], off
	s_waitcnt vmcnt(8)
	s_waitcnt lgkmcnt(0)
	s_barrier
	s_waitcnt lgkmcnt(0)
	v_mfma_f32_16x16x32_bf16 v[120:123], v[144:147], v[188:191], v[120:123]
	v_mfma_f32_16x16x32_bf16 v[124:127], v[160:163], v[188:191], v[124:127]
	v_mfma_f32_16x16x32_bf16 v[108:111], v[144:147], v[196:199], v[108:111]
	v_mfma_f32_16x16x32_bf16 v[104:107], v[160:163], v[196:199], v[104:107]
	v_mfma_f32_16x16x32_bf16 v[92:95], v[144:147], v[204:207], v[92:95]
	v_mfma_f32_16x16x32_bf16 v[88:91], v[160:163], v[204:207], v[88:91]
	v_mfma_f32_16x16x32_bf16 v[76:79], v[144:147], v[212:215], v[76:79]
	v_mfma_f32_16x16x32_bf16 v[72:75], v[160:163], v[212:215], v[72:75]
	v_mfma_f32_16x16x32_bf16 v[120:123], v[148:151], v[192:195], v[120:123]
	v_mfma_f32_16x16x32_bf16 v[124:127], v[164:167], v[192:195], v[124:127]
	v_mfma_f32_16x16x32_bf16 v[108:111], v[148:151], v[200:203], v[108:111]
	v_mfma_f32_16x16x32_bf16 v[104:107], v[164:167], v[200:203], v[104:107]
	v_mfma_f32_16x16x32_bf16 v[92:95], v[148:151], v[208:211], v[92:95]
	v_mfma_f32_16x16x32_bf16 v[88:91], v[164:167], v[208:211], v[88:91]
	v_mfma_f32_16x16x32_bf16 v[76:79], v[148:151], v[216:219], v[76:79]
	v_mfma_f32_16x16x32_bf16 v[72:75], v[164:167], v[216:219], v[72:75]
	v_mfma_f32_16x16x32_bf16 v[116:119], v[168:171], v[188:191], v[116:119]
	v_mfma_f32_16x16x32_bf16 v[112:115], v[176:179], v[188:191], v[112:115]
	v_mfma_f32_16x16x32_bf16 v[100:103], v[168:171], v[196:199], v[100:103]
	v_mfma_f32_16x16x32_bf16 v[96:99], v[176:179], v[196:199], v[96:99]
	v_mfma_f32_16x16x32_bf16 v[84:87], v[168:171], v[204:207], v[84:87]
	v_mfma_f32_16x16x32_bf16 v[80:83], v[176:179], v[204:207], v[80:83]
	v_mfma_f32_16x16x32_bf16 v[68:71], v[168:171], v[212:215], v[68:71]
	v_mfma_f32_16x16x32_bf16 v[64:67], v[176:179], v[212:215], v[64:67]
	v_mfma_f32_16x16x32_bf16 v[116:119], v[172:175], v[192:195], v[116:119]
	v_mfma_f32_16x16x32_bf16 v[112:115], v[180:183], v[192:195], v[112:115]
	v_mfma_f32_16x16x32_bf16 v[100:103], v[172:175], v[200:203], v[100:103]
	v_mfma_f32_16x16x32_bf16 v[96:99], v[180:183], v[200:203], v[96:99]
	v_mfma_f32_16x16x32_bf16 v[84:87], v[172:175], v[208:211], v[84:87]
	v_mfma_f32_16x16x32_bf16 v[80:83], v[180:183], v[208:211], v[80:83]
	v_mfma_f32_16x16x32_bf16 v[68:71], v[172:175], v[216:219], v[68:71]
	v_mfma_f32_16x16x32_bf16 v[64:67], v[180:183], v[216:219], v[64:67]
	s_barrier
	s_add_i32 s44, s72, s51
	v_lshl_add_u64 v[184:185], v[184:185], 0, s[16:17]
	s_mov_b32 m0, s44
	ds_read_b128 v[188:191], v157 offset:49152
	ds_read_b128 v[192:195], v157 offset:50176
	ds_read_b128 v[196:199], v157 offset:51200
	ds_read_b128 v[200:203], v157 offset:52224
	ds_read_b128 v[204:207], v157 offset:53248
	ds_read_b128 v[208:211], v157 offset:54272
	ds_read_b128 v[212:215], v157 offset:55296
	ds_read_b128 v[216:219], v157 offset:56320
	global_load_lds_dwordx4 v[184:185], off
	s_add_i32 m0, s44, 0x2000
	s_add_u32 s42, s42, 0x80080
	v_lshl_add_u64 v[184:185], v[220:221], 0, s[16:17]
	s_addc_u32 s43, s43, 0
	s_add_i32 s44, s73, s51
	global_load_lds_dwordx4 v[184:185], off
	v_lshl_add_u64 v[184:185], s[42:43], 0, v[132:133]
	s_mov_b32 m0, s44
	s_nop 0
	global_load_lds_dwordx4 v[184:185], off
	v_lshl_add_u64 v[184:185], s[42:43], 0, v[128:129]
	s_add_i32 m0, s44, 0x2000
	s_nop 0
	global_load_lds_dwordx4 v[184:185], off
	v_lshl_add_u64 v[184:185], v[222:223], 0, s[16:17]
	s_mov_b32 m0, s57
	s_nop 0
	global_load_lds_dwordx4 v[184:185], off
	v_lshl_add_u64 v[184:185], v[224:225], 0, s[16:17]
	s_mov_b32 m0, s58
	s_nop 0
	global_load_lds_dwordx4 v[184:185], off
	s_waitcnt vmcnt(8)
	s_waitcnt lgkmcnt(0)
	s_barrier
	s_waitcnt lgkmcnt(0)
	v_mfma_f32_16x16x32_bf16 v[60:63], v[144:147], v[188:191], v[60:63]
	v_mfma_f32_16x16x32_bf16 v[56:59], v[160:163], v[188:191], v[56:59]
	v_mfma_f32_16x16x32_bf16 v[44:47], v[144:147], v[196:199], v[44:47]
	v_mfma_f32_16x16x32_bf16 v[40:43], v[160:163], v[196:199], v[40:43]
	v_mfma_f32_16x16x32_bf16 v[28:31], v[144:147], v[204:207], v[28:31]
	v_mfma_f32_16x16x32_bf16 v[24:27], v[160:163], v[204:207], v[24:27]
	v_mfma_f32_16x16x32_bf16 v[12:15], v[144:147], v[212:215], v[12:15]
	v_mfma_f32_16x16x32_bf16 v[8:11], v[160:163], v[212:215], v[8:11]
	v_mfma_f32_16x16x32_bf16 v[60:63], v[148:151], v[192:195], v[60:63]
	v_mfma_f32_16x16x32_bf16 v[56:59], v[164:167], v[192:195], v[56:59]
	v_mfma_f32_16x16x32_bf16 v[44:47], v[148:151], v[200:203], v[44:47]
	v_mfma_f32_16x16x32_bf16 v[40:43], v[164:167], v[200:203], v[40:43]
	v_mfma_f32_16x16x32_bf16 v[28:31], v[148:151], v[208:211], v[28:31]
	v_mfma_f32_16x16x32_bf16 v[24:27], v[164:167], v[208:211], v[24:27]
	v_mfma_f32_16x16x32_bf16 v[12:15], v[148:151], v[216:219], v[12:15]
	v_mfma_f32_16x16x32_bf16 v[8:11], v[164:167], v[216:219], v[8:11]
	v_mfma_f32_16x16x32_bf16 v[52:55], v[168:171], v[188:191], v[52:55]
	v_mfma_f32_16x16x32_bf16 v[48:51], v[176:179], v[188:191], v[48:51]
	v_mfma_f32_16x16x32_bf16 v[36:39], v[168:171], v[196:199], v[36:39]
	v_mfma_f32_16x16x32_bf16 v[32:35], v[176:179], v[196:199], v[32:35]
	v_mfma_f32_16x16x32_bf16 v[20:23], v[168:171], v[204:207], v[20:23]
	v_mfma_f32_16x16x32_bf16 v[16:19], v[176:179], v[204:207], v[16:19]
	v_mfma_f32_16x16x32_bf16 v[4:7], v[168:171], v[212:215], v[4:7]
	v_mfma_f32_16x16x32_bf16 v[0:3], v[176:179], v[212:215], v[0:3]
	v_mfma_f32_16x16x32_bf16 v[52:55], v[172:175], v[192:195], v[52:55]
	v_mfma_f32_16x16x32_bf16 v[48:51], v[180:183], v[192:195], v[48:51]
	v_mfma_f32_16x16x32_bf16 v[36:39], v[172:175], v[200:203], v[36:39]
	v_mfma_f32_16x16x32_bf16 v[32:35], v[180:183], v[200:203], v[32:35]
	v_mfma_f32_16x16x32_bf16 v[20:23], v[172:175], v[208:211], v[20:23]
	v_mfma_f32_16x16x32_bf16 v[16:19], v[180:183], v[208:211], v[16:19]
	v_mfma_f32_16x16x32_bf16 v[4:7], v[172:175], v[216:219], v[4:7]
	v_mfma_f32_16x16x32_bf16 v[0:3], v[180:183], v[216:219], v[0:3]
	s_barrier
	s_add_u32 s69, s69, 0x100
	s_addc_u32 s70, s70, 0
	s_add_u32 s40, s40, 0x100
	s_addc_u32 s41, s41, 0
	s_cmp_ge_i32 s71, s56
	s_mov_b32 s42, s71
	s_cbranch_scc0 .LBB0_829
; #define PG8_BAR __builtin_amdgcn_s_barrier()
; template <class Epi, class Sched, bool ALIGN_EPI = false, bool SP2 = false>
; __device__ __forceinline__ void gemm_phase(PG8_LAS unsigned char* lds, const Gemm g, const Sched& S, const Epi& E) {
;     ...
;         if constexpr (ALIGN_EPI) { if (wr == 0) PG8_BAR; }
.LBB0_830:
	s_and_b64 vcc, exec, s[20:21]
	s_cbranch_vccz .LBB0_832
	s_barrier

; template <class Epi, class Sched, bool ALIGN_EPI = false, bool SP2 = false>
; __device__ __forceinline__ void gemm_phase(PG8_LAS unsigned char* lds, const Gemm g, const Sched& S, const Epi& E) {
;     ...
; #pragma unroll
;     for (int a = 0; a < 2; ++a)
; #pragma unroll
;         for (int b = 0; b < 2; ++b)
; #pragma unroll
;             for (int m = 0; m < 4; ++m)
; #pragma unroll
;                 for (int n = 0; n < 2; ++n) acc[a][b][m][n] = (f32x4){0.f, 0.f, 0.f, 0.f};
;     bf16x8 At[4][2], B0[2][2], B1[2][2];
;     const char* cA = (const char*)(g.A + (size_t)cur.g * g.gsA) + (size_t)cur.pm * tstepA; const char* cB = (const char*)(g.Bt + (size_t)cur.g * g.gsB) + (size_t)cur.pn * tstepB;
;     S.a_ready(cur);
;     if constexpr (SP2) {
;         PG8_STAGE(PG8_SB(0, 0), cB, voffB); PG8_STAGE(PG8_SB(0, 1), cB + hstepB, voffB); PG8_STAGE(PG8_SA(0, 0), cA, voffA); PG8_STAGE(PG8_SA(0, 1), cA + hstepA, voffA);
;         if (wr == 1) PG8_BAR;
;         PG8_WAIT_V(2); PG8_BAR;
;         PG8_STAGE(PG8_SB(1, 0), cB + kstep, voffB); PG8_STAGE(PG8_SA(1, 0), cA + kstep, voffA); PG8_STAGE(PG8_SB(1, 1), cB + hstepB + kstep, voffB);
;         PG8_WAIT_V(6); PG8_BAR;
;     } else {
;         PG8_STAGE(PG8_SB(0, 0), cB, voffB); PG8_STAGE(PG8_SA(0, 0), cA, voffA); PG8_STAGE(PG8_SB(0, 1), cB + hstepB, voffB); PG8_STAGE(PG8_SA(0, 1), cA + hstepA, voffA);
;         if (wr == 1) PG8_BAR;
;         PG8_WAIT_V(4); PG8_BAR;
;         PG8_STAGE(PG8_SB(1, 0), cB + kstep, voffB); PG8_STAGE(PG8_SA(1, 0), cA + kstep, voffA); PG8_STAGE(PG8_SB(1, 1), cB + hstepB + kstep, voffB);
;         PG8_WAIT_V(6); PG8_BAR;
;     }
;     for (;;) {
;         const bool has_next = S.next(ui + 1, nxt);
;         const char* nA = has_next ? (const char*)(g.A + (size_t)nxt.g * g.gsA) + (size_t)nxt.pm * tstepA : cA; const char* nB = has_next ? (const char*)(g.Bt + (size_t)nxt.g * g.gsB) + (size_t)nxt.pn * tstepB : cB;
;         for (int t = 0; t < nt; t += 2) {
;             if constexpr (Epi::MIDK) { if (t == (nt >> 1)) { asm volatile("s_waitcnt vmcnt(0)" ::: "memory"); E.mid(acc, cur, wr, wc, fr, fq); asm volatile("s_waitcnt vmcnt(0)" ::: "memory"); } }
;             const bool last = (t == nt - 2);
;             const char* a1 = cA + (size_t)(t + 1) * kstep;
;             const char* a2 = last ? nA : cA + (size_t)(t + 2) * kstep; const char* b2 = last ? nB : cB + (size_t)(t + 2) * kstep;
.LBB0_897:
	s_ashr_i32 s29, s28, 31
	s_lshl_b64 s[30:31], s[28:29], 22
	s_add_u32 s30, s45, s30
	s_addc_u32 s31, s46, s31
	s_ashr_i32 s27, s26, 31
	s_lshl_b64 s[34:35], s[26:27], 22
	s_add_u32 s34, s47, s34
	v_mov_b32_e32 v127, 0
	s_addc_u32 s35, s48, s35
	s_andn2_b64 vcc, exec, s[12:13]
	v_mov_b32_e32 v126, v127
	v_mov_b32_e32 v125, v127
	v_mov_b32_e32 v124, v127
	v_mov_b32_e32 v123, v127
	v_mov_b32_e32 v122, v127
	v_mov_b32_e32 v121, v127
	v_mov_b32_e32 v120, v127
	v_mov_b32_e32 v111, v127
	v_mov_b32_e32 v110, v127
	v_mov_b32_e32 v109, v127
	v_mov_b32_e32 v108, v127
	v_mov_b32_e32 v107, v127
	v_mov_b32_e32 v106, v127
	v_mov_b32_e32 v105, v127
	v_mov_b32_e32 v104, v127
	v_mov_b32_e32 v95, v127
	v_mov_b32_e32 v94, v127
	v_mov_b32_e32 v93, v127
	v_mov_b32_e32 v92, v127
	v_mov_b32_e32 v91, v127
	v_mov_b32_e32 v90, v127
	v_mov_b32_e32 v89, v127
	v_mov_b32_e32 v88, v127
	v_mov_b32_e32 v79, v127
	v_mov_b32_e32 v78, v127
	v_mov_b32_e32 v77, v127
	v_mov_b32_e32 v76, v127
	v_mov_b32_e32 v75, v127
	v_mov_b32_e32 v74, v127
	v_mov_b32_e32 v73, v127
	v_mov_b32_e32 v72, v127
	v_mov_b32_e32 v119, v127
	v_mov_b32_e32 v118, v127
	v_mov_b32_e32 v117, v127
	v_mov_b32_e32 v116, v127
	v_mov_b32_e32 v115, v127
	v_mov_b32_e32 v114, v127
	v_mov_b32_e32 v113, v127
	v_mov_b32_e32 v112, v127
	v_mov_b32_e32 v103, v127
	v_mov_b32_e32 v102, v127
	v_mov_b32_e32 v101, v127
	v_mov_b32_e32 v100, v127
	v_mov_b32_e32 v99, v127
	v_mov_b32_e32 v98, v127
	v_mov_b32_e32 v97, v127
	v_mov_b32_e32 v96, v127
	v_mov_b32_e32 v87, v127
	v_mov_b32_e32 v86, v127
	v_mov_b32_e32 v85, v127
	v_mov_b32_e32 v84, v127
	v_mov_b32_e32 v83, v127
	v_mov_b32_e32 v82, v127
	v_mov_b32_e32 v81, v127
	v_mov_b32_e32 v80, v127
	v_mov_b32_e32 v71, v127
	v_mov_b32_e32 v70, v127
	v_mov_b32_e32 v69, v127
	v_mov_b32_e32 v68, v127
	v_mov_b32_e32 v67, v127
	v_mov_b32_e32 v66, v127
	v_mov_b32_e32 v65, v127
	v_mov_b32_e32 v64, v127
	v_mov_b32_e32 v63, v127
	v_mov_b32_e32 v62, v127
	v_mov_b32_e32 v61, v127
	v_mov_b32_e32 v60, v127
	v_mov_b32_e32 v59, v127
	v_mov_b32_e32 v58, v127
	v_mov_b32_e32 v57, v127
	v_mov_b32_e32 v56, v127
	v_mov_b32_e32 v47, v127
	v_mov_b32_e32 v46, v127
	v_mov_b32_e32 v45, v127
	v_mov_b32_e32 v44, v127
	v_mov_b32_e32 v43, v127
	v_mov_b32_e32 v42, v127
	v_mov_b32_e32 v41, v127
	v_mov_b32_e32 v40, v127
	v_mov_b32_e32 v31, v127
	v_mov_b32_e32 v30, v127
	v_mov_b32_e32 v29, v127
	v_mov_b32_e32 v28, v127
	v_mov_b32_e32 v27, v127
	v_mov_b32_e32 v26, v127
	v_mov_b32_e32 v25, v127
	v_mov_b32_e32 v24, v127
	v_mov_b32_e32 v15, v127
	v_mov_b32_e32 v14, v127
	v_mov_b32_e32 v13, v127
	v_mov_b32_e32 v12, v127
	v_mov_b32_e32 v11, v127
	v_mov_b32_e32 v10, v127
	v_mov_b32_e32 v9, v127
	v_mov_b32_e32 v8, v127
	v_mov_b32_e32 v55, v127
	v_mov_b32_e32 v54, v127
	v_mov_b32_e32 v53, v127
	v_mov_b32_e32 v52, v127
	v_mov_b32_e32 v51, v127
	v_mov_b32_e32 v50, v127
	v_mov_b32_e32 v49, v127
	v_mov_b32_e32 v48, v127
	v_mov_b32_e32 v39, v127
	v_mov_b32_e32 v38, v127
	v_mov_b32_e32 v37, v127
	v_mov_b32_e32 v36, v127
	v_mov_b32_e32 v35, v127
	v_mov_b32_e32 v34, v127
	v_mov_b32_e32 v33, v127
	v_mov_b32_e32 v32, v127
	v_mov_b32_e32 v23, v127
	v_mov_b32_e32 v22, v127
	v_mov_b32_e32 v21, v127
	v_mov_b32_e32 v20, v127
	v_mov_b32_e32 v19, v127
	v_mov_b32_e32 v18, v127
	v_mov_b32_e32 v17, v127
	v_mov_b32_e32 v16, v127
	v_mov_b32_e32 v7, v127
	v_mov_b32_e32 v6, v127
	v_mov_b32_e32 v5, v127
	v_mov_b32_e32 v4, v127
	s_waitcnt lgkmcnt(0)
	v_mov_b32_e32 v3, v127
	v_mov_b32_e32 v2, v127
	v_mov_b32_e32 v1, v127
	v_mov_b32_e32 v0, v127
	s_cbranch_vccnz .LBB0_900
	s_and_b64 s[42:43], s[6:7], exec
	s_cselect_b32 s27, s31, s41
	s_cselect_b32 s29, s30, s40
	s_cselect_b32 s65, s35, s39
	s_cselect_b32 s66, s34, s38
	s_add_u32 s67, s38, 0x100
	s_addc_u32 s68, s39, 0
	s_add_u32 s38, s40, 0x200080
	s_addc_u32 s39, s41, 0
	s_mov_b32 s40, 0
.LBB0_899:
	ds_read_b128 v[146:149], v156
	ds_read_b128 v[160:163], v156 offset:1024
	ds_read_b128 v[164:167], v156 offset:2048
	ds_read_b128 v[168:171], v156 offset:3072
	ds_read_b128 v[172:175], v157
	ds_read_b128 v[176:179], v157 offset:1024
	ds_read_b128 v[180:183], v157 offset:2048
	ds_read_b128 v[188:191], v157 offset:3072
	s_add_i32 s69, s40, 2
	s_add_u32 s41, s38, 0xffe00080
	s_addc_u32 s42, s39, -1
	s_cmp_eq_u32 s58, s40
	s_cselect_b32 s40, s66, s67
	s_cselect_b32 s43, s27, s42
	s_cselect_b32 s42, s29, s41
	s_cselect_b32 s41, s65, s68
	v_lshl_add_u64 v[150:151], s[38:39], 0, v[140:141]
	s_add_i32 m0, s50, 0xc000
	ds_read_b128 v[192:195], v158
	ds_read_b128 v[196:199], v158 offset:1024
	ds_read_b128 v[200:203], v158 offset:2048
	ds_read_b128 v[204:207], v158 offset:3072
	ds_read_b128 v[208:211], v158 offset:4096
	ds_read_b128 v[212:215], v158 offset:5120
	ds_read_b128 v[216:219], v158 offset:6144
	ds_read_b128 v[220:223], v158 offset:7168
	global_load_lds_dwordx4 v[150:151], off
	v_lshl_add_u64 v[150:151], s[38:39], 0, v[138:139]
	s_add_i32 m0, s50, 0xe000
	s_nop 0
	global_load_lds_dwordx4 v[150:151], off
	s_waitcnt vmcnt(8)
	s_waitcnt lgkmcnt(0)
	s_barrier
; #define PG8_STAGE(bufoff, gbase, voff) do { _Pragma("unroll") for (int _i = 0; _i < 2; ++_i) \
;         __builtin_amdgcn_global_load_lds((const unsigned*)((const char*)(gbase) + (voff)[_i]), (PG8_LAS unsigned*)(lds + (bufoff) + ldsw + _i * 8192), 16, 0, 0); } while (0)
; #define PG8_LDA(dst, b, h) do { _Pragma("unroll") for (int m = 0; m < 4; ++m) _Pragma("unroll") for (int k = 0; k < 2; ++k) dst[m][k] = *(const PG8_LAS bf16x8*)(lds + PG8_SA(b, h) + aoff + m * 2048 + k * 1024); } while (0)
; #define PG8_MMA(ai, bj, At, Bt) do { __builtin_amdgcn_s_setprio(1); _Pragma("unroll") for (int m = 0; m < 4; ++m) _Pragma("unroll") for (int n = 0; n < 2; ++n) _Pragma("unroll") for (int k = 0; k < 2; ++k) \
;         acc[ai][bj][m][n] = __builtin_amdgcn_mfma_f32_16x16x32_bf16(Bt[n][k], At[m][k], acc[ai][bj][m][n], 0, 0, 0); __builtin_amdgcn_s_setprio(0); } while (0)
; #define PG8_WAIT_V(n) asm volatile("s_waitcnt vmcnt(" #n ")" ::: "memory")
; #define PG8_WAIT_L(n) asm volatile("s_waitcnt lgkmcnt(" #n ")" ::: "memory")
; #define PG8_BAR __builtin_amdgcn_s_barrier()
; #define PG8_SCHED __builtin_amdgcn_sched_barrier(0)
; template <class Epi, class Sched, bool ALIGN_EPI = false, bool SP2 = false>
; __device__ __forceinline__ void gemm_phase(PG8_LAS unsigned char* lds, const Gemm g, const Sched& S, const Epi& E) {
;     ...
;             PG8_WAIT_V(8); PG8_WAIT_L(0); PG8_BAR; PG8_MMA(0, 0, At, B0); PG8_MMA(0, 1, At, B1); PG8_BAR; PG8_SCHED;
;             PG8_LDA(At, 0, 1); PG8_STAGE(PG8_SB(0, 0), b2, voffB); PG8_STAGE(PG8_SB(0, 1), b2 + hstepB, voffB); PG8_STAGE(PG8_SA(0, 0), a2, voffA);
;             PG8_WAIT_V(8); PG8_WAIT_L(0); PG8_BAR; PG8_MMA(1, 0, At, B0); PG8_MMA(1, 1, At, B1); PG8_BAR; PG8_SCHED;
	s_waitcnt lgkmcnt(0)
	v_mfma_f32_16x16x32_bf16 v[124:127], v[146:149], v[192:195], v[124:127]
	v_mfma_f32_16x16x32_bf16 v[120:123], v[164:167], v[192:195], v[120:123]
	v_mfma_f32_16x16x32_bf16 v[108:111], v[146:149], v[200:203], v[108:111]
	v_mfma_f32_16x16x32_bf16 v[104:107], v[164:167], v[200:203], v[104:107]
	v_mfma_f32_16x16x32_bf16 v[92:95], v[146:149], v[208:211], v[92:95]
	v_mfma_f32_16x16x32_bf16 v[88:91], v[164:167], v[208:211], v[88:91]
	v_mfma_f32_16x16x32_bf16 v[76:79], v[146:149], v[216:219], v[76:79]
	v_mfma_f32_16x16x32_bf16 v[72:75], v[164:167], v[216:219], v[72:75]
	v_mfma_f32_16x16x32_bf16 v[124:127], v[160:163], v[196:199], v[124:127]
	v_mfma_f32_16x16x32_bf16 v[120:123], v[168:171], v[196:199], v[120:123]
	v_mfma_f32_16x16x32_bf16 v[108:111], v[160:163], v[204:207], v[108:111]
	v_mfma_f32_16x16x32_bf16 v[104:107], v[168:171], v[204:207], v[104:107]
	v_mfma_f32_16x16x32_bf16 v[92:95], v[160:163], v[212:215], v[92:95]
	v_mfma_f32_16x16x32_bf16 v[88:91], v[168:171], v[212:215], v[88:91]
	v_mfma_f32_16x16x32_bf16 v[76:79], v[160:163], v[220:223], v[76:79]
	v_mfma_f32_16x16x32_bf16 v[72:75], v[168:171], v[220:223], v[72:75]
	v_mfma_f32_16x16x32_bf16 v[116:119], v[172:175], v[192:195], v[116:119]
	v_mfma_f32_16x16x32_bf16 v[112:115], v[180:183], v[192:195], v[112:115]
	v_mfma_f32_16x16x32_bf16 v[100:103], v[172:175], v[200:203], v[100:103]
	v_mfma_f32_16x16x32_bf16 v[96:99], v[180:183], v[200:203], v[96:99]
	v_mfma_f32_16x16x32_bf16 v[84:87], v[172:175], v[208:211], v[84:87]
	v_mfma_f32_16x16x32_bf16 v[80:83], v[180:183], v[208:211], v[80:83]
	v_mfma_f32_16x16x32_bf16 v[68:71], v[172:175], v[216:219], v[68:71]
	v_mfma_f32_16x16x32_bf16 v[64:67], v[180:183], v[216:219], v[64:67]
	v_mfma_f32_16x16x32_bf16 v[116:119], v[176:179], v[196:199], v[116:119]
	v_mfma_f32_16x16x32_bf16 v[112:115], v[188:191], v[196:199], v[112:115]
	v_mfma_f32_16x16x32_bf16 v[100:103], v[176:179], v[204:207], v[100:103]
	v_mfma_f32_16x16x32_bf16 v[96:99], v[188:191], v[204:207], v[96:99]
	v_mfma_f32_16x16x32_bf16 v[84:87], v[176:179], v[212:215], v[84:87]
	v_mfma_f32_16x16x32_bf16 v[80:83], v[188:191], v[212:215], v[80:83]
	v_mfma_f32_16x16x32_bf16 v[68:71], v[176:179], v[220:223], v[68:71]
	v_mfma_f32_16x16x32_bf16 v[64:67], v[188:191], v[220:223], v[64:67]
	s_barrier
	s_add_i32 s70, s59, s49
	v_lshl_add_u64 v[150:151], s[40:41], 0, v[130:131]
	s_mov_b32 m0, s70
	ds_read_b128 v[192:195], v158 offset:16384
	ds_read_b128 v[196:199], v158 offset:17408
	ds_read_b128 v[200:203], v158 offset:18432
	ds_read_b128 v[204:207], v158 offset:19456
	ds_read_b128 v[208:211], v158 offset:20480
	ds_read_b128 v[212:215], v158 offset:21504
	ds_read_b128 v[216:219], v158 offset:22528
	ds_read_b128 v[220:223], v158 offset:23552
	global_load_lds_dwordx4 v[150:151], off
	s_add_i32 m0, s70, 0x2000
	s_add_u32 s70, s40, 0x200000
	v_lshl_add_u64 v[184:185], s[40:41], 0, v[134:135]
	s_addc_u32 s71, s41, 0
	s_add_i32 s72, s60, s49
	global_load_lds_dwordx4 v[184:185], off
	v_lshl_add_u64 v[224:225], s[70:71], 0, v[130:131]
	s_mov_b32 m0, s72
	v_lshl_add_u64 v[228:229], s[42:43], 0, v[132:133]
	global_load_lds_dwordx4 v[224:225], off
	v_lshl_add_u64 v[224:225], s[70:71], 0, v[134:135]
	s_add_i32 m0, s72, 0x2000
	s_nop 0
	global_load_lds_dwordx4 v[224:225], off
	v_lshl_add_u64 v[224:225], s[42:43], 0, v[128:129]
	s_mov_b32 m0, s50
	s_nop 0
	global_load_lds_dwordx4 v[224:225], off
	s_mov_b32 m0, s51
	s_nop 0
	global_load_lds_dwordx4 v[228:229], off
	s_waitcnt vmcnt(8)
	s_waitcnt lgkmcnt(0)
	s_barrier
	s_waitcnt lgkmcnt(0)
	v_mfma_f32_16x16x32_bf16 v[60:63], v[146:149], v[192:195], v[60:63]
	v_mfma_f32_16x16x32_bf16 v[56:59], v[164:167], v[192:195], v[56:59]
	v_mfma_f32_16x16x32_bf16 v[44:47], v[146:149], v[200:203], v[44:47]
	v_mfma_f32_16x16x32_bf16 v[40:43], v[164:167], v[200:203], v[40:43]
	v_mfma_f32_16x16x32_bf16 v[28:31], v[146:149], v[208:211], v[28:31]
	v_mfma_f32_16x16x32_bf16 v[24:27], v[164:167], v[208:211], v[24:27]
	v_mfma_f32_16x16x32_bf16 v[12:15], v[146:149], v[216:219], v[12:15]
	v_mfma_f32_16x16x32_bf16 v[8:11], v[164:167], v[216:219], v[8:11]
	v_mfma_f32_16x16x32_bf16 v[60:63], v[160:163], v[196:199], v[60:63]
	v_mfma_f32_16x16x32_bf16 v[56:59], v[168:171], v[196:199], v[56:59]
	v_mfma_f32_16x16x32_bf16 v[44:47], v[160:163], v[204:207], v[44:47]
	v_mfma_f32_16x16x32_bf16 v[40:43], v[168:171], v[204:207], v[40:43]
	v_mfma_f32_16x16x32_bf16 v[28:31], v[160:163], v[212:215], v[28:31]
	v_mfma_f32_16x16x32_bf16 v[24:27], v[168:171], v[212:215], v[24:27]
	v_mfma_f32_16x16x32_bf16 v[12:15], v[160:163], v[220:223], v[12:15]
	v_mfma_f32_16x16x32_bf16 v[8:11], v[168:171], v[220:223], v[8:11]
	v_mfma_f32_16x16x32_bf16 v[52:55], v[172:175], v[192:195], v[52:55]
	v_mfma_f32_16x16x32_bf16 v[48:51], v[180:183], v[192:195], v[48:51]
	v_mfma_f32_16x16x32_bf16 v[36:39], v[172:175], v[200:203], v[36:39]
	v_mfma_f32_16x16x32_bf16 v[32:35], v[180:183], v[200:203], v[32:35]
	v_mfma_f32_16x16x32_bf16 v[20:23], v[172:175], v[208:211], v[20:23]
	v_mfma_f32_16x16x32_bf16 v[16:19], v[180:183], v[208:211], v[16:19]
	v_mfma_f32_16x16x32_bf16 v[4:7], v[172:175], v[216:219], v[4:7]
	v_mfma_f32_16x16x32_bf16 v[0:3], v[180:183], v[216:219], v[0:3]
	v_mfma_f32_16x16x32_bf16 v[52:55], v[176:179], v[196:199], v[52:55]
	v_mfma_f32_16x16x32_bf16 v[48:51], v[188:191], v[196:199], v[48:51]
	v_mfma_f32_16x16x32_bf16 v[36:39], v[176:179], v[204:207], v[36:39]
	v_mfma_f32_16x16x32_bf16 v[32:35], v[188:191], v[204:207], v[32:35]
	v_mfma_f32_16x16x32_bf16 v[20:23], v[176:179], v[212:215], v[20:23]
	v_mfma_f32_16x16x32_bf16 v[16:19], v[188:191], v[212:215], v[16:19]
	v_mfma_f32_16x16x32_bf16 v[4:7], v[176:179], v[220:223], v[4:7]
	v_mfma_f32_16x16x32_bf16 v[0:3], v[188:191], v[220:223], v[0:3]
	s_barrier
; #define PG8_STAGE(bufoff, gbase, voff) do { _Pragma("unroll") for (int _i = 0; _i < 2; ++_i) \
;         __builtin_amdgcn_global_load_lds((const unsigned*)((const char*)(gbase) + (voff)[_i]), (PG8_LAS unsigned*)(lds + (bufoff) + ldsw + _i * 8192), 16, 0, 0); } while (0)
; #define PG8_LDA(dst, b, h) do { _Pragma("unroll") for (int m = 0; m < 4; ++m) _Pragma("unroll") for (int k = 0; k < 2; ++k) dst[m][k] = *(const PG8_LAS bf16x8*)(lds + PG8_SA(b, h) + aoff + m * 2048 + k * 1024); } while (0)
; #define PG8_LDB(dst, b, h) do { _Pragma("unroll") for (int n = 0; n < 2; ++n) _Pragma("unroll") for (int k = 0; k < 2; ++k) dst[n][k] = *(const PG8_LAS bf16x8*)(lds + PG8_SB(b, h) + boff + n * 2048 + k * 1024); } while (0)
; #define PG8_MMA(ai, bj, At, Bt) do { __builtin_amdgcn_s_setprio(1); _Pragma("unroll") for (int m = 0; m < 4; ++m) _Pragma("unroll") for (int n = 0; n < 2; ++n) _Pragma("unroll") for (int k = 0; k < 2; ++k) \
;         acc[ai][bj][m][n] = __builtin_amdgcn_mfma_f32_16x16x32_bf16(Bt[n][k], At[m][k], acc[ai][bj][m][n], 0, 0, 0); __builtin_amdgcn_s_setprio(0); } while (0)
; #define PG8_WAIT_V(n) asm volatile("s_waitcnt vmcnt(" #n ")" ::: "memory")
; #define PG8_WAIT_L(n) asm volatile("s_waitcnt lgkmcnt(" #n ")" ::: "memory")
; #define PG8_BAR __builtin_amdgcn_s_barrier()
; #define PG8_SCHED __builtin_amdgcn_sched_barrier(0)
; template <class Epi, class Sched, bool ALIGN_EPI = false, bool SP2 = false>
; __device__ __forceinline__ void gemm_phase(PG8_LAS unsigned char* lds, const Gemm g, const Sched& S, const Epi& E) {
;     ...
;             PG8_LDB(B0, 1, 0); PG8_LDB(B1, 1, 1); PG8_SCHED; PG8_LDA(At, 1, 0); PG8_STAGE(PG8_SA(0, 1), a2 + hstepA, voffA);
;             PG8_WAIT_V(8); PG8_WAIT_L(0); PG8_BAR; PG8_MMA(0, 0, At, B0); PG8_MMA(0, 1, At, B1); PG8_BAR; PG8_SCHED;
;             PG8_LDA(At, 1, 1); PG8_STAGE(PG8_SB(1, 0), b3, voffB); PG8_STAGE(PG8_SB(1, 1), b3 + hstepB, voffB); PG8_STAGE(PG8_SA(1, 0), a3, voffA);
;             PG8_WAIT_V(8); PG8_WAIT_L(0); PG8_BAR; PG8_MMA(1, 0, At, B0); PG8_MMA(1, 1, At, B1); PG8_BAR; PG8_SCHED;
	s_add_i32 s70, 0, 0x18000
	v_add_u32_e32 v159, s70, v154
	s_add_i32 s71, 0, 0x1c000
	ds_read_b128 v[146:149], v159
	ds_read_b128 v[160:163], v159 offset:1024
	ds_read_b128 v[164:167], v159 offset:2048
	ds_read_b128 v[168:171], v159 offset:3072
	v_add_u32_e32 v159, s71, v154
	ds_read_b128 v[172:175], v159
	ds_read_b128 v[176:179], v159 offset:1024
	ds_read_b128 v[180:183], v159 offset:2048
	ds_read_b128 v[188:191], v159 offset:3072
	s_add_u32 s42, s42, 0x200000
	s_addc_u32 s43, s43, 0
	s_mov_b32 m0, s52
	v_lshl_add_u64 v[230:231], s[42:43], 0, v[128:129]
	ds_read_b128 v[192:195], v158 offset:32768
	ds_read_b128 v[196:199], v158 offset:33792
	ds_read_b128 v[200:203], v158 offset:34816
	ds_read_b128 v[204:207], v158 offset:35840
	ds_read_b128 v[208:211], v158 offset:36864
	ds_read_b128 v[212:215], v158 offset:37888
	ds_read_b128 v[216:219], v158 offset:38912
	ds_read_b128 v[220:223], v158 offset:39936
	global_load_lds_dwordx4 v[230:231], off
	v_lshl_add_u64 v[230:231], s[42:43], 0, v[132:133]
	s_mov_b32 m0, s53
	s_nop 0
	global_load_lds_dwordx4 v[230:231], off
	s_waitcnt vmcnt(8)
	s_waitcnt lgkmcnt(0)
	s_barrier
	s_waitcnt lgkmcnt(0)
	v_mfma_f32_16x16x32_bf16 v[124:127], v[146:149], v[192:195], v[124:127]
	v_mfma_f32_16x16x32_bf16 v[120:123], v[164:167], v[192:195], v[120:123]
	v_mfma_f32_16x16x32_bf16 v[108:111], v[146:149], v[200:203], v[108:111]
	v_mfma_f32_16x16x32_bf16 v[104:107], v[164:167], v[200:203], v[104:107]
	v_mfma_f32_16x16x32_bf16 v[92:95], v[146:149], v[208:211], v[92:95]
	v_mfma_f32_16x16x32_bf16 v[88:91], v[164:167], v[208:211], v[88:91]
	v_mfma_f32_16x16x32_bf16 v[76:79], v[146:149], v[216:219], v[76:79]
	v_mfma_f32_16x16x32_bf16 v[72:75], v[164:167], v[216:219], v[72:75]
	v_mfma_f32_16x16x32_bf16 v[124:127], v[160:163], v[196:199], v[124:127]
	v_mfma_f32_16x16x32_bf16 v[120:123], v[168:171], v[196:199], v[120:123]
	v_mfma_f32_16x16x32_bf16 v[108:111], v[160:163], v[204:207], v[108:111]
	v_mfma_f32_16x16x32_bf16 v[104:107], v[168:171], v[204:207], v[104:107]
	v_mfma_f32_16x16x32_bf16 v[92:95], v[160:163], v[212:215], v[92:95]
	v_mfma_f32_16x16x32_bf16 v[88:91], v[168:171], v[212:215], v[88:91]
	v_mfma_f32_16x16x32_bf16 v[76:79], v[160:163], v[220:223], v[76:79]
	v_mfma_f32_16x16x32_bf16 v[72:75], v[168:171], v[220:223], v[72:75]
	v_mfma_f32_16x16x32_bf16 v[116:119], v[172:175], v[192:195], v[116:119]
	v_mfma_f32_16x16x32_bf16 v[112:115], v[180:183], v[192:195], v[112:115]
	v_mfma_f32_16x16x32_bf16 v[100:103], v[172:175], v[200:203], v[100:103]
	v_mfma_f32_16x16x32_bf16 v[96:99], v[180:183], v[200:203], v[96:99]
	v_mfma_f32_16x16x32_bf16 v[84:87], v[172:175], v[208:211], v[84:87]
	v_mfma_f32_16x16x32_bf16 v[80:83], v[180:183], v[208:211], v[80:83]
	v_mfma_f32_16x16x32_bf16 v[68:71], v[172:175], v[216:219], v[68:71]
	v_mfma_f32_16x16x32_bf16 v[64:67], v[180:183], v[216:219], v[64:67]
	v_mfma_f32_16x16x32_bf16 v[116:119], v[176:179], v[196:199], v[116:119]
	v_mfma_f32_16x16x32_bf16 v[112:115], v[188:191], v[196:199], v[112:115]
	v_mfma_f32_16x16x32_bf16 v[100:103], v[176:179], v[204:207], v[100:103]
	v_mfma_f32_16x16x32_bf16 v[96:99], v[188:191], v[204:207], v[96:99]
	v_mfma_f32_16x16x32_bf16 v[84:87], v[176:179], v[212:215], v[84:87]
	v_mfma_f32_16x16x32_bf16 v[80:83], v[188:191], v[212:215], v[80:83]
	v_mfma_f32_16x16x32_bf16 v[68:71], v[176:179], v[220:223], v[68:71]
	v_mfma_f32_16x16x32_bf16 v[64:67], v[188:191], v[220:223], v[64:67]
	s_barrier
	s_add_i32 s42, s70, s49
	v_lshl_add_u64 v[150:151], v[150:151], 0, s[10:11]
	s_mov_b32 m0, s42
	ds_read_b128 v[192:195], v158 offset:49152
	ds_read_b128 v[196:199], v158 offset:50176
	ds_read_b128 v[200:203], v158 offset:51200
	ds_read_b128 v[204:207], v158 offset:52224
	ds_read_b128 v[208:211], v158 offset:53248
	ds_read_b128 v[212:215], v158 offset:54272
	ds_read_b128 v[216:219], v158 offset:55296
	ds_read_b128 v[220:223], v158 offset:56320
	global_load_lds_dwordx4 v[150:151], off
	s_add_i32 m0, s42, 0x2000
	s_add_u32 s40, s40, 0x200080
	v_lshl_add_u64 v[150:151], v[184:185], 0, s[10:11]
	s_addc_u32 s41, s41, 0
	s_add_i32 s42, s71, s49
	global_load_lds_dwordx4 v[150:151], off
	v_lshl_add_u64 v[150:151], s[40:41], 0, v[130:131]
	s_mov_b32 m0, s42
	s_nop 0
	global_load_lds_dwordx4 v[150:151], off
	v_lshl_add_u64 v[150:151], s[40:41], 0, v[134:135]
	s_add_i32 m0, s42, 0x2000
	s_nop 0
	global_load_lds_dwordx4 v[150:151], off
	v_lshl_add_u64 v[150:151], v[224:225], 0, s[10:11]
	s_mov_b32 m0, s56
	s_nop 0
	global_load_lds_dwordx4 v[150:151], off
	v_lshl_add_u64 v[150:151], v[228:229], 0, s[10:11]
	s_mov_b32 m0, s57
	s_nop 0
	global_load_lds_dwordx4 v[150:151], off
	s_waitcnt vmcnt(8)
	s_waitcnt lgkmcnt(0)
	s_barrier
	s_waitcnt lgkmcnt(0)
	v_mfma_f32_16x16x32_bf16 v[60:63], v[146:149], v[192:195], v[60:63]
	v_mfma_f32_16x16x32_bf16 v[56:59], v[164:167], v[192:195], v[56:59]
	v_mfma_f32_16x16x32_bf16 v[44:47], v[146:149], v[200:203], v[44:47]
	v_mfma_f32_16x16x32_bf16 v[40:43], v[164:167], v[200:203], v[40:43]
	v_mfma_f32_16x16x32_bf16 v[28:31], v[146:149], v[208:211], v[28:31]
	v_mfma_f32_16x16x32_bf16 v[24:27], v[164:167], v[208:211], v[24:27]
	v_mfma_f32_16x16x32_bf16 v[12:15], v[146:149], v[216:219], v[12:15]
	v_mfma_f32_16x16x32_bf16 v[8:11], v[164:167], v[216:219], v[8:11]
	v_mfma_f32_16x16x32_bf16 v[60:63], v[160:163], v[196:199], v[60:63]
	v_mfma_f32_16x16x32_bf16 v[56:59], v[168:171], v[196:199], v[56:59]
	v_mfma_f32_16x16x32_bf16 v[44:47], v[160:163], v[204:207], v[44:47]
	v_mfma_f32_16x16x32_bf16 v[40:43], v[168:171], v[204:207], v[40:43]
	v_mfma_f32_16x16x32_bf16 v[28:31], v[160:163], v[212:215], v[28:31]
	v_mfma_f32_16x16x32_bf16 v[24:27], v[168:171], v[212:215], v[24:27]
	v_mfma_f32_16x16x32_bf16 v[12:15], v[160:163], v[220:223], v[12:15]
	v_mfma_f32_16x16x32_bf16 v[8:11], v[168:171], v[220:223], v[8:11]
	v_mfma_f32_16x16x32_bf16 v[52:55], v[172:175], v[192:195], v[52:55]
	v_mfma_f32_16x16x32_bf16 v[48:51], v[180:183], v[192:195], v[48:51]
	v_mfma_f32_16x16x32_bf16 v[36:39], v[172:175], v[200:203], v[36:39]
	v_mfma_f32_16x16x32_bf16 v[32:35], v[180:183], v[200:203], v[32:35]
	v_mfma_f32_16x16x32_bf16 v[20:23], v[172:175], v[208:211], v[20:23]
	v_mfma_f32_16x16x32_bf16 v[16:19], v[180:183], v[208:211], v[16:19]
	v_mfma_f32_16x16x32_bf16 v[4:7], v[172:175], v[216:219], v[4:7]
	v_mfma_f32_16x16x32_bf16 v[0:3], v[180:183], v[216:219], v[0:3]
	v_mfma_f32_16x16x32_bf16 v[52:55], v[176:179], v[196:199], v[52:55]
	v_mfma_f32_16x16x32_bf16 v[48:51], v[188:191], v[196:199], v[48:51]
	v_mfma_f32_16x16x32_bf16 v[36:39], v[176:179], v[204:207], v[36:39]
	v_mfma_f32_16x16x32_bf16 v[32:35], v[188:191], v[204:207], v[32:35]
	v_mfma_f32_16x16x32_bf16 v[20:23], v[176:179], v[212:215], v[20:23]
	v_mfma_f32_16x16x32_bf16 v[16:19], v[188:191], v[212:215], v[16:19]
	v_mfma_f32_16x16x32_bf16 v[4:7], v[176:179], v[220:223], v[4:7]
	v_mfma_f32_16x16x32_bf16 v[0:3], v[188:191], v[220:223], v[0:3]
	s_barrier
	s_add_u32 s67, s67, 0x100
	s_addc_u32 s68, s68, 0
	s_add_u32 s38, s38, 0x100
	s_addc_u32 s39, s39, 0
	s_cmp_ge_i32 s69, s55
	s_mov_b32 s40, s69
	s_cbranch_scc0 .LBB0_899
; #define PG8_BAR __builtin_amdgcn_s_barrier()
; template <class Epi, class Sched, bool ALIGN_EPI = false, bool SP2 = false>
; __device__ __forceinline__ void gemm_phase(PG8_LAS unsigned char* lds, const Gemm g, const Sched& S, const Epi& E) {
;     ...
;         if constexpr (ALIGN_EPI) { if (wr == 0) PG8_BAR; }
.LBB0_900:
	s_and_b64 vcc, exec, s[16:17]
	s_cbranch_vccz .LBB0_902
	s_barrier

; template <class Epi, class Sched, bool ALIGN_EPI = false, bool SP2 = false>
; __device__ __forceinline__ void gemm_phase(PG8_LAS unsigned char* lds, const Gemm g, const Sched& S, const Epi& E) {
;     ...
; #pragma unroll
;     for (int a = 0; a < 2; ++a)
; #pragma unroll
;         for (int b = 0; b < 2; ++b)
; #pragma unroll
;             for (int m = 0; m < 4; ++m)
; #pragma unroll
;                 for (int n = 0; n < 2; ++n) acc[a][b][m][n] = (f32x4){0.f, 0.f, 0.f, 0.f};
;     bf16x8 At[4][2], B0[2][2], B1[2][2];
;     const char* cA = (const char*)(g.A + (size_t)cur.g * g.gsA) + (size_t)cur.pm * tstepA; const char* cB = (const char*)(g.Bt + (size_t)cur.g * g.gsB) + (size_t)cur.pn * tstepB;
;     S.a_ready(cur);
;     if constexpr (SP2) {
;         PG8_STAGE(PG8_SB(0, 0), cB, voffB); PG8_STAGE(PG8_SB(0, 1), cB + hstepB, voffB); PG8_STAGE(PG8_SA(0, 0), cA, voffA); PG8_STAGE(PG8_SA(0, 1), cA + hstepA, voffA);
;         if (wr == 1) PG8_BAR;
;         PG8_WAIT_V(2); PG8_BAR;
;         PG8_STAGE(PG8_SB(1, 0), cB + kstep, voffB); PG8_STAGE(PG8_SA(1, 0), cA + kstep, voffA); PG8_STAGE(PG8_SB(1, 1), cB + hstepB + kstep, voffB);
;         PG8_WAIT_V(6); PG8_BAR;
;     } else {
;         PG8_STAGE(PG8_SB(0, 0), cB, voffB); PG8_STAGE(PG8_SA(0, 0), cA, voffA); PG8_STAGE(PG8_SB(0, 1), cB + hstepB, voffB); PG8_STAGE(PG8_SA(0, 1), cA + hstepA, voffA);
;         if (wr == 1) PG8_BAR;
;         PG8_WAIT_V(4); PG8_BAR;
;         PG8_STAGE(PG8_SB(1, 0), cB + kstep, voffB); PG8_STAGE(PG8_SA(1, 0), cA + kstep, voffA); PG8_STAGE(PG8_SB(1, 1), cB + hstepB + kstep, voffB);
;         PG8_WAIT_V(6); PG8_BAR;
;     }
;     for (;;) {
;         const bool has_next = S.next(ui + 1, nxt);
;         const char* nA = has_next ? (const char*)(g.A + (size_t)nxt.g * g.gsA) + (size_t)nxt.pm * tstepA : cA; const char* nB = has_next ? (const char*)(g.Bt + (size_t)nxt.g * g.gsB) + (size_t)nxt.pn * tstepB : cB;
;         for (int t = 0; t < nt; t += 2) {
;             if constexpr (Epi::MIDK) { if (t == (nt >> 1)) { asm volatile("s_waitcnt vmcnt(0)" ::: "memory"); E.mid(acc, cur, wr, wc, fr, fq); asm volatile("s_waitcnt vmcnt(0)" ::: "memory"); } }
;             const bool last = (t == nt - 2);
;             const char* a1 = cA + (size_t)(t + 1) * kstep;
;             const char* a2 = last ? nA : cA + (size_t)(t + 2) * kstep; const char* b2 = last ? nB : cB + (size_t)(t + 2) * kstep;
.LBB0_986:
	s_ashr_i32 s35, s34, 31
	s_lshl_b64 s[36:37], s[34:35], 17
	s_add_u32 s36, s48, s36
	s_addc_u32 s37, s49, s37
	s_ashr_i32 s31, s30, 31
	s_lshl_b64 s[38:39], s[30:31], 17
	s_add_u32 s38, s50, s38
	v_mov_b32_e32 v127, 0
	s_addc_u32 s39, s51, s39
	s_and_b64 vcc, exec, s[6:7]
	v_mov_b32_e32 v126, v127
	v_mov_b32_e32 v125, v127
	v_mov_b32_e32 v124, v127
	v_mov_b32_e32 v123, v127
	v_mov_b32_e32 v122, v127
	v_mov_b32_e32 v121, v127
	v_mov_b32_e32 v120, v127
	v_mov_b32_e32 v111, v127
	v_mov_b32_e32 v110, v127
	v_mov_b32_e32 v109, v127
	v_mov_b32_e32 v108, v127
	v_mov_b32_e32 v107, v127
	v_mov_b32_e32 v106, v127
	v_mov_b32_e32 v105, v127
	v_mov_b32_e32 v104, v127
	v_mov_b32_e32 v95, v127
	v_mov_b32_e32 v94, v127
	v_mov_b32_e32 v93, v127
	v_mov_b32_e32 v92, v127
	v_mov_b32_e32 v91, v127
	v_mov_b32_e32 v90, v127
	v_mov_b32_e32 v89, v127
	v_mov_b32_e32 v88, v127
	v_mov_b32_e32 v79, v127
	v_mov_b32_e32 v78, v127
	v_mov_b32_e32 v77, v127
	v_mov_b32_e32 v76, v127
	v_mov_b32_e32 v75, v127
	v_mov_b32_e32 v74, v127
	v_mov_b32_e32 v73, v127
	v_mov_b32_e32 v72, v127
	v_mov_b32_e32 v119, v127
	v_mov_b32_e32 v118, v127
	v_mov_b32_e32 v117, v127
	v_mov_b32_e32 v116, v127
	v_mov_b32_e32 v115, v127
	v_mov_b32_e32 v114, v127
	v_mov_b32_e32 v113, v127
	v_mov_b32_e32 v112, v127
	v_mov_b32_e32 v103, v127
	v_mov_b32_e32 v102, v127
	v_mov_b32_e32 v101, v127
	v_mov_b32_e32 v100, v127
	v_mov_b32_e32 v99, v127
	v_mov_b32_e32 v98, v127
	v_mov_b32_e32 v97, v127
	v_mov_b32_e32 v96, v127
	v_mov_b32_e32 v87, v127
	v_mov_b32_e32 v86, v127
	v_mov_b32_e32 v85, v127
	v_mov_b32_e32 v84, v127
	v_mov_b32_e32 v83, v127
	v_mov_b32_e32 v82, v127
	v_mov_b32_e32 v81, v127
	v_mov_b32_e32 v80, v127
	v_mov_b32_e32 v71, v127
	v_mov_b32_e32 v70, v127
	v_mov_b32_e32 v69, v127
	v_mov_b32_e32 v68, v127
	v_mov_b32_e32 v67, v127
	v_mov_b32_e32 v66, v127
	v_mov_b32_e32 v65, v127
	v_mov_b32_e32 v64, v127
	v_mov_b32_e32 v63, v127
	v_mov_b32_e32 v62, v127
	v_mov_b32_e32 v61, v127
	v_mov_b32_e32 v60, v127
	v_mov_b32_e32 v59, v127
	v_mov_b32_e32 v58, v127
	v_mov_b32_e32 v57, v127
	v_mov_b32_e32 v56, v127
	v_mov_b32_e32 v47, v127
	v_mov_b32_e32 v46, v127
	v_mov_b32_e32 v45, v127
	v_mov_b32_e32 v44, v127
	v_mov_b32_e32 v43, v127
	v_mov_b32_e32 v42, v127
	v_mov_b32_e32 v41, v127
	v_mov_b32_e32 v40, v127
	v_mov_b32_e32 v31, v127
	v_mov_b32_e32 v30, v127
	v_mov_b32_e32 v29, v127
	v_mov_b32_e32 v28, v127
	v_mov_b32_e32 v27, v127
	v_mov_b32_e32 v26, v127
	v_mov_b32_e32 v25, v127
	v_mov_b32_e32 v24, v127
	v_mov_b32_e32 v15, v127
	v_mov_b32_e32 v14, v127
	v_mov_b32_e32 v13, v127
	v_mov_b32_e32 v12, v127
	v_mov_b32_e32 v11, v127
	v_mov_b32_e32 v10, v127
	v_mov_b32_e32 v9, v127
	v_mov_b32_e32 v8, v127
	v_mov_b32_e32 v55, v127
	v_mov_b32_e32 v54, v127
	v_mov_b32_e32 v53, v127
	v_mov_b32_e32 v52, v127
	v_mov_b32_e32 v51, v127
	v_mov_b32_e32 v50, v127
	v_mov_b32_e32 v49, v127
	v_mov_b32_e32 v48, v127
	v_mov_b32_e32 v39, v127
	v_mov_b32_e32 v38, v127
	v_mov_b32_e32 v37, v127
	v_mov_b32_e32 v36, v127
	v_mov_b32_e32 v35, v127
	v_mov_b32_e32 v34, v127
	v_mov_b32_e32 v33, v127
	v_mov_b32_e32 v32, v127
	v_mov_b32_e32 v23, v127
	v_mov_b32_e32 v22, v127
	v_mov_b32_e32 v21, v127
	v_mov_b32_e32 v20, v127
	v_mov_b32_e32 v19, v127
	v_mov_b32_e32 v18, v127
	v_mov_b32_e32 v17, v127
	v_mov_b32_e32 v16, v127
	v_mov_b32_e32 v7, v127
	v_mov_b32_e32 v6, v127
	v_mov_b32_e32 v5, v127
	v_mov_b32_e32 v4, v127
	v_mov_b32_e32 v3, v127
	v_mov_b32_e32 v2, v127
	v_mov_b32_e32 v1, v127
	v_mov_b32_e32 v0, v127
	s_cbranch_vccnz .LBB0_989
	s_and_b64 s[44:45], s[8:9], exec
	s_cselect_b32 s31, s37, s43
	s_cselect_b32 s35, s36, s42
	s_cselect_b32 s67, s39, s41
	s_cselect_b32 s68, s38, s40
	s_add_u32 s69, s40, 0x100
	s_addc_u32 s70, s41, 0
	s_add_u32 s40, s42, 0x10080
	s_addc_u32 s41, s43, 0
	s_mov_b32 s42, 0
.LBB0_988:
	ds_read_b128 v[150:153], v147
	ds_read_b128 v[154:157], v147 offset:1024
	ds_read_b128 v[158:161], v147 offset:2048
	ds_read_b128 v[162:165], v147 offset:3072
	ds_read_b128 v[166:169], v148
	ds_read_b128 v[170:173], v148 offset:1024
	ds_read_b128 v[174:177], v148 offset:2048
	ds_read_b128 v[178:181], v148 offset:3072
	s_add_i32 s71, s42, 2
	s_add_u32 s43, s40, 0xffff0080
	s_addc_u32 s44, s41, -1
	s_cmp_eq_u32 s60, s42
	s_cselect_b32 s42, s68, s69
	s_cselect_b32 s45, s31, s44
	s_cselect_b32 s44, s35, s43
	s_cselect_b32 s43, s67, s70
	v_lshl_add_u64 v[216:217], s[40:41], 0, v[138:139]
	s_add_i32 m0, s29, 0xc000
	ds_read_b128 v[182:185], v149
	ds_read_b128 v[188:191], v149 offset:1024
	ds_read_b128 v[192:195], v149 offset:2048
	ds_read_b128 v[196:199], v149 offset:3072
	ds_read_b128 v[200:203], v149 offset:4096
	ds_read_b128 v[204:207], v149 offset:5120
	ds_read_b128 v[208:211], v149 offset:6144
	ds_read_b128 v[212:215], v149 offset:7168
	global_load_lds_dwordx4 v[216:217], off
	v_lshl_add_u64 v[216:217], s[40:41], 0, v[136:137]
	s_add_i32 m0, s29, 0xe000
	s_nop 0
	global_load_lds_dwordx4 v[216:217], off
	s_waitcnt vmcnt(8)
	s_waitcnt lgkmcnt(0)
	s_barrier
; #define PG8_STAGE(bufoff, gbase, voff) do { _Pragma("unroll") for (int _i = 0; _i < 2; ++_i) \
;         __builtin_amdgcn_global_load_lds((const unsigned*)((const char*)(gbase) + (voff)[_i]), (PG8_LAS unsigned*)(lds + (bufoff) + ldsw + _i * 8192), 16, 0, 0); } while (0)
; #define PG8_LDA(dst, b, h) do { _Pragma("unroll") for (int m = 0; m < 4; ++m) _Pragma("unroll") for (int k = 0; k < 2; ++k) dst[m][k] = *(const PG8_LAS bf16x8*)(lds + PG8_SA(b, h) + aoff + m * 2048 + k * 1024); } while (0)
; #define PG8_MMA(ai, bj, At, Bt) do { __builtin_amdgcn_s_setprio(1); _Pragma("unroll") for (int m = 0; m < 4; ++m) _Pragma("unroll") for (int n = 0; n < 2; ++n) _Pragma("unroll") for (int k = 0; k < 2; ++k) \
;         acc[ai][bj][m][n] = __builtin_amdgcn_mfma_f32_16x16x32_bf16(Bt[n][k], At[m][k], acc[ai][bj][m][n], 0, 0, 0); __builtin_amdgcn_s_setprio(0); } while (0)
; #define PG8_WAIT_V(n) asm volatile("s_waitcnt vmcnt(" #n ")" ::: "memory")
; #define PG8_WAIT_L(n) asm volatile("s_waitcnt lgkmcnt(" #n ")" ::: "memory")
; #define PG8_BAR __builtin_amdgcn_s_barrier()
; #define PG8_SCHED __builtin_amdgcn_sched_barrier(0)
; template <class Epi, class Sched, bool ALIGN_EPI = false, bool SP2 = false>
; __device__ __forceinline__ void gemm_phase(PG8_LAS unsigned char* lds, const Gemm g, const Sched& S, const Epi& E) {
;     ...
;             PG8_WAIT_V(8); PG8_WAIT_L(0); PG8_BAR; PG8_MMA(0, 0, At, B0); PG8_MMA(0, 1, At, B1); PG8_BAR; PG8_SCHED;
;             PG8_LDA(At, 0, 1); PG8_STAGE(PG8_SB(0, 0), b2, voffB); PG8_STAGE(PG8_SB(0, 1), b2 + hstepB, voffB); PG8_STAGE(PG8_SA(0, 0), a2, voffA);
;             PG8_WAIT_V(8); PG8_WAIT_L(0); PG8_BAR; PG8_MMA(1, 0, At, B0); PG8_MMA(1, 1, At, B1); PG8_BAR; PG8_SCHED;
	s_waitcnt lgkmcnt(0)
	v_mfma_f32_16x16x32_bf16 v[124:127], v[150:153], v[182:185], v[124:127]
	v_mfma_f32_16x16x32_bf16 v[120:123], v[158:161], v[182:185], v[120:123]
	v_mfma_f32_16x16x32_bf16 v[108:111], v[150:153], v[192:195], v[108:111]
	v_mfma_f32_16x16x32_bf16 v[104:107], v[158:161], v[192:195], v[104:107]
	v_mfma_f32_16x16x32_bf16 v[92:95], v[150:153], v[200:203], v[92:95]
	v_mfma_f32_16x16x32_bf16 v[88:91], v[158:161], v[200:203], v[88:91]
	v_mfma_f32_16x16x32_bf16 v[76:79], v[150:153], v[208:211], v[76:79]
	v_mfma_f32_16x16x32_bf16 v[72:75], v[158:161], v[208:211], v[72:75]
	v_mfma_f32_16x16x32_bf16 v[124:127], v[154:157], v[188:191], v[124:127]
	v_mfma_f32_16x16x32_bf16 v[120:123], v[162:165], v[188:191], v[120:123]
	v_mfma_f32_16x16x32_bf16 v[108:111], v[154:157], v[196:199], v[108:111]
	v_mfma_f32_16x16x32_bf16 v[104:107], v[162:165], v[196:199], v[104:107]
	v_mfma_f32_16x16x32_bf16 v[92:95], v[154:157], v[204:207], v[92:95]
	v_mfma_f32_16x16x32_bf16 v[88:91], v[162:165], v[204:207], v[88:91]
	v_mfma_f32_16x16x32_bf16 v[76:79], v[154:157], v[212:215], v[76:79]
	v_mfma_f32_16x16x32_bf16 v[72:75], v[162:165], v[212:215], v[72:75]
	v_mfma_f32_16x16x32_bf16 v[116:119], v[166:169], v[182:185], v[116:119]
	v_mfma_f32_16x16x32_bf16 v[112:115], v[174:177], v[182:185], v[112:115]
	v_mfma_f32_16x16x32_bf16 v[100:103], v[166:169], v[192:195], v[100:103]
	v_mfma_f32_16x16x32_bf16 v[96:99], v[174:177], v[192:195], v[96:99]
	v_mfma_f32_16x16x32_bf16 v[84:87], v[166:169], v[200:203], v[84:87]
	v_mfma_f32_16x16x32_bf16 v[80:83], v[174:177], v[200:203], v[80:83]
	v_mfma_f32_16x16x32_bf16 v[68:71], v[166:169], v[208:211], v[68:71]
	v_mfma_f32_16x16x32_bf16 v[64:67], v[174:177], v[208:211], v[64:67]
	v_mfma_f32_16x16x32_bf16 v[116:119], v[170:173], v[188:191], v[116:119]
	v_mfma_f32_16x16x32_bf16 v[112:115], v[178:181], v[188:191], v[112:115]
	v_mfma_f32_16x16x32_bf16 v[100:103], v[170:173], v[196:199], v[100:103]
	v_mfma_f32_16x16x32_bf16 v[96:99], v[178:181], v[196:199], v[96:99]
	v_mfma_f32_16x16x32_bf16 v[84:87], v[170:173], v[204:207], v[84:87]
	v_mfma_f32_16x16x32_bf16 v[80:83], v[178:181], v[204:207], v[80:83]
	v_mfma_f32_16x16x32_bf16 v[68:71], v[170:173], v[212:215], v[68:71]
	v_mfma_f32_16x16x32_bf16 v[64:67], v[178:181], v[212:215], v[64:67]
	s_barrier
	s_add_i32 s72, s61, s52
	v_lshl_add_u64 v[216:217], s[42:43], 0, v[130:131]
	s_mov_b32 m0, s72
	ds_read_b128 v[182:185], v149 offset:16384
	ds_read_b128 v[188:191], v149 offset:17408
	ds_read_b128 v[192:195], v149 offset:18432
	ds_read_b128 v[196:199], v149 offset:19456
	ds_read_b128 v[200:203], v149 offset:20480
	ds_read_b128 v[204:207], v149 offset:21504
	ds_read_b128 v[208:211], v149 offset:22528
	ds_read_b128 v[212:215], v149 offset:23552
	global_load_lds_dwordx4 v[216:217], off
	s_add_i32 m0, s72, 0x2000
	s_add_u32 s72, s42, 0x10000
	v_lshl_add_u64 v[218:219], s[42:43], 0, v[134:135]
	s_addc_u32 s73, s43, 0
	s_add_i32 s74, s62, s52
	global_load_lds_dwordx4 v[218:219], off
	v_lshl_add_u64 v[220:221], s[72:73], 0, v[130:131]
	s_mov_b32 m0, s74
	v_lshl_add_u64 v[222:223], s[44:45], 0, v[132:133]
	global_load_lds_dwordx4 v[220:221], off
	v_lshl_add_u64 v[220:221], s[72:73], 0, v[134:135]
	s_add_i32 m0, s74, 0x2000
	s_nop 0
	global_load_lds_dwordx4 v[220:221], off
	v_lshl_add_u64 v[220:221], s[44:45], 0, v[128:129]
	s_mov_b32 m0, s29
	s_nop 0
	global_load_lds_dwordx4 v[220:221], off
	s_mov_b32 m0, s53
	s_nop 0
	global_load_lds_dwordx4 v[222:223], off
	s_waitcnt vmcnt(8)
	s_waitcnt lgkmcnt(0)
	s_barrier
	s_waitcnt lgkmcnt(0)
	v_mfma_f32_16x16x32_bf16 v[60:63], v[150:153], v[182:185], v[60:63]
	v_mfma_f32_16x16x32_bf16 v[56:59], v[158:161], v[182:185], v[56:59]
	v_mfma_f32_16x16x32_bf16 v[44:47], v[150:153], v[192:195], v[44:47]
	v_mfma_f32_16x16x32_bf16 v[40:43], v[158:161], v[192:195], v[40:43]
	v_mfma_f32_16x16x32_bf16 v[28:31], v[150:153], v[200:203], v[28:31]
	v_mfma_f32_16x16x32_bf16 v[24:27], v[158:161], v[200:203], v[24:27]
	v_mfma_f32_16x16x32_bf16 v[12:15], v[150:153], v[208:211], v[12:15]
	v_mfma_f32_16x16x32_bf16 v[8:11], v[158:161], v[208:211], v[8:11]
	v_mfma_f32_16x16x32_bf16 v[60:63], v[154:157], v[188:191], v[60:63]
	v_mfma_f32_16x16x32_bf16 v[56:59], v[162:165], v[188:191], v[56:59]
	v_mfma_f32_16x16x32_bf16 v[44:47], v[154:157], v[196:199], v[44:47]
	v_mfma_f32_16x16x32_bf16 v[40:43], v[162:165], v[196:199], v[40:43]
	v_mfma_f32_16x16x32_bf16 v[28:31], v[154:157], v[204:207], v[28:31]
	v_mfma_f32_16x16x32_bf16 v[24:27], v[162:165], v[204:207], v[24:27]
	v_mfma_f32_16x16x32_bf16 v[12:15], v[154:157], v[212:215], v[12:15]
	v_mfma_f32_16x16x32_bf16 v[8:11], v[162:165], v[212:215], v[8:11]
	v_mfma_f32_16x16x32_bf16 v[52:55], v[166:169], v[182:185], v[52:55]
	v_mfma_f32_16x16x32_bf16 v[48:51], v[174:177], v[182:185], v[48:51]
	v_mfma_f32_16x16x32_bf16 v[36:39], v[166:169], v[192:195], v[36:39]
	v_mfma_f32_16x16x32_bf16 v[32:35], v[174:177], v[192:195], v[32:35]
	v_mfma_f32_16x16x32_bf16 v[20:23], v[166:169], v[200:203], v[20:23]
	v_mfma_f32_16x16x32_bf16 v[16:19], v[174:177], v[200:203], v[16:19]
	v_mfma_f32_16x16x32_bf16 v[4:7], v[166:169], v[208:211], v[4:7]
	v_mfma_f32_16x16x32_bf16 v[0:3], v[174:177], v[208:211], v[0:3]
	v_mfma_f32_16x16x32_bf16 v[52:55], v[170:173], v[188:191], v[52:55]
	v_mfma_f32_16x16x32_bf16 v[48:51], v[178:181], v[188:191], v[48:51]
	v_mfma_f32_16x16x32_bf16 v[36:39], v[170:173], v[196:199], v[36:39]
	v_mfma_f32_16x16x32_bf16 v[32:35], v[178:181], v[196:199], v[32:35]
	v_mfma_f32_16x16x32_bf16 v[20:23], v[170:173], v[204:207], v[20:23]
	v_mfma_f32_16x16x32_bf16 v[16:19], v[178:181], v[204:207], v[16:19]
	v_mfma_f32_16x16x32_bf16 v[4:7], v[170:173], v[212:215], v[4:7]
	v_mfma_f32_16x16x32_bf16 v[0:3], v[178:181], v[212:215], v[0:3]
	s_barrier
; #define PG8_STAGE(bufoff, gbase, voff) do { _Pragma("unroll") for (int _i = 0; _i < 2; ++_i) \
;         __builtin_amdgcn_global_load_lds((const unsigned*)((const char*)(gbase) + (voff)[_i]), (PG8_LAS unsigned*)(lds + (bufoff) + ldsw + _i * 8192), 16, 0, 0); } while (0)
; #define PG8_LDA(dst, b, h) do { _Pragma("unroll") for (int m = 0; m < 4; ++m) _Pragma("unroll") for (int k = 0; k < 2; ++k) dst[m][k] = *(const PG8_LAS bf16x8*)(lds + PG8_SA(b, h) + aoff + m * 2048 + k * 1024); } while (0)
; #define PG8_LDB(dst, b, h) do { _Pragma("unroll") for (int n = 0; n < 2; ++n) _Pragma("unroll") for (int k = 0; k < 2; ++k) dst[n][k] = *(const PG8_LAS bf16x8*)(lds + PG8_SB(b, h) + boff + n * 2048 + k * 1024); } while (0)
; #define PG8_MMA(ai, bj, At, Bt) do { __builtin_amdgcn_s_setprio(1); _Pragma("unroll") for (int m = 0; m < 4; ++m) _Pragma("unroll") for (int n = 0; n < 2; ++n) _Pragma("unroll") for (int k = 0; k < 2; ++k) \
;         acc[ai][bj][m][n] = __builtin_amdgcn_mfma_f32_16x16x32_bf16(Bt[n][k], At[m][k], acc[ai][bj][m][n], 0, 0, 0); __builtin_amdgcn_s_setprio(0); } while (0)
; #define PG8_WAIT_V(n) asm volatile("s_waitcnt vmcnt(" #n ")" ::: "memory")
; #define PG8_WAIT_L(n) asm volatile("s_waitcnt lgkmcnt(" #n ")" ::: "memory")
; #define PG8_BAR __builtin_amdgcn_s_barrier()
; #define PG8_SCHED __builtin_amdgcn_sched_barrier(0)
; template <class Epi, class Sched, bool ALIGN_EPI = false, bool SP2 = false>
; __device__ __forceinline__ void gemm_phase(PG8_LAS unsigned char* lds, const Gemm g, const Sched& S, const Epi& E) {
;     ...
;             PG8_LDB(B0, 1, 0); PG8_LDB(B1, 1, 1); PG8_SCHED; PG8_LDA(At, 1, 0); PG8_STAGE(PG8_SA(0, 1), a2 + hstepA, voffA);
;             PG8_WAIT_V(8); PG8_WAIT_L(0); PG8_BAR; PG8_MMA(0, 0, At, B0); PG8_MMA(0, 1, At, B1); PG8_BAR; PG8_SCHED;
;             PG8_LDA(At, 1, 1); PG8_STAGE(PG8_SB(1, 0), b3, voffB); PG8_STAGE(PG8_SB(1, 1), b3 + hstepB, voffB); PG8_STAGE(PG8_SA(1, 0), a3, voffA);
;             PG8_WAIT_V(8); PG8_WAIT_L(0); PG8_BAR; PG8_MMA(1, 0, At, B0); PG8_MMA(1, 1, At, B1); PG8_BAR; PG8_SCHED;
	s_add_i32 s72, 0, 0x18000
	s_add_i32 s73, 0, 0x1c000
	v_add_u32_e32 v162, s72, v145
	v_add_u32_e32 v178, s73, v145
	ds_read_b128 v[150:153], v162
	ds_read_b128 v[154:157], v162 offset:1024
	ds_read_b128 v[158:161], v162 offset:2048
	ds_read_b128 v[162:165], v162 offset:3072
	ds_read_b128 v[166:169], v178
	ds_read_b128 v[170:173], v178 offset:1024
	ds_read_b128 v[174:177], v178 offset:2048
	ds_read_b128 v[178:181], v178 offset:3072
	s_add_u32 s44, s44, 0x10000
	s_addc_u32 s45, s45, 0
	s_mov_b32 m0, s54
	v_lshl_add_u64 v[224:225], s[44:45], 0, v[128:129]
	ds_read_b128 v[182:185], v149 offset:32768
	ds_read_b128 v[188:191], v149 offset:33792
	ds_read_b128 v[192:195], v149 offset:34816
	ds_read_b128 v[196:199], v149 offset:35840
	ds_read_b128 v[200:203], v149 offset:36864
	ds_read_b128 v[204:207], v149 offset:37888
	ds_read_b128 v[208:211], v149 offset:38912
	ds_read_b128 v[212:215], v149 offset:39936
	global_load_lds_dwordx4 v[224:225], off
	v_lshl_add_u64 v[224:225], s[44:45], 0, v[132:133]
	s_mov_b32 m0, s55
	s_nop 0
	global_load_lds_dwordx4 v[224:225], off
	s_waitcnt vmcnt(8)
	s_waitcnt lgkmcnt(0)
	s_barrier
	s_waitcnt lgkmcnt(0)
	v_mfma_f32_16x16x32_bf16 v[124:127], v[150:153], v[182:185], v[124:127]
	v_mfma_f32_16x16x32_bf16 v[120:123], v[158:161], v[182:185], v[120:123]
	v_mfma_f32_16x16x32_bf16 v[108:111], v[150:153], v[192:195], v[108:111]
	v_mfma_f32_16x16x32_bf16 v[104:107], v[158:161], v[192:195], v[104:107]
	v_mfma_f32_16x16x32_bf16 v[92:95], v[150:153], v[200:203], v[92:95]
	v_mfma_f32_16x16x32_bf16 v[88:91], v[158:161], v[200:203], v[88:91]
	v_mfma_f32_16x16x32_bf16 v[76:79], v[150:153], v[208:211], v[76:79]
	v_mfma_f32_16x16x32_bf16 v[72:75], v[158:161], v[208:211], v[72:75]
	v_mfma_f32_16x16x32_bf16 v[124:127], v[154:157], v[188:191], v[124:127]
	v_mfma_f32_16x16x32_bf16 v[120:123], v[162:165], v[188:191], v[120:123]
	v_mfma_f32_16x16x32_bf16 v[108:111], v[154:157], v[196:199], v[108:111]
	v_mfma_f32_16x16x32_bf16 v[104:107], v[162:165], v[196:199], v[104:107]
	v_mfma_f32_16x16x32_bf16 v[92:95], v[154:157], v[204:207], v[92:95]
	v_mfma_f32_16x16x32_bf16 v[88:91], v[162:165], v[204:207], v[88:91]
	v_mfma_f32_16x16x32_bf16 v[76:79], v[154:157], v[212:215], v[76:79]
	v_mfma_f32_16x16x32_bf16 v[72:75], v[162:165], v[212:215], v[72:75]
	v_mfma_f32_16x16x32_bf16 v[116:119], v[166:169], v[182:185], v[116:119]
	v_mfma_f32_16x16x32_bf16 v[112:115], v[174:177], v[182:185], v[112:115]
	v_mfma_f32_16x16x32_bf16 v[100:103], v[166:169], v[192:195], v[100:103]
	v_mfma_f32_16x16x32_bf16 v[96:99], v[174:177], v[192:195], v[96:99]
	v_mfma_f32_16x16x32_bf16 v[84:87], v[166:169], v[200:203], v[84:87]
	v_mfma_f32_16x16x32_bf16 v[80:83], v[174:177], v[200:203], v[80:83]
	v_mfma_f32_16x16x32_bf16 v[68:71], v[166:169], v[208:211], v[68:71]
	v_mfma_f32_16x16x32_bf16 v[64:67], v[174:177], v[208:211], v[64:67]
	v_mfma_f32_16x16x32_bf16 v[116:119], v[170:173], v[188:191], v[116:119]
	v_mfma_f32_16x16x32_bf16 v[112:115], v[178:181], v[188:191], v[112:115]
	v_mfma_f32_16x16x32_bf16 v[100:103], v[170:173], v[196:199], v[100:103]
	v_mfma_f32_16x16x32_bf16 v[96:99], v[178:181], v[196:199], v[96:99]
	v_mfma_f32_16x16x32_bf16 v[84:87], v[170:173], v[204:207], v[84:87]
	v_mfma_f32_16x16x32_bf16 v[80:83], v[178:181], v[204:207], v[80:83]
	v_mfma_f32_16x16x32_bf16 v[68:71], v[170:173], v[212:215], v[68:71]
	v_mfma_f32_16x16x32_bf16 v[64:67], v[178:181], v[212:215], v[64:67]
	s_barrier
	s_add_i32 s44, s72, s52
	v_lshl_add_u64 v[216:217], v[216:217], 0, s[16:17]
	s_mov_b32 m0, s44
	ds_read_b128 v[182:185], v149 offset:49152
	ds_read_b128 v[188:191], v149 offset:50176
	ds_read_b128 v[192:195], v149 offset:51200
	ds_read_b128 v[196:199], v149 offset:52224
	ds_read_b128 v[200:203], v149 offset:53248
	ds_read_b128 v[204:207], v149 offset:54272
	ds_read_b128 v[208:211], v149 offset:55296
	ds_read_b128 v[212:215], v149 offset:56320
	global_load_lds_dwordx4 v[216:217], off
	s_add_i32 m0, s44, 0x2000
	s_add_u32 s42, s42, 0x10080
	v_lshl_add_u64 v[216:217], v[218:219], 0, s[16:17]
	s_addc_u32 s43, s43, 0
	s_add_i32 s44, s73, s52
	global_load_lds_dwordx4 v[216:217], off
	v_lshl_add_u64 v[216:217], s[42:43], 0, v[130:131]
	s_mov_b32 m0, s44
	s_nop 0
	global_load_lds_dwordx4 v[216:217], off
	v_lshl_add_u64 v[216:217], s[42:43], 0, v[134:135]
	s_add_i32 m0, s44, 0x2000
	s_nop 0
	global_load_lds_dwordx4 v[216:217], off
	v_lshl_add_u64 v[216:217], v[220:221], 0, s[16:17]
	s_mov_b32 m0, s58
	s_nop 0
	global_load_lds_dwordx4 v[216:217], off
	v_lshl_add_u64 v[216:217], v[222:223], 0, s[16:17]
	s_mov_b32 m0, s59
	s_nop 0
	global_load_lds_dwordx4 v[216:217], off
	s_waitcnt vmcnt(8)
	s_waitcnt lgkmcnt(0)
	s_barrier
	s_waitcnt lgkmcnt(0)
	v_mfma_f32_16x16x32_bf16 v[60:63], v[150:153], v[182:185], v[60:63]
	v_mfma_f32_16x16x32_bf16 v[56:59], v[158:161], v[182:185], v[56:59]
	v_mfma_f32_16x16x32_bf16 v[44:47], v[150:153], v[192:195], v[44:47]
	v_mfma_f32_16x16x32_bf16 v[40:43], v[158:161], v[192:195], v[40:43]
	v_mfma_f32_16x16x32_bf16 v[28:31], v[150:153], v[200:203], v[28:31]
	v_mfma_f32_16x16x32_bf16 v[24:27], v[158:161], v[200:203], v[24:27]
	v_mfma_f32_16x16x32_bf16 v[12:15], v[150:153], v[208:211], v[12:15]
	v_mfma_f32_16x16x32_bf16 v[8:11], v[158:161], v[208:211], v[8:11]
	v_mfma_f32_16x16x32_bf16 v[60:63], v[154:157], v[188:191], v[60:63]
	v_mfma_f32_16x16x32_bf16 v[56:59], v[162:165], v[188:191], v[56:59]
	v_mfma_f32_16x16x32_bf16 v[44:47], v[154:157], v[196:199], v[44:47]
	v_mfma_f32_16x16x32_bf16 v[40:43], v[162:165], v[196:199], v[40:43]
	v_mfma_f32_16x16x32_bf16 v[28:31], v[154:157], v[204:207], v[28:31]
	v_mfma_f32_16x16x32_bf16 v[24:27], v[162:165], v[204:207], v[24:27]
	v_mfma_f32_16x16x32_bf16 v[12:15], v[154:157], v[212:215], v[12:15]
	v_mfma_f32_16x16x32_bf16 v[8:11], v[162:165], v[212:215], v[8:11]
	v_mfma_f32_16x16x32_bf16 v[52:55], v[166:169], v[182:185], v[52:55]
	v_mfma_f32_16x16x32_bf16 v[48:51], v[174:177], v[182:185], v[48:51]
	v_mfma_f32_16x16x32_bf16 v[36:39], v[166:169], v[192:195], v[36:39]
	v_mfma_f32_16x16x32_bf16 v[32:35], v[174:177], v[192:195], v[32:35]
	v_mfma_f32_16x16x32_bf16 v[20:23], v[166:169], v[200:203], v[20:23]
	v_mfma_f32_16x16x32_bf16 v[16:19], v[174:177], v[200:203], v[16:19]
	v_mfma_f32_16x16x32_bf16 v[4:7], v[166:169], v[208:211], v[4:7]
	v_mfma_f32_16x16x32_bf16 v[0:3], v[174:177], v[208:211], v[0:3]
	v_mfma_f32_16x16x32_bf16 v[52:55], v[170:173], v[188:191], v[52:55]
	v_mfma_f32_16x16x32_bf16 v[48:51], v[178:181], v[188:191], v[48:51]
	v_mfma_f32_16x16x32_bf16 v[36:39], v[170:173], v[196:199], v[36:39]
	v_mfma_f32_16x16x32_bf16 v[32:35], v[178:181], v[196:199], v[32:35]
	v_mfma_f32_16x16x32_bf16 v[20:23], v[170:173], v[204:207], v[20:23]
	v_mfma_f32_16x16x32_bf16 v[16:19], v[178:181], v[204:207], v[16:19]
	v_mfma_f32_16x16x32_bf16 v[4:7], v[170:173], v[212:215], v[4:7]
	v_mfma_f32_16x16x32_bf16 v[0:3], v[178:181], v[212:215], v[0:3]
	s_barrier
	s_add_u32 s69, s69, 0x100
	s_addc_u32 s70, s70, 0
	s_add_u32 s40, s40, 0x100
	s_addc_u32 s41, s41, 0
	s_cmp_ge_i32 s71, s57
	s_mov_b32 s42, s71
	s_cbranch_scc0 .LBB0_988
; #define PG8_BAR __builtin_amdgcn_s_barrier()
; template <class Epi, class Sched, bool ALIGN_EPI = false, bool SP2 = false>
; __device__ __forceinline__ void gemm_phase(PG8_LAS unsigned char* lds, const Gemm g, const Sched& S, const Epi& E) {
;     ...
;         if constexpr (ALIGN_EPI) { if (wr == 0) PG8_BAR; }
.LBB0_989:
	s_and_b64 vcc, exec, s[18:19]
	s_cbranch_vccz .LBB0_991
	s_barrier

;     __host__ __device__ bool next(int i, Unit& u) const { return i < cnt ? so.next(base + i, u) : false; }
;     __host__ __device__ bool next(int i, Unit& u) const { const int L = i * G + c; if (L >= 32) return false; u.g = L >> 3; u.pm = L & 7; u.pn = 0; return true; }
; #define PG8_STAGE(bufoff, gbase, voff) do { _Pragma("unroll") for (int _i = 0; _i < 2; ++_i) \
;         __builtin_amdgcn_global_load_lds((const unsigned*)((const char*)(gbase) + (voff)[_i]), (PG8_LAS unsigned*)(lds + (bufoff) + ldsw + _i * 8192), 16, 0, 0); } while (0)
; #define PG8_WAIT_V(n) asm volatile("s_waitcnt vmcnt(" #n ")" ::: "memory")
; #define PG8_WAIT_L(n) asm volatile("s_waitcnt lgkmcnt(" #n ")" ::: "memory")
; #define PG8_BAR __builtin_amdgcn_s_barrier()
; template <class Epi, class Sched, bool ALIGN_EPI = false, bool SP2 = false>
; __device__ __forceinline__ void gemm_phase(PG8_LAS unsigned char* lds, const Gemm g, const Sched& S, const Epi& E) {
;     ...
;     for (;;) {
;         const bool has_next = S.next(ui + 1, nxt);
;         const char* nA = has_next ? (const char*)(g.A + (size_t)nxt.g * g.gsA) + (size_t)nxt.pm * tstepA : cA; const char* nB = has_next ? (const char*)(g.Bt + (size_t)nxt.g * g.gsB) + (size_t)nxt.pn * tstepB : cB;
;         for (int t = 0; t < nt; t += 2) {
;             if constexpr (Epi::MIDK) { if (t == (nt >> 1)) { asm volatile("s_waitcnt vmcnt(0)" ::: "memory"); E.mid(acc, cur, wr, wc, fr, fq); asm volatile("s_waitcnt vmcnt(0)" ::: "memory"); } }
;             const bool last = (t == nt - 2);
;             const char* a1 = cA + (size_t)(t + 1) * kstep;
;             const char* a2 = last ? nA : cA + (size_t)(t + 2) * kstep; const char* b2 = last ? nB : cB + (size_t)(t + 2) * kstep;
;             const char* a3 = a2 + kstep; const char* b3 = b2 + kstep;
;             if (last && has_next) S.a_ready(nxt);
;             if constexpr (SP2) {
;             PG8_LDB(B0, 0, 0); PG8_LDB(B1, 0, 1); PG8_SCHED; PG8_LDA(At, 0, 0); PG8_STAGE(PG8_SA(1, 1), a1 + hstepA, voffA);
;             PG8_WAIT_V(8); PG8_WAIT_L(0); PG8_BAR; PG8_MMA(0, 0, At, B0); PG8_MMA(0, 1, At, B1); PG8_BAR; PG8_SCHED;
;             PG8_LDA(At, 0, 1); PG8_STAGE(PG8_SB(0, 0), b2, voffB); PG8_STAGE(PG8_SB(0, 1), b2 + hstepB, voffB); PG8_STAGE(PG8_SA(0, 0), a2, voffA);
;             PG8_WAIT_V(8); PG8_WAIT_L(0); PG8_BAR; PG8_MMA(1, 0, At, B0); PG8_MMA(1, 1, At, B1); PG8_BAR; PG8_SCHED;
.LBB0_1012:
	s_ashr_i32 s29, s28, 31
	s_lshl_b64 s[30:31], s[28:29], 20
	s_add_u32 s30, s16, s30
	s_addc_u32 s31, s17, s31
	s_ashr_i32 s27, s26, 31
	s_lshl_b64 s[34:35], s[26:27], 20
	s_add_u32 s34, s44, s34
	s_addc_u32 s35, s45, s35
	s_andn2_b64 vcc, exec, s[24:25]
	s_cbranch_vccnz .LBB0_1015
	s_and_b64 s[36:37], s[6:7], exec
	s_cselect_b32 s27, s31, s21
	s_cselect_b32 s29, s30, s20
	s_cselect_b32 s62, s35, s19
	s_cselect_b32 s63, s34, s18
	s_add_u32 s64, s18, 0x100
	s_addc_u32 s65, s19, 0
	s_add_u32 s36, s20, 0x80080
	s_addc_u32 s37, s21, 0
	s_mov_b32 s38, 0
.LBB0_1014:
	v_add_u32_e32 v113, s58, v149
	ds_read_b128 v[158:161], v113
	ds_read_b128 v[162:165], v113 offset:1024
	ds_read_b128 v[166:169], v113 offset:2048
	ds_read_b128 v[170:173], v113 offset:3072
	v_add_u32_e32 v113, s59, v149
	ds_read_b128 v[174:177], v113
	ds_read_b128 v[178:181], v113 offset:1024
	ds_read_b128 v[182:185], v113 offset:2048
	ds_read_b128 v[188:191], v113 offset:3072
	s_add_i32 s66, s38, 2
	s_add_u32 s39, s36, 0xfff80080
	s_addc_u32 s40, s37, -1
	s_cmp_eq_u32 s56, s38
	s_cselect_b32 s38, s63, s64
	s_cselect_b32 s41, s27, s40
	s_cselect_b32 s40, s29, s39
	s_cselect_b32 s39, s62, s65
	v_lshl_add_u64 v[114:115], s[36:37], 0, v[142:143]
	s_add_i32 m0, s13, 0xc000
	ds_read_b128 v[192:195], v150
	ds_read_b128 v[196:199], v150 offset:1024
	ds_read_b128 v[200:203], v150 offset:2048
	ds_read_b128 v[204:207], v150 offset:3072
	ds_read_b128 v[208:211], v150 offset:4096
	ds_read_b128 v[212:215], v150 offset:5120
	ds_read_b128 v[216:219], v150 offset:6144
	ds_read_b128 v[220:223], v150 offset:7168
	global_load_lds_dwordx4 v[114:115], off
	v_lshl_add_u64 v[114:115], s[36:37], 0, v[140:141]
	s_add_i32 m0, s13, 0xe000
	s_nop 0
	global_load_lds_dwordx4 v[114:115], off
	s_waitcnt vmcnt(8)
	s_waitcnt lgkmcnt(0)
	s_barrier
	s_waitcnt lgkmcnt(0)
	v_mfma_f32_16x16x32_bf16 v[128:131], v[158:161], v[192:195], v[128:131]
	v_mfma_f32_16x16x32_bf16 v[124:127], v[166:169], v[192:195], v[124:127]
	v_mfma_f32_16x16x32_bf16 v[108:111], v[158:161], v[200:203], v[108:111]
	v_mfma_f32_16x16x32_bf16 v[104:107], v[166:169], v[200:203], v[104:107]
	v_mfma_f32_16x16x32_bf16 v[92:95], v[158:161], v[208:211], v[92:95]
	v_mfma_f32_16x16x32_bf16 v[88:91], v[166:169], v[208:211], v[88:91]
	v_mfma_f32_16x16x32_bf16 v[76:79], v[158:161], v[216:219], v[76:79]
	v_mfma_f32_16x16x32_bf16 v[72:75], v[166:169], v[216:219], v[72:75]
	v_mfma_f32_16x16x32_bf16 v[128:131], v[162:165], v[196:199], v[128:131]
	v_mfma_f32_16x16x32_bf16 v[124:127], v[170:173], v[196:199], v[124:127]
	v_mfma_f32_16x16x32_bf16 v[108:111], v[162:165], v[204:207], v[108:111]
	v_mfma_f32_16x16x32_bf16 v[104:107], v[170:173], v[204:207], v[104:107]
	v_mfma_f32_16x16x32_bf16 v[92:95], v[162:165], v[212:215], v[92:95]
	v_mfma_f32_16x16x32_bf16 v[88:91], v[170:173], v[212:215], v[88:91]
	v_mfma_f32_16x16x32_bf16 v[76:79], v[162:165], v[220:223], v[76:79]
	v_mfma_f32_16x16x32_bf16 v[72:75], v[170:173], v[220:223], v[72:75]
	v_mfma_f32_16x16x32_bf16 v[120:123], v[174:177], v[192:195], v[120:123]
	v_mfma_f32_16x16x32_bf16 v[114:117], v[182:185], v[192:195], v[116:119]
	v_mfma_f32_16x16x32_bf16 v[100:103], v[174:177], v[200:203], v[100:103]
	v_mfma_f32_16x16x32_bf16 v[96:99], v[182:185], v[200:203], v[96:99]
	v_mfma_f32_16x16x32_bf16 v[84:87], v[174:177], v[208:211], v[84:87]
	v_mfma_f32_16x16x32_bf16 v[80:83], v[182:185], v[208:211], v[80:83]
	v_mfma_f32_16x16x32_bf16 v[68:71], v[174:177], v[216:219], v[68:71]
	v_mfma_f32_16x16x32_bf16 v[64:67], v[182:185], v[216:219], v[64:67]
	v_mfma_f32_16x16x32_bf16 v[120:123], v[178:181], v[196:199], v[120:123]
	v_mfma_f32_16x16x32_bf16 v[114:117], v[188:191], v[196:199], v[114:117]
	v_mfma_f32_16x16x32_bf16 v[100:103], v[178:181], v[204:207], v[100:103]
	v_mfma_f32_16x16x32_bf16 v[96:99], v[188:191], v[204:207], v[96:99]
	v_mfma_f32_16x16x32_bf16 v[84:87], v[178:181], v[212:215], v[84:87]
	v_mfma_f32_16x16x32_bf16 v[80:83], v[188:191], v[212:215], v[80:83]
	v_mfma_f32_16x16x32_bf16 v[68:71], v[178:181], v[220:223], v[68:71]
	v_mfma_f32_16x16x32_bf16 v[64:67], v[188:191], v[220:223], v[64:67]
	s_barrier
	s_add_i32 s67, s58, s43
	v_lshl_add_u64 v[152:153], s[38:39], 0, v[134:135]
	s_mov_b32 m0, s67
	ds_read_b128 v[192:195], v150 offset:16384
	ds_read_b128 v[196:199], v150 offset:17408
	ds_read_b128 v[200:203], v150 offset:18432
	ds_read_b128 v[204:207], v150 offset:19456
	ds_read_b128 v[208:211], v150 offset:20480
	ds_read_b128 v[212:215], v150 offset:21504
	ds_read_b128 v[216:219], v150 offset:22528
	ds_read_b128 v[220:223], v150 offset:23552
	global_load_lds_dwordx4 v[152:153], off
	s_add_i32 m0, s67, 0x2000
	s_add_u32 s68, s38, 0x80000
	v_lshl_add_u64 v[224:225], s[38:39], 0, v[138:139]
	s_addc_u32 s69, s39, 0
	s_add_i32 s67, s59, s43
	global_load_lds_dwordx4 v[224:225], off
	v_lshl_add_u64 v[118:119], s[68:69], 0, v[134:135]
	s_mov_b32 m0, s67
	v_lshl_add_u64 v[226:227], s[40:41], 0, v[132:133]
	global_load_lds_dwordx4 v[118:119], off
	v_lshl_add_u64 v[118:119], s[68:69], 0, v[138:139]
	s_add_i32 m0, s67, 0x2000
	v_lshl_add_u64 v[228:229], s[40:41], 0, v[136:137]
	global_load_lds_dwordx4 v[118:119], off
	s_mov_b32 m0, s13
	s_nop 0
	global_load_lds_dwordx4 v[226:227], off
	s_mov_b32 m0, s48
	s_nop 0
	global_load_lds_dwordx4 v[228:229], off
	s_waitcnt vmcnt(8)
	s_waitcnt lgkmcnt(0)
	s_barrier
; #define PG8_STAGE(bufoff, gbase, voff) do { _Pragma("unroll") for (int _i = 0; _i < 2; ++_i) \
;         __builtin_amdgcn_global_load_lds((const unsigned*)((const char*)(gbase) + (voff)[_i]), (PG8_LAS unsigned*)(lds + (bufoff) + ldsw + _i * 8192), 16, 0, 0); } while (0)
; #define PG8_LDA(dst, b, h) do { _Pragma("unroll") for (int m = 0; m < 4; ++m) _Pragma("unroll") for (int k = 0; k < 2; ++k) dst[m][k] = *(const PG8_LAS bf16x8*)(lds + PG8_SA(b, h) + aoff + m * 2048 + k * 1024); } while (0)
; #define PG8_LDB(dst, b, h) do { _Pragma("unroll") for (int n = 0; n < 2; ++n) _Pragma("unroll") for (int k = 0; k < 2; ++k) dst[n][k] = *(const PG8_LAS bf16x8*)(lds + PG8_SB(b, h) + boff + n * 2048 + k * 1024); } while (0)
; #define PG8_MMA(ai, bj, At, Bt) do { __builtin_amdgcn_s_setprio(1); _Pragma("unroll") for (int m = 0; m < 4; ++m) _Pragma("unroll") for (int n = 0; n < 2; ++n) _Pragma("unroll") for (int k = 0; k < 2; ++k) \
;         acc[ai][bj][m][n] = __builtin_amdgcn_mfma_f32_16x16x32_bf16(Bt[n][k], At[m][k], acc[ai][bj][m][n], 0, 0, 0); __builtin_amdgcn_s_setprio(0); } while (0)
; #define PG8_WAIT_V(n) asm volatile("s_waitcnt vmcnt(" #n ")" ::: "memory")
; #define PG8_WAIT_L(n) asm volatile("s_waitcnt lgkmcnt(" #n ")" ::: "memory")
; #define PG8_BAR __builtin_amdgcn_s_barrier()
; #define PG8_SCHED __builtin_amdgcn_sched_barrier(0)
; template <class Epi, class Sched, bool ALIGN_EPI = false, bool SP2 = false>
; __device__ __forceinline__ void gemm_phase(PG8_LAS unsigned char* lds, const Gemm g, const Sched& S, const Epi& E) {
;     ...
;             PG8_WAIT_V(8); PG8_WAIT_L(0); PG8_BAR; PG8_MMA(0, 0, At, B0); PG8_MMA(0, 1, At, B1); PG8_BAR; PG8_SCHED;
;             PG8_LDA(At, 0, 1); PG8_STAGE(PG8_SB(0, 0), b2, voffB); PG8_STAGE(PG8_SB(0, 1), b2 + hstepB, voffB); PG8_STAGE(PG8_SA(0, 0), a2, voffA);
;             PG8_WAIT_V(8); PG8_WAIT_L(0); PG8_BAR; PG8_MMA(1, 0, At, B0); PG8_MMA(1, 1, At, B1); PG8_BAR; PG8_SCHED;
;             PG8_LDB(B0, 1, 0); PG8_LDB(B1, 1, 1); PG8_SCHED; PG8_LDA(At, 1, 0); PG8_STAGE(PG8_SA(0, 1), a2 + hstepA, voffA);
;             PG8_WAIT_V(8); PG8_WAIT_L(0); PG8_BAR; PG8_MMA(0, 0, At, B0); PG8_MMA(0, 1, At, B1); PG8_BAR; PG8_SCHED;
	s_waitcnt lgkmcnt(0)
	v_mfma_f32_16x16x32_bf16 v[60:63], v[158:161], v[192:195], v[60:63]
	v_mfma_f32_16x16x32_bf16 v[56:59], v[166:169], v[192:195], v[56:59]
	v_mfma_f32_16x16x32_bf16 v[44:47], v[158:161], v[200:203], v[44:47]
	v_mfma_f32_16x16x32_bf16 v[40:43], v[166:169], v[200:203], v[40:43]
	v_mfma_f32_16x16x32_bf16 v[28:31], v[158:161], v[208:211], v[28:31]
	v_mfma_f32_16x16x32_bf16 v[24:27], v[166:169], v[208:211], v[24:27]
	v_mfma_f32_16x16x32_bf16 v[12:15], v[158:161], v[216:219], v[12:15]
	v_mfma_f32_16x16x32_bf16 v[8:11], v[166:169], v[216:219], v[8:11]
	v_mfma_f32_16x16x32_bf16 v[60:63], v[162:165], v[196:199], v[60:63]
	v_mfma_f32_16x16x32_bf16 v[56:59], v[170:173], v[196:199], v[56:59]
	v_mfma_f32_16x16x32_bf16 v[44:47], v[162:165], v[204:207], v[44:47]
	v_mfma_f32_16x16x32_bf16 v[40:43], v[170:173], v[204:207], v[40:43]
	v_mfma_f32_16x16x32_bf16 v[28:31], v[162:165], v[212:215], v[28:31]
	v_mfma_f32_16x16x32_bf16 v[24:27], v[170:173], v[212:215], v[24:27]
	v_mfma_f32_16x16x32_bf16 v[12:15], v[162:165], v[220:223], v[12:15]
	v_mfma_f32_16x16x32_bf16 v[8:11], v[170:173], v[220:223], v[8:11]
	v_mfma_f32_16x16x32_bf16 v[52:55], v[174:177], v[192:195], v[52:55]
	v_mfma_f32_16x16x32_bf16 v[48:51], v[182:185], v[192:195], v[48:51]
	v_mfma_f32_16x16x32_bf16 v[36:39], v[174:177], v[200:203], v[36:39]
	v_mfma_f32_16x16x32_bf16 v[32:35], v[182:185], v[200:203], v[32:35]
	v_mfma_f32_16x16x32_bf16 v[20:23], v[174:177], v[208:211], v[20:23]
	v_mfma_f32_16x16x32_bf16 v[16:19], v[182:185], v[208:211], v[16:19]
	v_mfma_f32_16x16x32_bf16 v[4:7], v[174:177], v[216:219], v[4:7]
	v_mfma_f32_16x16x32_bf16 v[0:3], v[182:185], v[216:219], v[0:3]
	v_mfma_f32_16x16x32_bf16 v[52:55], v[178:181], v[196:199], v[52:55]
	v_mfma_f32_16x16x32_bf16 v[48:51], v[188:191], v[196:199], v[48:51]
	v_mfma_f32_16x16x32_bf16 v[36:39], v[178:181], v[204:207], v[36:39]
	v_mfma_f32_16x16x32_bf16 v[32:35], v[188:191], v[204:207], v[32:35]
	v_mfma_f32_16x16x32_bf16 v[20:23], v[178:181], v[212:215], v[20:23]
	v_mfma_f32_16x16x32_bf16 v[16:19], v[188:191], v[212:215], v[16:19]
	v_mfma_f32_16x16x32_bf16 v[4:7], v[178:181], v[220:223], v[4:7]
	v_mfma_f32_16x16x32_bf16 v[0:3], v[188:191], v[220:223], v[0:3]
	s_barrier
	s_add_i32 s67, 0, 0x18000
	v_add_u32_e32 v113, s67, v149
	s_add_i32 s68, 0, 0x1c000
	ds_read_b128 v[158:161], v113
	ds_read_b128 v[162:165], v113 offset:1024
	ds_read_b128 v[166:169], v113 offset:2048
	ds_read_b128 v[170:173], v113 offset:3072
	v_add_u32_e32 v113, s68, v149
	ds_read_b128 v[174:177], v113
	ds_read_b128 v[178:181], v113 offset:1024
	ds_read_b128 v[182:185], v113 offset:2048
	ds_read_b128 v[188:191], v113 offset:3072
	s_add_u32 s40, s40, 0x80000
	s_addc_u32 s41, s41, 0
	s_mov_b32 m0, s49
	v_lshl_add_u64 v[118:119], s[40:41], 0, v[132:133]
	ds_read_b128 v[192:195], v150 offset:32768
	ds_read_b128 v[196:199], v150 offset:33792
	ds_read_b128 v[200:203], v150 offset:34816
	ds_read_b128 v[204:207], v150 offset:35840
	ds_read_b128 v[208:211], v150 offset:36864
	ds_read_b128 v[212:215], v150 offset:37888
	ds_read_b128 v[216:219], v150 offset:38912
	ds_read_b128 v[220:223], v150 offset:39936
	global_load_lds_dwordx4 v[118:119], off
	v_lshl_add_u64 v[118:119], s[40:41], 0, v[136:137]
	s_mov_b32 m0, s50
	s_nop 0
	global_load_lds_dwordx4 v[118:119], off
	s_waitcnt vmcnt(8)
	s_waitcnt lgkmcnt(0)
	s_barrier
	s_waitcnt lgkmcnt(0)
	v_mfma_f32_16x16x32_bf16 v[128:131], v[158:161], v[192:195], v[128:131]
	v_mfma_f32_16x16x32_bf16 v[124:127], v[166:169], v[192:195], v[124:127]
	v_mfma_f32_16x16x32_bf16 v[108:111], v[158:161], v[200:203], v[108:111]
	v_mfma_f32_16x16x32_bf16 v[104:107], v[166:169], v[200:203], v[104:107]
	v_mfma_f32_16x16x32_bf16 v[92:95], v[158:161], v[208:211], v[92:95]
	v_mfma_f32_16x16x32_bf16 v[88:91], v[166:169], v[208:211], v[88:91]
	v_mfma_f32_16x16x32_bf16 v[76:79], v[158:161], v[216:219], v[76:79]
	v_mfma_f32_16x16x32_bf16 v[72:75], v[166:169], v[216:219], v[72:75]
	v_mfma_f32_16x16x32_bf16 v[128:131], v[162:165], v[196:199], v[128:131]
	v_mfma_f32_16x16x32_bf16 v[124:127], v[170:173], v[196:199], v[124:127]
	v_mfma_f32_16x16x32_bf16 v[108:111], v[162:165], v[204:207], v[108:111]
	v_mfma_f32_16x16x32_bf16 v[104:107], v[170:173], v[204:207], v[104:107]
	v_mfma_f32_16x16x32_bf16 v[92:95], v[162:165], v[212:215], v[92:95]
	v_mfma_f32_16x16x32_bf16 v[88:91], v[170:173], v[212:215], v[88:91]
	v_mfma_f32_16x16x32_bf16 v[76:79], v[162:165], v[220:223], v[76:79]
	v_mfma_f32_16x16x32_bf16 v[72:75], v[170:173], v[220:223], v[72:75]
	v_mfma_f32_16x16x32_bf16 v[118:121], v[174:177], v[192:195], v[120:123]
	v_mfma_f32_16x16x32_bf16 v[114:117], v[182:185], v[192:195], v[114:117]
	v_mfma_f32_16x16x32_bf16 v[100:103], v[174:177], v[200:203], v[100:103]
	v_mfma_f32_16x16x32_bf16 v[96:99], v[182:185], v[200:203], v[96:99]
	v_mfma_f32_16x16x32_bf16 v[84:87], v[174:177], v[208:211], v[84:87]
	v_mfma_f32_16x16x32_bf16 v[80:83], v[182:185], v[208:211], v[80:83]
	v_mfma_f32_16x16x32_bf16 v[68:71], v[174:177], v[216:219], v[68:71]
	v_mfma_f32_16x16x32_bf16 v[64:67], v[182:185], v[216:219], v[64:67]
	v_mfma_f32_16x16x32_bf16 v[120:123], v[178:181], v[196:199], v[118:121]
	v_mfma_f32_16x16x32_bf16 v[116:119], v[188:191], v[196:199], v[114:117]
	v_mfma_f32_16x16x32_bf16 v[100:103], v[178:181], v[204:207], v[100:103]
	v_mfma_f32_16x16x32_bf16 v[96:99], v[188:191], v[204:207], v[96:99]
	v_mfma_f32_16x16x32_bf16 v[84:87], v[178:181], v[212:215], v[84:87]
	v_mfma_f32_16x16x32_bf16 v[80:83], v[188:191], v[212:215], v[80:83]
	v_mfma_f32_16x16x32_bf16 v[68:71], v[178:181], v[220:223], v[68:71]
	v_mfma_f32_16x16x32_bf16 v[64:67], v[188:191], v[220:223], v[64:67]
	s_barrier
; #define PG8_STAGE(bufoff, gbase, voff) do { _Pragma("unroll") for (int _i = 0; _i < 2; ++_i) \
;         __builtin_amdgcn_global_load_lds((const unsigned*)((const char*)(gbase) + (voff)[_i]), (PG8_LAS unsigned*)(lds + (bufoff) + ldsw + _i * 8192), 16, 0, 0); } while (0)
; #define PG8_LDA(dst, b, h) do { _Pragma("unroll") for (int m = 0; m < 4; ++m) _Pragma("unroll") for (int k = 0; k < 2; ++k) dst[m][k] = *(const PG8_LAS bf16x8*)(lds + PG8_SA(b, h) + aoff + m * 2048 + k * 1024); } while (0)
; #define PG8_LDB(dst, b, h) do { _Pragma("unroll") for (int n = 0; n < 2; ++n) _Pragma("unroll") for (int k = 0; k < 2; ++k) dst[n][k] = *(const PG8_LAS bf16x8*)(lds + PG8_SB(b, h) + boff + n * 2048 + k * 1024); } while (0)
; #define PG8_MMA(ai, bj, At, Bt) do { __builtin_amdgcn_s_setprio(1); _Pragma("unroll") for (int m = 0; m < 4; ++m) _Pragma("unroll") for (int n = 0; n < 2; ++n) _Pragma("unroll") for (int k = 0; k < 2; ++k) \
;         acc[ai][bj][m][n] = __builtin_amdgcn_mfma_f32_16x16x32_bf16(Bt[n][k], At[m][k], acc[ai][bj][m][n], 0, 0, 0); __builtin_amdgcn_s_setprio(0); } while (0)
; #define PG8_WAIT_V(n) asm volatile("s_waitcnt vmcnt(" #n ")" ::: "memory")
; #define PG8_WAIT_L(n) asm volatile("s_waitcnt lgkmcnt(" #n ")" ::: "memory")
; #define PG8_BAR __builtin_amdgcn_s_barrier()
; template <class Epi, class Sched, bool ALIGN_EPI = false, bool SP2 = false>
; __device__ __forceinline__ void gemm_phase(PG8_LAS unsigned char* lds, const Gemm g, const Sched& S, const Epi& E) {
;     ...
;             PG8_LDB(B0, 1, 0); PG8_LDB(B1, 1, 1); PG8_SCHED; PG8_LDA(At, 1, 0); PG8_STAGE(PG8_SA(0, 1), a2 + hstepA, voffA);
;             PG8_WAIT_V(8); PG8_WAIT_L(0); PG8_BAR; PG8_MMA(0, 0, At, B0); PG8_MMA(0, 1, At, B1); PG8_BAR; PG8_SCHED;
;             PG8_LDA(At, 1, 1); PG8_STAGE(PG8_SB(1, 0), b3, voffB); PG8_STAGE(PG8_SB(1, 1), b3 + hstepB, voffB); PG8_STAGE(PG8_SA(1, 0), a3, voffA);
;             PG8_WAIT_V(8); PG8_WAIT_L(0); PG8_BAR; PG8_MMA(1, 0, At, B0); PG8_MMA(1, 1, At, B1); PG8_BAR; PG8_SCHED;
;     ...
;         if (!has_next) break;
; #pragma unroll
;         for (int a = 0; a < 2; ++a)
; #pragma unroll
;             for (int b = 0; b < 2; ++b)
; #pragma unroll
;                 for (int m = 0; m < 4; ++m)
; #pragma unroll
;                     for (int n = 0; n < 2; ++n) acc[a][b][m][n] = (f32x4){0.f, 0.f, 0.f, 0.f};
;         cur = nxt; cA = nA; cB = nB; ++ui;
	s_add_i32 s40, s67, s43
	v_lshl_add_u64 v[114:115], v[152:153], 0, s[22:23]
	s_mov_b32 m0, s40
	ds_read_b128 v[192:195], v150 offset:49152
	ds_read_b128 v[196:199], v150 offset:50176
	ds_read_b128 v[200:203], v150 offset:51200
	ds_read_b128 v[204:207], v150 offset:52224
	ds_read_b128 v[208:211], v150 offset:53248
	ds_read_b128 v[212:215], v150 offset:54272
	ds_read_b128 v[216:219], v150 offset:55296
	ds_read_b128 v[220:223], v150 offset:56320
	global_load_lds_dwordx4 v[114:115], off
	s_add_i32 m0, s40, 0x2000
	s_add_u32 s38, s38, 0x80080
	v_lshl_add_u64 v[114:115], v[224:225], 0, s[22:23]
	s_addc_u32 s39, s39, 0
	s_add_i32 s40, s68, s43
	global_load_lds_dwordx4 v[114:115], off
	v_lshl_add_u64 v[114:115], s[38:39], 0, v[134:135]
	s_mov_b32 m0, s40
	s_nop 0
	global_load_lds_dwordx4 v[114:115], off
	v_lshl_add_u64 v[114:115], s[38:39], 0, v[138:139]
	s_add_i32 m0, s40, 0x2000
	s_nop 0
	global_load_lds_dwordx4 v[114:115], off
	v_lshl_add_u64 v[114:115], v[226:227], 0, s[22:23]
	s_mov_b32 m0, s54
	s_nop 0
	global_load_lds_dwordx4 v[114:115], off
	v_lshl_add_u64 v[114:115], v[228:229], 0, s[22:23]
	s_mov_b32 m0, s55
	s_nop 0
	global_load_lds_dwordx4 v[114:115], off
	s_waitcnt vmcnt(8)
	s_waitcnt lgkmcnt(0)
	s_barrier
	s_waitcnt lgkmcnt(0)
	v_mfma_f32_16x16x32_bf16 v[60:63], v[158:161], v[192:195], v[60:63]
	v_mfma_f32_16x16x32_bf16 v[56:59], v[166:169], v[192:195], v[56:59]
	v_mfma_f32_16x16x32_bf16 v[44:47], v[158:161], v[200:203], v[44:47]
	v_mfma_f32_16x16x32_bf16 v[40:43], v[166:169], v[200:203], v[40:43]
	v_mfma_f32_16x16x32_bf16 v[28:31], v[158:161], v[208:211], v[28:31]
	v_mfma_f32_16x16x32_bf16 v[24:27], v[166:169], v[208:211], v[24:27]
	v_mfma_f32_16x16x32_bf16 v[12:15], v[158:161], v[216:219], v[12:15]
	v_mfma_f32_16x16x32_bf16 v[8:11], v[166:169], v[216:219], v[8:11]
	v_mfma_f32_16x16x32_bf16 v[60:63], v[162:165], v[196:199], v[60:63]
	v_mfma_f32_16x16x32_bf16 v[56:59], v[170:173], v[196:199], v[56:59]
	v_mfma_f32_16x16x32_bf16 v[44:47], v[162:165], v[204:207], v[44:47]
	v_mfma_f32_16x16x32_bf16 v[40:43], v[170:173], v[204:207], v[40:43]
	v_mfma_f32_16x16x32_bf16 v[28:31], v[162:165], v[212:215], v[28:31]
	v_mfma_f32_16x16x32_bf16 v[24:27], v[170:173], v[212:215], v[24:27]
	v_mfma_f32_16x16x32_bf16 v[12:15], v[162:165], v[220:223], v[12:15]
	v_mfma_f32_16x16x32_bf16 v[8:11], v[170:173], v[220:223], v[8:11]
	v_mfma_f32_16x16x32_bf16 v[52:55], v[174:177], v[192:195], v[52:55]
	v_mfma_f32_16x16x32_bf16 v[48:51], v[182:185], v[192:195], v[48:51]
	v_mfma_f32_16x16x32_bf16 v[36:39], v[174:177], v[200:203], v[36:39]
	v_mfma_f32_16x16x32_bf16 v[32:35], v[182:185], v[200:203], v[32:35]
	v_mfma_f32_16x16x32_bf16 v[20:23], v[174:177], v[208:211], v[20:23]
	v_mfma_f32_16x16x32_bf16 v[16:19], v[182:185], v[208:211], v[16:19]
	v_mfma_f32_16x16x32_bf16 v[4:7], v[174:177], v[216:219], v[4:7]
	v_mfma_f32_16x16x32_bf16 v[0:3], v[182:185], v[216:219], v[0:3]
	v_mfma_f32_16x16x32_bf16 v[52:55], v[178:181], v[196:199], v[52:55]
	v_mfma_f32_16x16x32_bf16 v[48:51], v[188:191], v[196:199], v[48:51]
	v_mfma_f32_16x16x32_bf16 v[36:39], v[178:181], v[204:207], v[36:39]
	v_mfma_f32_16x16x32_bf16 v[32:35], v[188:191], v[204:207], v[32:35]
	v_mfma_f32_16x16x32_bf16 v[20:23], v[178:181], v[212:215], v[20:23]
	v_mfma_f32_16x16x32_bf16 v[16:19], v[188:191], v[212:215], v[16:19]
	v_mfma_f32_16x16x32_bf16 v[4:7], v[178:181], v[220:223], v[4:7]
	v_mfma_f32_16x16x32_bf16 v[0:3], v[188:191], v[220:223], v[0:3]
	s_barrier
	s_add_u32 s64, s64, 0x100
	s_addc_u32 s65, s65, 0
	s_add_u32 s36, s36, 0x100
	s_addc_u32 s37, s37, 0
	s_cmp_ge_i32 s66, s53
	s_mov_b32 s38, s66
	s_cbranch_scc0 .LBB0_1014
.LBB0_1015:
	s_andn2_b64 vcc, exec, s[6:7]
	s_cbranch_vccnz .LBB0_1005
	v_mov_b32_e32 v113, v112
	v_mov_b32_e32 v114, v112
	v_mov_b32_e32 v115, v112
	v_mov_b64_e32 v[0:1], v[112:113]
	v_mov_b64_e32 v[4:5], v[112:113]
	v_mov_b64_e32 v[16:17], v[112:113]
	v_mov_b64_e32 v[20:21], v[112:113]
	v_mov_b64_e32 v[32:33], v[112:113]
	v_mov_b64_e32 v[36:37], v[112:113]
	v_mov_b64_e32 v[48:49], v[112:113]
	v_mov_b64_e32 v[52:53], v[112:113]
	v_mov_b64_e32 v[8:9], v[112:113]
	v_mov_b64_e32 v[12:13], v[112:113]
	v_mov_b64_e32 v[24:25], v[112:113]
	v_mov_b64_e32 v[28:29], v[112:113]
	v_mov_b64_e32 v[40:41], v[112:113]
	v_mov_b64_e32 v[44:45], v[112:113]
	v_mov_b64_e32 v[56:57], v[112:113]
	v_mov_b64_e32 v[60:61], v[112:113]
	v_mov_b64_e32 v[64:65], v[112:113]
	v_mov_b64_e32 v[68:69], v[112:113]
	v_mov_b64_e32 v[80:81], v[112:113]
	v_mov_b64_e32 v[84:85], v[112:113]
	v_mov_b64_e32 v[96:97], v[112:113]
	v_mov_b64_e32 v[100:101], v[112:113]
	v_mov_b64_e32 v[118:119], v[114:115]
	v_mov_b64_e32 v[122:123], v[114:115]
	v_mov_b64_e32 v[72:73], v[112:113]
	v_mov_b64_e32 v[76:77], v[112:113]
	v_mov_b64_e32 v[88:89], v[112:113]
	v_mov_b64_e32 v[92:93], v[112:113]
	v_mov_b64_e32 v[104:105], v[112:113]
	v_mov_b64_e32 v[108:109], v[112:113]
	v_mov_b64_e32 v[126:127], v[114:115]
	v_mov_b64_e32 v[130:131], v[114:115]
	v_mov_b64_e32 v[2:3], v[114:115]
	v_mov_b64_e32 v[6:7], v[114:115]
	v_mov_b64_e32 v[18:19], v[114:115]
	v_mov_b64_e32 v[22:23], v[114:115]
	v_mov_b64_e32 v[34:35], v[114:115]
	v_mov_b64_e32 v[38:39], v[114:115]
	v_mov_b64_e32 v[50:51], v[114:115]
	v_mov_b64_e32 v[54:55], v[114:115]
	v_mov_b64_e32 v[10:11], v[114:115]
	v_mov_b64_e32 v[14:15], v[114:115]
	v_mov_b64_e32 v[26:27], v[114:115]
	v_mov_b64_e32 v[30:31], v[114:115]
	v_mov_b64_e32 v[42:43], v[114:115]
	v_mov_b64_e32 v[46:47], v[114:115]
	v_mov_b64_e32 v[58:59], v[114:115]
	v_mov_b64_e32 v[62:63], v[114:115]
	v_mov_b64_e32 v[66:67], v[114:115]
	v_mov_b64_e32 v[70:71], v[114:115]
	v_mov_b64_e32 v[82:83], v[114:115]
	v_mov_b64_e32 v[86:87], v[114:115]
	v_mov_b64_e32 v[98:99], v[114:115]
	v_mov_b64_e32 v[102:103], v[114:115]
	v_mov_b64_e32 v[116:117], v[112:113]
	v_mov_b64_e32 v[120:121], v[112:113]
	v_mov_b64_e32 v[74:75], v[114:115]
	v_mov_b64_e32 v[78:79], v[114:115]
	v_mov_b64_e32 v[90:91], v[114:115]
	v_mov_b64_e32 v[94:95], v[114:115]
	v_mov_b64_e32 v[106:107], v[114:115]
	v_mov_b64_e32 v[110:111], v[114:115]
	v_mov_b64_e32 v[124:125], v[112:113]
	v_mov_b64_e32 v[128:129], v[112:113]
	s_mov_b32 s57, s26
	s_mov_b32 s12, s28
	s_mov_b64 s[18:19], s[34:35]
	s_mov_b64 s[20:21], s[30:31]
	s_mov_b32 s60, s61
	s_branch .LBB0_1005
